# trailing half's post-epilogue re-offset barrier deferred to just before the next tile's first LDS read (scheduler code of both halves overlaps)
# baseline (speedup 1.0000x reference)
;     __device__ __forceinline__ unsigned char* ws() const { return (unsigned char*)(GAS unsigned char*)get(22); }
; __device__ __forceinline__ void prologue(const PT a, unsigned char* ws, int tid, int wave, int lane, int bid, int G) {
;     const int gtid = bid * 512 + tid, GT = G * 512, gw = bid * NWAVES + wave, NGW = G * NWAVES;
;     float* ssq = (float*)(ws + WS_SSQ); bf16* hb = (bf16*)(ws + WS_HB); float* rope = (float*)(ws + WS_ROPE);
;     for (int i = gtid; i < (TPAD - T_ROWS) * 16; i += GT) ssq[(size_t)T_ROWS * 16 + i] = 0.f;
.LBB0_31:
	s_mov_b32 s101, 0
	s_add_i32 s0, 0, 0x204b0
	v_mov_b32_e32 v16, v190
	s_mov_b32 s38, s14
	s_mov_b32 s39, s16
	v_mov_b32_e32 v1, s0
	ds_read_b64 v[2:3], v1
	v_lshl_add_u32 v6, s38, 9, v16
	s_movk_i32 s0, 0xc00
	v_readfirstlane_b32 s30, v16
	s_lshl_b32 s6, s39, 9
	s_waitcnt lgkmcnt(0)
	v_readfirstlane_b32 s11, v3
	v_readfirstlane_b32 s10, v2
	v_cmp_gt_i32_e32 vcc, s0, v6
	s_and_saveexec_b64 s[2:3], vcc
	s_cbranch_execz .LBB0_39
	v_cvt_f32_u32_e32 v1, s6
	v_add_u32_e32 v7, s6, v6
	v_mov_b32_e32 v2, s6
	v_cmp_gt_i32_e32 vcc, s0, v7
	v_rcp_iflag_f32_e32 v1, v1
	s_sub_i32 s4, 0, s6
	v_max_i32_e32 v3, 0xc00, v7
	v_addc_co_u32_e64 v2, s[0:1], v6, v2, vcc
	v_mul_f32_e32 v1, 0x4f7ffffe, v1
	v_cvt_u32_f32_e32 v1, v1
	v_sub_u32_e32 v2, v3, v2
	v_mul_lo_u32 v3, s4, v1
	v_mul_hi_u32 v3, v1, v3
	v_add_u32_e32 v1, v1, v3
	v_mul_hi_u32 v1, v2, v1
	v_mul_lo_u32 v3, v1, s6
	v_sub_u32_e32 v2, v2, v3
	v_add_u32_e32 v4, 1, v1
	v_cmp_le_u32_e64 s[0:1], s6, v2
	v_subrev_u32_e32 v3, s6, v2
	s_nop 0
	v_cndmask_b32_e64 v1, v1, v4, s[0:1]
	v_cndmask_b32_e64 v2, v2, v3, s[0:1]
	v_add_u32_e32 v3, 1, v1
	v_cmp_le_u32_e64 s[0:1], s6, v2
	v_mov_b32_e32 v2, v6
	s_nop 0
	v_cndmask_b32_e64 v1, v1, v3, s[0:1]
	v_addc_co_u32_e32 v1, vcc, 1, v1, vcc
	v_cmp_lt_u32_e32 vcc, 1, v1
	s_mov_b64 s[0:1], -1
	s_and_saveexec_b64 s[4:5], vcc
	s_cbranch_execz .LBB0_36
	s_add_u32 s8, s10, 0x300000
	s_addc_u32 s9, s11, 0
	v_and_b32_e32 v4, -2, v1
	s_lshl_b32 s7, s39, 10
	s_mov_b32 s15, s7
	s_mov_b64 s[24:25], 0
	v_mov_b32_e32 v5, 0
	v_mov_b32_e32 v8, v4
	v_mov_b64_e32 v[2:3], v[6:7]

;     __device__ __forceinline__ bool next(int i, pg8::Unit& u) const { if (!base.next(i >> 2, u)) return false; u.sub = i & 3; return true; }
;     __host__ __device__ bool next(int i, Unit& u) const {
;         const long L = (long)i * G + c; if (L >= nwg) return false;
;         int wgid = (int)L; { const int q = nwg / NXCD, r = nwg % NXCD, xcd = wgid % NXCD, off = wgid / NXCD; wgid = (xcd < r ? xcd * (q + 1) : r * (q + 1) + (xcd - r) * q) + off; }
;         const int nig = WGM * nN, gid = wgid / nig, fm = gid * WGM, gsz = (nM - fm) < WGM ? (nM - fm) : WGM;
;         u.pm = fm + ((wgid % nig) % gsz); u.pn = (wgid % nig) / gsz; u.sub = 0; return true;
; template <class Epi, class Sched, bool ALIGN_EPI = false, bool SP2 = false>
; __device__ __forceinline__ void gemm_phase(PG8_LAS unsigned char* lds, const Gemm g, const Sched& S, const Epi& E, const int tid) {
;     ...
;     Unit cur, nxt; int ui = 0;
;     if (!S.next(0, cur)) return;
.LBB0_322:
	s_mov_b32 s101, 0
	s_add_i32 s0, 0, 0x204b0
	v_mov_b32_e32 v10, v190
	s_mov_b32 s25, s14
	s_mov_b32 s44, s16
	v_mov_b32_e32 v1, s0
	ds_read_b64 v[2:3], v1
	s_cmpk_gt_i32 s25, 0x10ab
	v_readfirstlane_b32 s10, v10
	s_waitcnt lgkmcnt(0)
	v_readfirstlane_b32 s3, v3
	v_readfirstlane_b32 s2, v2
	s_cbranch_scc1 .LBB0_346
	s_ashr_i32 s45, s25, 31
	s_lshr_b32 s0, s45, 29
	s_add_i32 s6, s25, s0
	s_and_b32 s0, s6, -8
	s_sub_i32 s5, s25, s0
	s_cmp_gt_i32 s5, 3
	s_cbranch_scc0 .LBB0_325
	s_mul_i32 s0, s5, 0x215
	s_add_i32 s4, s0, 4
	s_ashr_i32 s0, s6, 3
	s_cbranch_execz .LBB0_326
	s_branch .LBB0_327

; #define PG8_STAGE(bufoff, gbase, voff) do { _Pragma("unroll") for (int _i = 0; _i < 2; ++_i) \
;         __builtin_amdgcn_global_load_lds((const unsigned*)((const char*)(gbase) + (voff)[_i]), (PG8_LAS unsigned*)(lds + (bufoff) + ldsw + _i * 8192), 16, 0, 0); } while (0)
; #define PG8_LDA(dst, b, h) do { _Pragma("unroll") for (int m = 0; m < 4; ++m) _Pragma("unroll") for (int k = 0; k < 2; ++k) dst[m][k] = *(const PG8_LAS bf16x8*)(lds + PG8_SA(b, h) + aoff + m * 2048 + k * 1024); } while (0)
; #define PG8_LDB(dst, b, h) do { _Pragma("unroll") for (int n = 0; n < 2; ++n) _Pragma("unroll") for (int k = 0; k < 2; ++k) dst[n][k] = *(const PG8_LAS bf16x8*)(lds + PG8_SB(b, h) + boff + n * 2048 + k * 1024); } while (0)
; #define PG8_MMA(ai, bj, At, Bt) do { __builtin_amdgcn_s_setprio(1); _Pragma("unroll") for (int m = 0; m < 4; ++m) _Pragma("unroll") for (int n = 0; n < 2; ++n) _Pragma("unroll") for (int k = 0; k < 2; ++k) \
;         acc[ai][bj][m][n] = __builtin_amdgcn_mfma_f32_16x16x32_bf16(Bt[n][k], At[m][k], acc[ai][bj][m][n], 0, 0, 0); __builtin_amdgcn_s_setprio(0); } while (0)
; #define PG8_WAIT_V(n) asm volatile("s_waitcnt vmcnt(" #n ")" ::: "memory")
; #define PG8_WAIT_L(n) asm volatile("s_waitcnt lgkmcnt(" #n ")" ::: "memory")
; template <class Epi, class Sched, bool ALIGN_EPI = false, bool SP2 = false>
; __device__ __forceinline__ void gemm_phase(PG8_LAS unsigned char* lds, const Gemm g, const Sched& S, const Epi& E, const int tid) {
;     ...
;             const bool last = (t == nt - 2);
;             const char* a1 = cA + (size_t)(t + 1) * kstep;
;             const char* a2 = last ? nA : cA + (size_t)(t + 2) * kstep; const char* b2 = last ? nB : cB + (size_t)(t + 2) * kstep;
;             const char* a3 = a2 + kstep; const char* b3 = b2 + kstep;
;             if (last && has_next) S.a_ready(nxt);
;             if constexpr (SP2) {
;             PG8_LDB(B0, 0, 0); PG8_LDB(B1, 0, 1); PG8_SCHED; PG8_LDA(At, 0, 0); PG8_STAGE(PG8_SA(1, 1), a1 + hstep, voffA);
;             PG8_WAIT_V(8); PG8_WAIT_L(0); PG8_BAR; PG8_MMA(0, 0, At, B0); PG8_MMA(0, 1, At, B1); PG8_BAR; PG8_SCHED;
;             PG8_LDA(At, 0, 1); PG8_STAGE(PG8_SB(0, 0), b2, voffB); PG8_STAGE(PG8_SB(0, 1), b2 + hstep, voffB); PG8_STAGE(PG8_SA(0, 0), a2, voffA);
;             PG8_WAIT_V(8); PG8_WAIT_L(0); PG8_BAR; PG8_MMA(1, 0, At, B0); PG8_MMA(1, 1, At, B1); PG8_BAR; PG8_SCHED;
.LBB0_338:
	s_ashr_i32 s29, s28, 31
	s_lshl_b64 s[18:19], s[28:29], 19
	s_add_u32 s30, s46, s18
	s_addc_u32 s31, s47, s19
	s_and_b64 s[18:19], s[2:3], exec
	s_cselect_b32 s29, s31, s41
	s_cselect_b32 s62, s30, s40
	s_ashr_i32 s27, s26, 31
	s_lshl_b64 s[18:19], s[26:27], 19
	s_add_u32 s34, s48, s18
	s_addc_u32 s35, s49, s19
	s_and_b64 s[18:19], s[2:3], exec
	s_cselect_b32 s27, s35, s39
	s_cselect_b32 s63, s34, s38
	s_add_u32 s64, s38, 0x100
	s_addc_u32 s65, s39, 0
	s_add_u32 s38, s40, 0x40080
	s_addc_u32 s39, s41, 0
	s_mov_b32 s66, -2
	s_cmp_eq_u32 s101, 0
	s_cbranch_scc1 .Lnobar0
	s_barrier
.Lnobar0:
	ds_read_b128 v[150:153], v161
	ds_read_b128 v[172:175], v161 offset:1024
	ds_read_b128 v[176:179], v161 offset:2048
	ds_read_b128 v[180:183], v161 offset:3072
	ds_read_b128 v[184:187], v163
	ds_read_b128 v[192:195], v163 offset:1024
	ds_read_b128 v[196:199], v163 offset:2048
	ds_read_b128 v[200:203], v163 offset:3072
	s_add_u32 s15, s38, 0xfffc0080
	s_addc_u32 s18, s39, -1
	s_cmp_eq_u32 s66, 12
	s_cselect_b32 s43, s29, s18
	s_cselect_b32 s42, s62, s15
	s_cselect_b32 s41, s27, s65
	s_cselect_b32 s40, s63, s64
	v_lshl_add_u64 v[154:155], s[38:39], 0, v[144:145]
	s_add_i32 m0, s51, 0xc000
	ds_read_b128 v[204:207], v167
	ds_read_b128 v[208:211], v167 offset:1024
	ds_read_b128 v[212:215], v167 offset:2048
	ds_read_b128 v[216:219], v167 offset:3072
	ds_read_b128 v[220:223], v167 offset:4096
	ds_read_b128 v[224:227], v167 offset:5120
	ds_read_b128 v[228:231], v167 offset:6144
	ds_read_b128 v[232:235], v167 offset:7168
	global_load_lds_dwordx4 v[154:155], off
	v_lshl_add_u64 v[154:155], s[38:39], 0, v[142:143]
	s_add_i32 m0, s51, 0xe000
	s_nop 0
	global_load_lds_dwordx4 v[154:155], off
	s_waitcnt vmcnt(16)
	s_waitcnt lgkmcnt(0)
	s_barrier
	s_setprio 1
	s_waitcnt lgkmcnt(0)
	v_mfma_f32_16x16x32_bf16 v[126:129], v[150:153], v[204:207], 0
	v_mfma_f32_16x16x32_bf16 v[122:125], v[176:179], v[204:207], 0
	v_mfma_f32_16x16x32_bf16 v[110:113], v[150:153], v[212:215], 0
	v_mfma_f32_16x16x32_bf16 v[106:109], v[176:179], v[212:215], 0
	v_mfma_f32_16x16x32_bf16 v[94:97], v[150:153], v[220:223], 0
	v_mfma_f32_16x16x32_bf16 v[90:93], v[176:179], v[220:223], 0
	v_mfma_f32_16x16x32_bf16 v[78:81], v[150:153], v[228:231], 0
	v_mfma_f32_16x16x32_bf16 v[74:77], v[176:179], v[228:231], 0
	v_mfma_f32_16x16x32_bf16 v[126:129], v[172:175], v[208:211], v[126:129]
	v_mfma_f32_16x16x32_bf16 v[122:125], v[180:183], v[208:211], v[122:125]
	v_mfma_f32_16x16x32_bf16 v[110:113], v[172:175], v[216:219], v[110:113]
	v_mfma_f32_16x16x32_bf16 v[106:109], v[180:183], v[216:219], v[106:109]
	v_mfma_f32_16x16x32_bf16 v[94:97], v[172:175], v[224:227], v[94:97]
	v_mfma_f32_16x16x32_bf16 v[90:93], v[180:183], v[224:227], v[90:93]
	v_mfma_f32_16x16x32_bf16 v[78:81], v[172:175], v[232:235], v[78:81]
	v_mfma_f32_16x16x32_bf16 v[74:77], v[180:183], v[232:235], v[74:77]
	s_setprio 0
	s_setprio 1
	v_mfma_f32_16x16x32_bf16 v[118:121], v[184:187], v[204:207], 0
	v_mfma_f32_16x16x32_bf16 v[114:117], v[196:199], v[204:207], 0
	v_mfma_f32_16x16x32_bf16 v[102:105], v[184:187], v[212:215], 0
	v_mfma_f32_16x16x32_bf16 v[98:101], v[196:199], v[212:215], 0
	v_mfma_f32_16x16x32_bf16 v[86:89], v[184:187], v[220:223], 0
	v_mfma_f32_16x16x32_bf16 v[82:85], v[196:199], v[220:223], 0
	v_mfma_f32_16x16x32_bf16 v[70:73], v[184:187], v[228:231], 0
	v_mfma_f32_16x16x32_bf16 v[66:69], v[196:199], v[228:231], 0
	v_mfma_f32_16x16x32_bf16 v[118:121], v[192:195], v[208:211], v[118:121]
	v_mfma_f32_16x16x32_bf16 v[114:117], v[200:203], v[208:211], v[114:117]
	v_mfma_f32_16x16x32_bf16 v[102:105], v[192:195], v[216:219], v[102:105]
	v_mfma_f32_16x16x32_bf16 v[98:101], v[200:203], v[216:219], v[98:101]
	v_mfma_f32_16x16x32_bf16 v[86:89], v[192:195], v[224:227], v[86:89]
	v_mfma_f32_16x16x32_bf16 v[82:85], v[200:203], v[224:227], v[82:85]
	v_mfma_f32_16x16x32_bf16 v[70:73], v[192:195], v[232:235], v[70:73]
	v_mfma_f32_16x16x32_bf16 v[66:69], v[200:203], v[232:235], v[66:69]
	s_setprio 0
	s_barrier
	s_add_i32 s15, s58, s50
	v_lshl_add_u64 v[154:155], s[40:41], 0, v[132:133]
	s_mov_b32 m0, s15
	ds_read_b128 v[204:207], v167 offset:16384
	ds_read_b128 v[208:211], v167 offset:17408
	ds_read_b128 v[212:215], v167 offset:18432
	ds_read_b128 v[216:219], v167 offset:19456
	ds_read_b128 v[220:223], v167 offset:20480
	ds_read_b128 v[224:227], v167 offset:21504
	ds_read_b128 v[228:231], v167 offset:22528
	ds_read_b128 v[232:235], v167 offset:23552
	global_load_lds_dwordx4 v[154:155], off
	s_add_i32 m0, s15, 0x2000
	s_add_u32 s18, s40, 0x40000
	v_lshl_add_u64 v[158:159], s[40:41], 0, v[136:137]
	s_addc_u32 s19, s41, 0
	s_add_i32 s15, s59, s50
	global_load_lds_dwordx4 v[158:159], off
	v_lshl_add_u64 v[164:165], s[18:19], 0, v[132:133]
	s_mov_b32 m0, s15
	v_lshl_add_u64 v[168:169], s[42:43], 0, v[134:135]
	global_load_lds_dwordx4 v[164:165], off
	v_lshl_add_u64 v[164:165], s[18:19], 0, v[136:137]
	s_add_i32 m0, s15, 0x2000
	s_nop 0
	global_load_lds_dwordx4 v[164:165], off
	v_lshl_add_u64 v[164:165], s[42:43], 0, v[130:131]
	s_mov_b32 m0, s51
	s_nop 0
	global_load_lds_dwordx4 v[164:165], off
	s_mov_b32 m0, s52
	s_nop 0
	global_load_lds_dwordx4 v[168:169], off
	s_waitcnt vmcnt(8)
; #define PG8_STAGE(bufoff, gbase, voff) do { _Pragma("unroll") for (int _i = 0; _i < 2; ++_i) \
;         __builtin_amdgcn_global_load_lds((const unsigned*)((const char*)(gbase) + (voff)[_i]), (PG8_LAS unsigned*)(lds + (bufoff) + ldsw + _i * 8192), 16, 0, 0); } while (0)
; #define PG8_LDA(dst, b, h) do { _Pragma("unroll") for (int m = 0; m < 4; ++m) _Pragma("unroll") for (int k = 0; k < 2; ++k) dst[m][k] = *(const PG8_LAS bf16x8*)(lds + PG8_SA(b, h) + aoff + m * 2048 + k * 1024); } while (0)
; #define PG8_LDB(dst, b, h) do { _Pragma("unroll") for (int n = 0; n < 2; ++n) _Pragma("unroll") for (int k = 0; k < 2; ++k) dst[n][k] = *(const PG8_LAS bf16x8*)(lds + PG8_SB(b, h) + boff + n * 2048 + k * 1024); } while (0)
; #define PG8_MMA(ai, bj, At, Bt) do { __builtin_amdgcn_s_setprio(1); _Pragma("unroll") for (int m = 0; m < 4; ++m) _Pragma("unroll") for (int n = 0; n < 2; ++n) _Pragma("unroll") for (int k = 0; k < 2; ++k) \
;         acc[ai][bj][m][n] = __builtin_amdgcn_mfma_f32_16x16x32_bf16(Bt[n][k], At[m][k], acc[ai][bj][m][n], 0, 0, 0); __builtin_amdgcn_s_setprio(0); } while (0)
; #define PG8_WAIT_V(n) asm volatile("s_waitcnt vmcnt(" #n ")" ::: "memory")
; #define PG8_WAIT_L(n) asm volatile("s_waitcnt lgkmcnt(" #n ")" ::: "memory")
; #define PG8_BAR __builtin_amdgcn_s_barrier()
; #define PG8_SCHED __builtin_amdgcn_sched_barrier(0)
; template <class Epi, class Sched, bool ALIGN_EPI = false, bool SP2 = false>
; __device__ __forceinline__ void gemm_phase(PG8_LAS unsigned char* lds, const Gemm g, const Sched& S, const Epi& E, const int tid) {
;     ...
;             PG8_WAIT_V(8); PG8_WAIT_L(0); PG8_BAR; PG8_MMA(1, 0, At, B0); PG8_MMA(1, 1, At, B1); PG8_BAR; PG8_SCHED;
;             PG8_LDB(B0, 1, 0); PG8_LDB(B1, 1, 1); PG8_SCHED; PG8_LDA(At, 1, 0); PG8_STAGE(PG8_SA(0, 1), a2 + hstep, voffA);
; __device__ __forceinline__ void rstd8(const float* ssq, int row0, int fq, float (&rs)[8]) {
;     f32x4 pr[8];
; #pragma unroll
;     for (int i = 0; i < 8; ++i) pr[i] = *(const f32x4*)(ssq + (size_t)(row0 + (i >> 2) * 128 + (i & 3) * 16) * 16 + 4 * fq);
; #pragma unroll
;     for (int i = 0; i < 8; ++i) { float s = (pr[i][0] + pr[i][1]) + (pr[i][2] + pr[i][3]); s = xsum16(s); s = xsum32(s); rs[i] = __builtin_amdgcn_rsqf(s * (1.0f / DM) + NORM_EPS); }
; }
	v_add_f32_e32 v6, v6, v7
	v_add_f32_e32 v18, v18, v19
	v_add_f32_e32 v22, v22, v23
	v_add_f32_e32 v34, v34, v35
	v_add_f32_e32 v38, v38, v39
	v_add_f32_e32 v50, v50, v51
	v_add_f32_e32 v54, v54, v55
	v_add_f32_e32 v58, v58, v59
	v_add_f32_e32 v8, v8, v9
	v_add_f32_e32 v20, v20, v21
	v_add_f32_e32 v24, v24, v25
	v_add_f32_e32 v36, v36, v37
	v_add_f32_e32 v40, v40, v41
	v_add_f32_e32 v52, v52, v53
	v_add_f32_e32 v56, v56, v57
	v_add_f32_e32 v60, v60, v61
	v_add_f32_e32 v243, v6, v8
	v_add_f32_e32 v244, v18, v20
	v_add_f32_e32 v245, v22, v24
	v_add_f32_e32 v246, v34, v36
	v_add_f32_e32 v247, v38, v40
	v_add_f32_e32 v248, v50, v52
	v_add_f32_e32 v249, v54, v56
	v_add_f32_e32 v250, v58, v60
	v_mov_b32_e32 v6, v243
	v_mov_b32_e32 v18, v244
	v_mov_b32_e32 v22, v245
	v_mov_b32_e32 v34, v246
	v_mov_b32_e32 v38, v247
	v_mov_b32_e32 v50, v248
	v_mov_b32_e32 v54, v249
	v_mov_b32_e32 v58, v250
	v_permlane16_swap_b32_e32 v243, v6
	v_permlane16_swap_b32_e32 v244, v18
	v_permlane16_swap_b32_e32 v245, v22
	v_permlane16_swap_b32_e32 v246, v34
	v_permlane16_swap_b32_e32 v247, v38
	v_permlane16_swap_b32_e32 v248, v50
	v_permlane16_swap_b32_e32 v249, v54
	v_permlane16_swap_b32_e32 v250, v58
	v_add_f32_e32 v243, v243, v6
	v_add_f32_e32 v244, v244, v18
	v_add_f32_e32 v245, v245, v22
	v_add_f32_e32 v246, v246, v34
	v_add_f32_e32 v247, v247, v38
	v_add_f32_e32 v248, v248, v50
	v_add_f32_e32 v249, v249, v54
	v_add_f32_e32 v250, v250, v58
	v_mov_b32_e32 v6, v243
	v_mov_b32_e32 v18, v244
	v_mov_b32_e32 v22, v245
	v_mov_b32_e32 v34, v246
	v_mov_b32_e32 v38, v247
	v_mov_b32_e32 v50, v248
	v_mov_b32_e32 v54, v249
	v_mov_b32_e32 v58, v250
	v_permlane32_swap_b32_e32 v243, v6
	v_permlane32_swap_b32_e32 v244, v18
	v_permlane32_swap_b32_e32 v245, v22
	v_permlane32_swap_b32_e32 v246, v34
	v_permlane32_swap_b32_e32 v247, v38
	v_permlane32_swap_b32_e32 v248, v50
	v_permlane32_swap_b32_e32 v249, v54
	v_permlane32_swap_b32_e32 v250, v58
	v_add_f32_e32 v243, v243, v6
	v_add_f32_e32 v244, v244, v18
	v_add_f32_e32 v245, v245, v22
	v_add_f32_e32 v246, v246, v34
	v_add_f32_e32 v247, v247, v38
	v_add_f32_e32 v248, v248, v50
	v_add_f32_e32 v249, v249, v54
	v_add_f32_e32 v250, v250, v58
	v_fmamk_f32 v243, v243, 0x3a800000, v171
	v_fmamk_f32 v244, v244, 0x3a800000, v171
	v_fmamk_f32 v245, v245, 0x3a800000, v171
	v_fmamk_f32 v246, v246, 0x3a800000, v171
	v_fmamk_f32 v247, v247, 0x3a800000, v171
	v_fmamk_f32 v248, v248, 0x3a800000, v171
	v_fmamk_f32 v249, v249, 0x3a800000, v171
	v_fmamk_f32 v250, v250, 0x3a800000, v171
	v_rsq_f32_e32 v243, v243
	v_rsq_f32_e32 v244, v244
	v_rsq_f32_e32 v245, v245
	v_rsq_f32_e32 v246, v246
	v_rsq_f32_e32 v247, v247
	v_rsq_f32_e32 v248, v248
	v_rsq_f32_e32 v249, v249
	v_rsq_f32_e32 v250, v250
	s_waitcnt lgkmcnt(0)
	s_barrier
	s_setprio 1
	s_waitcnt lgkmcnt(0)
	v_mfma_f32_16x16x32_bf16 v[62:65], v[150:153], v[204:207], 0
	v_mfma_f32_16x16x32_bf16 v[58:61], v[176:179], v[204:207], 0
	v_mfma_f32_16x16x32_bf16 v[46:49], v[150:153], v[212:215], 0
	v_mfma_f32_16x16x32_bf16 v[42:45], v[176:179], v[212:215], 0
	v_mfma_f32_16x16x32_bf16 v[30:33], v[150:153], v[220:223], 0
	v_mfma_f32_16x16x32_bf16 v[26:29], v[176:179], v[220:223], 0
	v_mfma_f32_16x16x32_bf16 v[14:17], v[150:153], v[228:231], 0
	v_mfma_f32_16x16x32_bf16 v[10:13], v[176:179], v[228:231], 0
	v_mfma_f32_16x16x32_bf16 v[62:65], v[172:175], v[208:211], v[62:65]
	v_mfma_f32_16x16x32_bf16 v[58:61], v[180:183], v[208:211], v[58:61]
	v_mfma_f32_16x16x32_bf16 v[46:49], v[172:175], v[216:219], v[46:49]
	v_mfma_f32_16x16x32_bf16 v[42:45], v[180:183], v[216:219], v[42:45]
	v_mfma_f32_16x16x32_bf16 v[30:33], v[172:175], v[224:227], v[30:33]
	v_mfma_f32_16x16x32_bf16 v[26:29], v[180:183], v[224:227], v[26:29]
	v_mfma_f32_16x16x32_bf16 v[14:17], v[172:175], v[232:235], v[14:17]
	v_mfma_f32_16x16x32_bf16 v[10:13], v[180:183], v[232:235], v[10:13]
	s_setprio 0
	s_setprio 1
	v_mfma_f32_16x16x32_bf16 v[54:57], v[184:187], v[204:207], 0
	v_mfma_f32_16x16x32_bf16 v[50:53], v[196:199], v[204:207], 0
	v_mfma_f32_16x16x32_bf16 v[38:41], v[184:187], v[212:215], 0
	v_mfma_f32_16x16x32_bf16 v[34:37], v[196:199], v[212:215], 0
	v_mfma_f32_16x16x32_bf16 v[22:25], v[184:187], v[220:223], 0
	v_mfma_f32_16x16x32_bf16 v[18:21], v[196:199], v[220:223], 0
	v_mfma_f32_16x16x32_bf16 v[6:9], v[184:187], v[228:231], 0
	v_mfma_f32_16x16x32_bf16 v[2:5], v[196:199], v[228:231], 0
	v_mfma_f32_16x16x32_bf16 v[54:57], v[192:195], v[208:211], v[54:57]
	v_mfma_f32_16x16x32_bf16 v[50:53], v[200:203], v[208:211], v[50:53]
	v_mfma_f32_16x16x32_bf16 v[38:41], v[192:195], v[216:219], v[38:41]
	v_mfma_f32_16x16x32_bf16 v[34:37], v[200:203], v[216:219], v[34:37]
	v_mfma_f32_16x16x32_bf16 v[22:25], v[192:195], v[224:227], v[22:25]
	v_mfma_f32_16x16x32_bf16 v[18:21], v[200:203], v[224:227], v[18:21]
	v_mfma_f32_16x16x32_bf16 v[6:9], v[192:195], v[232:235], v[6:9]
	v_mfma_f32_16x16x32_bf16 v[2:5], v[200:203], v[232:235], v[2:5]
	s_setprio 0
	s_barrier
	s_add_i32 s15, 0, 0x18000
	v_add_u32_e32 v156, s15, v157
	s_add_i32 s67, 0, 0x1c000
	ds_read_b128 v[150:153], v156
	ds_read_b128 v[172:175], v156 offset:1024
	ds_read_b128 v[176:179], v156 offset:2048
	ds_read_b128 v[180:183], v156 offset:3072
	v_add_u32_e32 v156, s67, v157
	ds_read_b128 v[184:187], v156
	ds_read_b128 v[192:195], v156 offset:1024
	ds_read_b128 v[196:199], v156 offset:2048
	ds_read_b128 v[200:203], v156 offset:3072
	s_add_u32 s18, s42, 0x40000
	s_addc_u32 s19, s43, 0
	s_mov_b32 m0, s53
	v_lshl_add_u64 v[188:189], s[18:19], 0, v[130:131]
	ds_read_b128 v[204:207], v167 offset:32768
	ds_read_b128 v[208:211], v167 offset:33792
	ds_read_b128 v[212:215], v167 offset:34816
	ds_read_b128 v[216:219], v167 offset:35840
	ds_read_b128 v[220:223], v167 offset:36864
	ds_read_b128 v[224:227], v167 offset:37888
	ds_read_b128 v[228:231], v167 offset:38912
	ds_read_b128 v[232:235], v167 offset:39936
	global_load_lds_dwordx4 v[188:189], off
	v_lshl_add_u64 v[188:189], s[18:19], 0, v[134:135]
	s_mov_b32 m0, s54
	s_nop 0
	global_load_lds_dwordx4 v[188:189], off
	s_waitcnt vmcnt(8)
	s_waitcnt lgkmcnt(0)
	s_barrier
; #define PG8_STAGE(bufoff, gbase, voff) do { _Pragma("unroll") for (int _i = 0; _i < 2; ++_i) \
;         __builtin_amdgcn_global_load_lds((const unsigned*)((const char*)(gbase) + (voff)[_i]), (PG8_LAS unsigned*)(lds + (bufoff) + ldsw + _i * 8192), 16, 0, 0); } while (0)
; #define PG8_LDA(dst, b, h) do { _Pragma("unroll") for (int m = 0; m < 4; ++m) _Pragma("unroll") for (int k = 0; k < 2; ++k) dst[m][k] = *(const PG8_LAS bf16x8*)(lds + PG8_SA(b, h) + aoff + m * 2048 + k * 1024); } while (0)
; #define PG8_LDB(dst, b, h) do { _Pragma("unroll") for (int n = 0; n < 2; ++n) _Pragma("unroll") for (int k = 0; k < 2; ++k) dst[n][k] = *(const PG8_LAS bf16x8*)(lds + PG8_SB(b, h) + boff + n * 2048 + k * 1024); } while (0)
; #define PG8_MMA(ai, bj, At, Bt) do { __builtin_amdgcn_s_setprio(1); _Pragma("unroll") for (int m = 0; m < 4; ++m) _Pragma("unroll") for (int n = 0; n < 2; ++n) _Pragma("unroll") for (int k = 0; k < 2; ++k) \
;         acc[ai][bj][m][n] = __builtin_amdgcn_mfma_f32_16x16x32_bf16(Bt[n][k], At[m][k], acc[ai][bj][m][n], 0, 0, 0); __builtin_amdgcn_s_setprio(0); } while (0)
; #define PG8_WAIT_V(n) asm volatile("s_waitcnt vmcnt(" #n ")" ::: "memory")
; #define PG8_WAIT_L(n) asm volatile("s_waitcnt lgkmcnt(" #n ")" ::: "memory")
; #define PG8_BAR __builtin_amdgcn_s_barrier()
; #define PG8_SCHED __builtin_amdgcn_sched_barrier(0)
; template <class Epi, class Sched, bool ALIGN_EPI = false, bool SP2 = false>
; __device__ __forceinline__ void gemm_phase(PG8_LAS unsigned char* lds, const Gemm g, const Sched& S, const Epi& E, const int tid) {
;     ...
;             PG8_LDB(B0, 1, 0); PG8_LDB(B1, 1, 1); PG8_SCHED; PG8_LDA(At, 1, 0); PG8_STAGE(PG8_SA(0, 1), a2 + hstep, voffA);
;             PG8_WAIT_V(8); PG8_WAIT_L(0); PG8_BAR; PG8_MMA(0, 0, At, B0); PG8_MMA(0, 1, At, B1); PG8_BAR; PG8_SCHED;
;             PG8_LDA(At, 1, 1); PG8_STAGE(PG8_SB(1, 0), b3, voffB); PG8_STAGE(PG8_SB(1, 1), b3 + hstep, voffB); PG8_STAGE(PG8_SA(1, 0), a3, voffA);
;             PG8_WAIT_V(8); PG8_WAIT_L(0); PG8_BAR; PG8_MMA(1, 0, At, B0); PG8_MMA(1, 1, At, B1); PG8_BAR; PG8_SCHED;
	s_setprio 1
	s_waitcnt lgkmcnt(0)
	v_mfma_f32_16x16x32_bf16 v[126:129], v[150:153], v[204:207], v[126:129]
	v_mfma_f32_16x16x32_bf16 v[122:125], v[176:179], v[204:207], v[122:125]
	v_mfma_f32_16x16x32_bf16 v[110:113], v[150:153], v[212:215], v[110:113]
	v_mfma_f32_16x16x32_bf16 v[106:109], v[176:179], v[212:215], v[106:109]
	v_mfma_f32_16x16x32_bf16 v[94:97], v[150:153], v[220:223], v[94:97]
	v_mfma_f32_16x16x32_bf16 v[90:93], v[176:179], v[220:223], v[90:93]
	v_mfma_f32_16x16x32_bf16 v[78:81], v[150:153], v[228:231], v[78:81]
	v_mfma_f32_16x16x32_bf16 v[74:77], v[176:179], v[228:231], v[74:77]
	v_mfma_f32_16x16x32_bf16 v[126:129], v[172:175], v[208:211], v[126:129]
	v_mfma_f32_16x16x32_bf16 v[122:125], v[180:183], v[208:211], v[122:125]
	v_mfma_f32_16x16x32_bf16 v[110:113], v[172:175], v[216:219], v[110:113]
	v_mfma_f32_16x16x32_bf16 v[106:109], v[180:183], v[216:219], v[106:109]
	v_mfma_f32_16x16x32_bf16 v[94:97], v[172:175], v[224:227], v[94:97]
	v_mfma_f32_16x16x32_bf16 v[90:93], v[180:183], v[224:227], v[90:93]
	v_mfma_f32_16x16x32_bf16 v[78:81], v[172:175], v[232:235], v[78:81]
	v_mfma_f32_16x16x32_bf16 v[74:77], v[180:183], v[232:235], v[74:77]
	s_setprio 0
	s_setprio 1
	v_mfma_f32_16x16x32_bf16 v[118:121], v[184:187], v[204:207], v[118:121]
	v_mfma_f32_16x16x32_bf16 v[114:117], v[196:199], v[204:207], v[114:117]
	v_mfma_f32_16x16x32_bf16 v[102:105], v[184:187], v[212:215], v[102:105]
	v_mfma_f32_16x16x32_bf16 v[98:101], v[196:199], v[212:215], v[98:101]
	v_mfma_f32_16x16x32_bf16 v[86:89], v[184:187], v[220:223], v[86:89]
	v_mfma_f32_16x16x32_bf16 v[82:85], v[196:199], v[220:223], v[82:85]
	v_mfma_f32_16x16x32_bf16 v[70:73], v[184:187], v[228:231], v[70:73]
	v_mfma_f32_16x16x32_bf16 v[66:69], v[196:199], v[228:231], v[66:69]
	v_mfma_f32_16x16x32_bf16 v[118:121], v[192:195], v[208:211], v[118:121]
	v_mfma_f32_16x16x32_bf16 v[114:117], v[200:203], v[208:211], v[114:117]
	v_mfma_f32_16x16x32_bf16 v[102:105], v[192:195], v[216:219], v[102:105]
	v_mfma_f32_16x16x32_bf16 v[98:101], v[200:203], v[216:219], v[98:101]
	v_mfma_f32_16x16x32_bf16 v[86:89], v[192:195], v[224:227], v[86:89]
	v_mfma_f32_16x16x32_bf16 v[82:85], v[200:203], v[224:227], v[82:85]
	v_mfma_f32_16x16x32_bf16 v[70:73], v[192:195], v[232:235], v[70:73]
	v_mfma_f32_16x16x32_bf16 v[66:69], v[200:203], v[232:235], v[66:69]
	s_setprio 0
	s_barrier
	s_add_i32 s15, s15, s50
	v_lshl_add_u64 v[154:155], v[154:155], 0, s[8:9]
	s_mov_b32 m0, s15
	ds_read_b128 v[204:207], v167 offset:49152
	ds_read_b128 v[208:211], v167 offset:50176
	ds_read_b128 v[212:215], v167 offset:51200
	ds_read_b128 v[216:219], v167 offset:52224
	ds_read_b128 v[220:223], v167 offset:53248
	ds_read_b128 v[224:227], v167 offset:54272
	ds_read_b128 v[228:231], v167 offset:55296
	ds_read_b128 v[232:235], v167 offset:56320
	global_load_lds_dwordx4 v[154:155], off
	s_add_i32 m0, s15, 0x2000
	s_add_u32 s18, s40, 0x40080
	v_lshl_add_u64 v[154:155], v[158:159], 0, s[8:9]
	s_addc_u32 s19, s41, 0
	s_add_i32 s15, s67, s50
	global_load_lds_dwordx4 v[154:155], off
	v_lshl_add_u64 v[154:155], s[18:19], 0, v[132:133]
	s_mov_b32 m0, s15
	s_nop 0
	global_load_lds_dwordx4 v[154:155], off
	v_lshl_add_u64 v[154:155], s[18:19], 0, v[136:137]
	s_add_i32 m0, s15, 0x2000
	s_nop 0
	global_load_lds_dwordx4 v[154:155], off
	v_lshl_add_u64 v[154:155], v[164:165], 0, s[8:9]
	s_mov_b32 m0, s55
	s_nop 0
	global_load_lds_dwordx4 v[154:155], off
	v_lshl_add_u64 v[154:155], v[168:169], 0, s[8:9]
	s_mov_b32 m0, s56
	s_nop 0
	global_load_lds_dwordx4 v[154:155], off
	s_waitcnt vmcnt(8)
	s_waitcnt lgkmcnt(0)
	s_barrier
	s_setprio 1
	s_waitcnt lgkmcnt(0)
	v_mfma_f32_16x16x32_bf16 v[62:65], v[150:153], v[204:207], v[62:65]
	v_mfma_f32_16x16x32_bf16 v[58:61], v[176:179], v[204:207], v[58:61]
	v_mfma_f32_16x16x32_bf16 v[46:49], v[150:153], v[212:215], v[46:49]
	v_mfma_f32_16x16x32_bf16 v[42:45], v[176:179], v[212:215], v[42:45]
	v_mfma_f32_16x16x32_bf16 v[30:33], v[150:153], v[220:223], v[30:33]
	v_mfma_f32_16x16x32_bf16 v[26:29], v[176:179], v[220:223], v[26:29]
	v_mfma_f32_16x16x32_bf16 v[14:17], v[150:153], v[228:231], v[14:17]
	v_mfma_f32_16x16x32_bf16 v[10:13], v[176:179], v[228:231], v[10:13]
	v_mfma_f32_16x16x32_bf16 v[62:65], v[172:175], v[208:211], v[62:65]
	v_mfma_f32_16x16x32_bf16 v[58:61], v[180:183], v[208:211], v[58:61]
	v_mfma_f32_16x16x32_bf16 v[46:49], v[172:175], v[216:219], v[46:49]
	v_mfma_f32_16x16x32_bf16 v[42:45], v[180:183], v[216:219], v[42:45]
	v_mfma_f32_16x16x32_bf16 v[30:33], v[172:175], v[224:227], v[30:33]
	v_mfma_f32_16x16x32_bf16 v[26:29], v[180:183], v[224:227], v[26:29]
	v_mfma_f32_16x16x32_bf16 v[14:17], v[172:175], v[232:235], v[14:17]
	v_mfma_f32_16x16x32_bf16 v[10:13], v[180:183], v[232:235], v[10:13]
	s_setprio 0
	s_setprio 1
	v_mfma_f32_16x16x32_bf16 v[54:57], v[184:187], v[204:207], v[54:57]
	v_mfma_f32_16x16x32_bf16 v[50:53], v[196:199], v[204:207], v[50:53]
	v_mfma_f32_16x16x32_bf16 v[38:41], v[184:187], v[212:215], v[38:41]
	v_mfma_f32_16x16x32_bf16 v[34:37], v[196:199], v[212:215], v[34:37]
	v_mfma_f32_16x16x32_bf16 v[22:25], v[184:187], v[220:223], v[22:25]
	v_mfma_f32_16x16x32_bf16 v[18:21], v[196:199], v[220:223], v[18:21]
	v_mfma_f32_16x16x32_bf16 v[6:9], v[184:187], v[228:231], v[6:9]
	v_mfma_f32_16x16x32_bf16 v[2:5], v[196:199], v[228:231], v[2:5]
	v_mfma_f32_16x16x32_bf16 v[54:57], v[192:195], v[208:211], v[54:57]
	v_mfma_f32_16x16x32_bf16 v[50:53], v[200:203], v[208:211], v[50:53]
	v_mfma_f32_16x16x32_bf16 v[38:41], v[192:195], v[216:219], v[38:41]
	v_mfma_f32_16x16x32_bf16 v[34:37], v[200:203], v[216:219], v[34:37]
	v_mfma_f32_16x16x32_bf16 v[22:25], v[192:195], v[224:227], v[22:25]
	v_mfma_f32_16x16x32_bf16 v[18:21], v[200:203], v[224:227], v[18:21]
	v_mfma_f32_16x16x32_bf16 v[6:9], v[192:195], v[232:235], v[6:9]
	v_mfma_f32_16x16x32_bf16 v[2:5], v[200:203], v[232:235], v[2:5]
	s_setprio 0
	s_barrier
	s_add_i32 s66, s66, 2
	s_add_u32 s64, s64, 0x100
	s_addc_u32 s65, s65, 0
	s_add_u32 s38, s38, 0x100
	s_addc_u32 s39, s39, 0

; __device__ __forceinline__ u32x4 pack8(const f32x4 a, const f32x4 b) { u32x4 w; w.x = pk2(a[0], a[1]); w.y = pk2(a[2], a[3]); w.z = pk2(b[0], b[1]); w.w = pk2(b[2], b[3]); return w; }
;     __device__ __forceinline__ void operator()(const Acc& acc, const Unit& u, int wr, int wc, int fr, int fq) const {
;         const int row0 = u.pm * 256 + wr * 64 + fr;
;         float rs[8]; rstd8(ssq, row0, fq, rs);
; #pragma unroll
;         for (int ai = 0; ai < 2; ++ai)
; #pragma unroll
;             for (int m = 0; m < 4; ++m) {
;                 const int row = row0 + ai * 128 + m * 16; const float r1 = rs[ai * 4 + m];
;                 f32x4 o[2];
; #pragma unroll
;                 for (int n = 0; n < 2; ++n) {
;                     const f32x4 gs = acc[ai][0][m][n] * r1, us = acc[ai][1][m][n] * r1, t = gs * -1.4426950408889634f;
;                     f32x4 d; d[0] = __builtin_amdgcn_exp2f(t[0]); d[1] = __builtin_amdgcn_exp2f(t[1]); d[2] = __builtin_amdgcn_exp2f(t[2]); d[3] = __builtin_amdgcn_exp2f(t[3]);
;                     d = d + 1.0f;
;                     f32x4 r; r[0] = __builtin_amdgcn_rcpf(d[0]); r[1] = __builtin_amdgcn_rcpf(d[1]); r[2] = __builtin_amdgcn_rcpf(d[2]); r[3] = __builtin_amdgcn_rcpf(d[3]);
;                     o[n] = (gs * us) * r;
;                 }
;                 *(u32x4*)(hid + (size_t)row * FF + u.pn * 128 + wc * 32 + 8 * fq) = pack8(o[0], o[1]);
.LBB0_342:
	v_lshl_add_u32 v176, s36, 8, v1
	v_ashrrev_i32_e32 v177, 31, v176
	v_or_b32_e32 v172, 16, v176
	v_ashrrev_i32_e32 v173, 31, v172
	v_or_b32_e32 v168, 32, v176
	v_ashrrev_i32_e32 v169, 31, v168
	v_or_b32_e32 v164, 48, v176
	v_ashrrev_i32_e32 v165, 31, v164
	v_add_u32_e32 v158, 0x80, v176
	v_ashrrev_i32_e32 v159, 31, v158
	v_add_u32_e32 v154, 0x90, v176
	v_ashrrev_i32_e32 v155, 31, v154
	v_add_u32_e32 v152, 0xa0, v176
	v_add_u32_e32 v150, 0xb0, v176
	v_ashrrev_i32_e32 v153, 31, v152
	v_ashrrev_i32_e32 v151, 31, v150
	v_lshlrev_b64 v[174:175], 6, v[152:153]
	v_lshlrev_b64 v[204:205], 6, v[150:151]
	v_lshl_add_u64 v[174:175], v[140:141], 0, v[174:175]
	v_lshl_add_u64 v[208:209], v[140:141], 0, v[204:205]
	s_nop 0
	s_andn2_b64 vcc, exec, s[2:3]
	s_mov_b64 s[2:3], -1
	v_mov_b32_e32 v178, v243
	v_pk_mul_f32 v[126:127], v[126:127], v[178:179] op_sel_hi:[1,0]
	v_pk_mul_f32 v[128:129], v[128:129], v[178:179] op_sel_hi:[1,0]
	v_pk_mul_f32 v[120:121], v[120:121], v[178:179] op_sel_hi:[1,0]
	v_pk_mul_f32 v[122:123], v[122:123], v[178:179] op_sel_hi:[1,0]
	v_pk_mul_f32 v[182:183], v[128:129], s[24:25] op_sel_hi:[1,0]
	v_pk_mul_f32 v[184:185], v[126:127], s[24:25] op_sel_hi:[1,0]
	v_pk_mul_f32 v[118:119], v[118:119], v[178:179] op_sel_hi:[1,0]
	v_pk_mul_f32 v[120:121], v[128:129], v[120:121]
	v_pk_mul_f32 v[124:125], v[124:125], v[178:179] op_sel_hi:[1,0]
	v_pk_mul_f32 v[128:129], v[122:123], s[24:25] op_sel_hi:[1,0]
	v_exp_f32_e32 v184, v184
	v_exp_f32_e32 v185, v185
	v_pk_mul_f32 v[118:119], v[126:127], v[118:119]
	v_pk_mul_f32 v[126:127], v[124:125], s[24:25] op_sel_hi:[1,0]
	v_exp_f32_e32 v128, v128
	v_exp_f32_e32 v129, v129
	v_exp_f32_e32 v182, v182
	v_exp_f32_e32 v183, v183
	v_exp_f32_e32 v126, v126
	v_exp_f32_e32 v127, v127
	v_pk_add_f32 v[184:185], v[184:185], 1.0 op_sel_hi:[1,0]
	v_pk_add_f32 v[128:129], v[128:129], 1.0 op_sel_hi:[1,0]
	v_pk_add_f32 v[182:183], v[182:183], 1.0 op_sel_hi:[1,0]
	v_rcp_f32_e32 v184, v184
	v_rcp_f32_e32 v185, v185
	v_pk_add_f32 v[126:127], v[126:127], 1.0 op_sel_hi:[1,0]
	v_rcp_f32_e32 v128, v128
	v_rcp_f32_e32 v129, v129
	v_rcp_f32_e32 v182, v182
	v_rcp_f32_e32 v183, v183
	v_rcp_f32_e32 v126, v126
	v_rcp_f32_e32 v127, v127
	v_pk_mul_f32 v[114:115], v[114:115], v[178:179] op_sel_hi:[1,0]
	v_pk_mul_f32 v[116:117], v[116:117], v[178:179] op_sel_hi:[1,0]
	v_pk_mul_f32 v[114:115], v[122:123], v[114:115]
	v_pk_mul_f32 v[118:119], v[118:119], v[184:185]
	v_pk_mul_f32 v[116:117], v[124:125], v[116:117]
	v_pk_mul_f32 v[114:115], v[114:115], v[128:129]
	v_pk_mul_f32 v[120:121], v[120:121], v[182:183]
	v_pk_mul_f32 v[122:123], v[116:117], v[126:127]
	v_cvt_pk_bf16_f32 v116, v118, v119
	v_cvt_pk_bf16_f32 v117, v120, v121
	v_cvt_pk_bf16_f32 v118, v114, v115
	v_mov_b64_e32 v[114:115], s[6:7]
	v_mad_i64_i32 v[120:121], s[18:19], v176, s60, v[114:115]
	s_lshl_b32 s18, s37, 7
	v_mov_b32_e32 v180, v244
	s_ashr_i32 s19, s18, 31
	s_lshl_b64 s[36:37], s[18:19], 1
	v_lshl_add_u64 v[120:121], v[120:121], 0, s[36:37]
	v_lshl_add_u64 v[120:121], v[120:121], 0, s[0:1]
	v_cvt_pk_bf16_f32 v119, v122, v123
	v_lshl_add_u64 v[120:121], v[120:121], 0, v[138:139]
	v_pk_mul_f32 v[110:111], v[110:111], v[180:181] op_sel_hi:[1,0]
	global_store_dwordx4 v[120:121], v[116:119], off
	v_pk_mul_f32 v[112:113], v[112:113], v[180:181] op_sel_hi:[1,0]
	v_pk_mul_f32 v[104:105], v[104:105], v[180:181] op_sel_hi:[1,0]
	v_pk_mul_f32 v[118:119], v[110:111], s[24:25] op_sel_hi:[1,0]
	v_pk_mul_f32 v[102:103], v[102:103], v[180:181] op_sel_hi:[1,0]
	v_pk_mul_f32 v[106:107], v[106:107], v[180:181] op_sel_hi:[1,0]
	v_pk_mul_f32 v[108:109], v[108:109], v[180:181] op_sel_hi:[1,0]
	v_pk_mul_f32 v[116:117], v[112:113], s[24:25] op_sel_hi:[1,0]
	v_exp_f32_e32 v118, v118
	v_exp_f32_e32 v119, v119
	v_pk_mul_f32 v[102:103], v[110:111], v[102:103]
	v_pk_mul_f32 v[104:105], v[112:113], v[104:105]
	v_pk_mul_f32 v[110:111], v[108:109], s[24:25] op_sel_hi:[1,0]
	v_pk_mul_f32 v[112:113], v[106:107], s[24:25] op_sel_hi:[1,0]
	v_exp_f32_e32 v110, v110
	v_exp_f32_e32 v112, v112
	v_exp_f32_e32 v111, v111
	v_exp_f32_e32 v113, v113
	v_exp_f32_e32 v116, v116
	v_exp_f32_e32 v117, v117
	v_pk_add_f32 v[118:119], v[118:119], 1.0 op_sel_hi:[1,0]
	v_rcp_f32_e32 v118, v118
	v_rcp_f32_e32 v119, v119
	v_pk_add_f32 v[110:111], v[110:111], 1.0 op_sel_hi:[1,0]
	v_pk_add_f32 v[112:113], v[112:113], 1.0 op_sel_hi:[1,0]
	v_rcp_f32_e32 v112, v112
	v_rcp_f32_e32 v110, v110
	v_rcp_f32_e32 v111, v111
	v_rcp_f32_e32 v113, v113
	v_pk_add_f32 v[116:117], v[116:117], 1.0 op_sel_hi:[1,0]
	v_pk_mul_f32 v[100:101], v[100:101], v[180:181] op_sel_hi:[1,0]
	v_pk_mul_f32 v[98:99], v[98:99], v[180:181] op_sel_hi:[1,0]
	v_mov_b32_e32 v174, v245
	v_rcp_f32_e32 v116, v116
	v_rcp_f32_e32 v117, v117
	v_pk_mul_f32 v[102:103], v[102:103], v[118:119]
	v_pk_mul_f32 v[98:99], v[106:107], v[98:99]
	v_pk_mul_f32 v[100:101], v[108:109], v[100:101]
	v_pk_mul_f32 v[104:105], v[104:105], v[116:117]
	v_pk_mul_f32 v[106:107], v[100:101], v[110:111]
	v_pk_mul_f32 v[100:101], v[98:99], v[112:113]
	v_cvt_pk_bf16_f32 v98, v102, v103
	v_mad_i64_i32 v[102:103], s[18:19], v172, s60, v[114:115]
	v_lshl_add_u64 v[102:103], v[102:103], 0, s[36:37]
	v_lshl_add_u64 v[102:103], v[102:103], 0, s[0:1]
	v_cvt_pk_bf16_f32 v99, v104, v105
	v_cvt_pk_bf16_f32 v100, v100, v101
	v_cvt_pk_bf16_f32 v101, v106, v107
	v_lshl_add_u64 v[102:103], v[102:103], 0, v[138:139]
	v_pk_mul_f32 v[94:95], v[94:95], v[174:175] op_sel_hi:[1,0]
	global_store_dwordx4 v[102:103], v[98:101], off
	v_pk_mul_f32 v[96:97], v[96:97], v[174:175] op_sel_hi:[1,0]
	v_pk_mul_f32 v[88:89], v[88:89], v[174:175] op_sel_hi:[1,0]
	v_pk_mul_f32 v[100:101], v[94:95], s[24:25] op_sel_hi:[1,0]
; __device__ __forceinline__ u32x4 pack8(const f32x4 a, const f32x4 b) { u32x4 w; w.x = pk2(a[0], a[1]); w.y = pk2(a[2], a[3]); w.z = pk2(b[0], b[1]); w.w = pk2(b[2], b[3]); return w; }
;     __device__ __forceinline__ void operator()(const Acc& acc, const Unit& u, int wr, int wc, int fr, int fq) const {
;     ...
;                 const int row = row0 + ai * 128 + m * 16; const float r1 = rs[ai * 4 + m];
;                 f32x4 o[2];
; #pragma unroll
;                 for (int n = 0; n < 2; ++n) {
;                     const f32x4 gs = acc[ai][0][m][n] * r1, us = acc[ai][1][m][n] * r1, t = gs * -1.4426950408889634f;
;                     f32x4 d; d[0] = __builtin_amdgcn_exp2f(t[0]); d[1] = __builtin_amdgcn_exp2f(t[1]); d[2] = __builtin_amdgcn_exp2f(t[2]); d[3] = __builtin_amdgcn_exp2f(t[3]);
;                     d = d + 1.0f;
;                     f32x4 r; r[0] = __builtin_amdgcn_rcpf(d[0]); r[1] = __builtin_amdgcn_rcpf(d[1]); r[2] = __builtin_amdgcn_rcpf(d[2]); r[3] = __builtin_amdgcn_rcpf(d[3]);
;                     o[n] = (gs * us) * r;
;                 }
;                 *(u32x4*)(hid + (size_t)row * FF + u.pn * 128 + wc * 32 + 8 * fq) = pack8(o[0], o[1]);
	v_pk_mul_f32 v[86:87], v[86:87], v[174:175] op_sel_hi:[1,0]
	v_pk_mul_f32 v[90:91], v[90:91], v[174:175] op_sel_hi:[1,0]
	v_pk_mul_f32 v[92:93], v[92:93], v[174:175] op_sel_hi:[1,0]
	v_pk_mul_f32 v[98:99], v[96:97], s[24:25] op_sel_hi:[1,0]
	v_exp_f32_e32 v100, v100
	v_exp_f32_e32 v101, v101
	v_pk_mul_f32 v[86:87], v[94:95], v[86:87]
	v_pk_mul_f32 v[88:89], v[96:97], v[88:89]
	v_pk_mul_f32 v[94:95], v[92:93], s[24:25] op_sel_hi:[1,0]
	v_pk_mul_f32 v[96:97], v[90:91], s[24:25] op_sel_hi:[1,0]
	v_exp_f32_e32 v94, v94
	v_exp_f32_e32 v96, v96
	v_exp_f32_e32 v95, v95
	v_exp_f32_e32 v97, v97
	v_exp_f32_e32 v98, v98
	v_exp_f32_e32 v99, v99
	v_pk_add_f32 v[100:101], v[100:101], 1.0 op_sel_hi:[1,0]
	v_rcp_f32_e32 v100, v100
	v_rcp_f32_e32 v101, v101
	v_pk_add_f32 v[94:95], v[94:95], 1.0 op_sel_hi:[1,0]
	v_pk_add_f32 v[96:97], v[96:97], 1.0 op_sel_hi:[1,0]
	v_rcp_f32_e32 v96, v96
	v_rcp_f32_e32 v94, v94
	v_rcp_f32_e32 v95, v95
	v_rcp_f32_e32 v97, v97
	v_pk_add_f32 v[98:99], v[98:99], 1.0 op_sel_hi:[1,0]
	v_pk_mul_f32 v[84:85], v[84:85], v[174:175] op_sel_hi:[1,0]
	v_pk_mul_f32 v[82:83], v[82:83], v[174:175] op_sel_hi:[1,0]
	v_mov_b32_e32 v170, v246
	v_rcp_f32_e32 v98, v98
	v_rcp_f32_e32 v99, v99
	v_pk_mul_f32 v[86:87], v[86:87], v[100:101]
	v_pk_mul_f32 v[82:83], v[90:91], v[82:83]
	v_pk_mul_f32 v[84:85], v[92:93], v[84:85]
	v_pk_mul_f32 v[88:89], v[88:89], v[98:99]
	v_pk_mul_f32 v[90:91], v[84:85], v[94:95]
	v_pk_mul_f32 v[84:85], v[82:83], v[96:97]
	v_cvt_pk_bf16_f32 v82, v86, v87
	v_mad_i64_i32 v[86:87], s[18:19], v168, s60, v[114:115]
	v_lshl_add_u64 v[86:87], v[86:87], 0, s[36:37]
	v_lshl_add_u64 v[86:87], v[86:87], 0, s[0:1]
	v_cvt_pk_bf16_f32 v83, v88, v89
	v_cvt_pk_bf16_f32 v84, v84, v85
	v_cvt_pk_bf16_f32 v85, v90, v91
	v_lshl_add_u64 v[86:87], v[86:87], 0, v[138:139]
	v_pk_mul_f32 v[78:79], v[78:79], v[170:171] op_sel_hi:[1,0]
	global_store_dwordx4 v[86:87], v[82:85], off
	v_pk_mul_f32 v[80:81], v[80:81], v[170:171] op_sel_hi:[1,0]
	v_pk_mul_f32 v[72:73], v[72:73], v[170:171] op_sel_hi:[1,0]
	v_pk_mul_f32 v[84:85], v[78:79], s[24:25] op_sel_hi:[1,0]
	v_pk_mul_f32 v[70:71], v[70:71], v[170:171] op_sel_hi:[1,0]
	v_pk_mul_f32 v[74:75], v[74:75], v[170:171] op_sel_hi:[1,0]
	v_pk_mul_f32 v[76:77], v[76:77], v[170:171] op_sel_hi:[1,0]
	v_pk_mul_f32 v[82:83], v[80:81], s[24:25] op_sel_hi:[1,0]
	v_exp_f32_e32 v84, v84
	v_exp_f32_e32 v85, v85
	v_pk_mul_f32 v[70:71], v[78:79], v[70:71]
	v_pk_mul_f32 v[72:73], v[80:81], v[72:73]
	v_pk_mul_f32 v[78:79], v[76:77], s[24:25] op_sel_hi:[1,0]
	v_pk_mul_f32 v[80:81], v[74:75], s[24:25] op_sel_hi:[1,0]
	v_exp_f32_e32 v78, v78
	v_exp_f32_e32 v80, v80
	v_exp_f32_e32 v79, v79
	v_exp_f32_e32 v81, v81
	v_exp_f32_e32 v82, v82
	v_exp_f32_e32 v83, v83
	v_pk_add_f32 v[84:85], v[84:85], 1.0 op_sel_hi:[1,0]
	v_rcp_f32_e32 v84, v84
	v_rcp_f32_e32 v85, v85
	v_pk_add_f32 v[78:79], v[78:79], 1.0 op_sel_hi:[1,0]
	v_pk_add_f32 v[80:81], v[80:81], 1.0 op_sel_hi:[1,0]
	v_rcp_f32_e32 v80, v80
	v_rcp_f32_e32 v78, v78
	v_rcp_f32_e32 v79, v79
	v_rcp_f32_e32 v81, v81
	v_pk_add_f32 v[82:83], v[82:83], 1.0 op_sel_hi:[1,0]
	v_pk_mul_f32 v[68:69], v[68:69], v[170:171] op_sel_hi:[1,0]
	v_pk_mul_f32 v[66:67], v[66:67], v[170:171] op_sel_hi:[1,0]
	v_mov_b32_e32 v166, v247
	v_rcp_f32_e32 v82, v82
	v_rcp_f32_e32 v83, v83
	v_pk_mul_f32 v[70:71], v[70:71], v[84:85]
	v_pk_mul_f32 v[66:67], v[74:75], v[66:67]
	v_pk_mul_f32 v[68:69], v[76:77], v[68:69]
	v_pk_mul_f32 v[72:73], v[72:73], v[82:83]
	v_pk_mul_f32 v[74:75], v[68:69], v[78:79]
	v_pk_mul_f32 v[68:69], v[66:67], v[80:81]
	v_cvt_pk_bf16_f32 v66, v70, v71
	v_mad_i64_i32 v[70:71], s[18:19], v164, s60, v[114:115]
	v_lshl_add_u64 v[70:71], v[70:71], 0, s[36:37]
	v_lshl_add_u64 v[70:71], v[70:71], 0, s[0:1]
	v_cvt_pk_bf16_f32 v67, v72, v73
	v_cvt_pk_bf16_f32 v68, v68, v69
	v_cvt_pk_bf16_f32 v69, v74, v75
	v_lshl_add_u64 v[70:71], v[70:71], 0, v[138:139]
	v_pk_mul_f32 v[62:63], v[62:63], v[166:167] op_sel_hi:[1,0]
	global_store_dwordx4 v[70:71], v[66:69], off
	v_pk_mul_f32 v[64:65], v[64:65], v[166:167] op_sel_hi:[1,0]
	v_pk_mul_f32 v[56:57], v[56:57], v[166:167] op_sel_hi:[1,0]
	v_pk_mul_f32 v[68:69], v[62:63], s[24:25] op_sel_hi:[1,0]
	v_pk_mul_f32 v[54:55], v[54:55], v[166:167] op_sel_hi:[1,0]
	v_pk_mul_f32 v[58:59], v[58:59], v[166:167] op_sel_hi:[1,0]
	v_pk_mul_f32 v[60:61], v[60:61], v[166:167] op_sel_hi:[1,0]
	v_pk_mul_f32 v[66:67], v[64:65], s[24:25] op_sel_hi:[1,0]
	v_exp_f32_e32 v68, v68
	v_exp_f32_e32 v69, v69
	v_pk_mul_f32 v[54:55], v[62:63], v[54:55]
	v_pk_mul_f32 v[56:57], v[64:65], v[56:57]
	v_pk_mul_f32 v[62:63], v[60:61], s[24:25] op_sel_hi:[1,0]
	v_pk_mul_f32 v[64:65], v[58:59], s[24:25] op_sel_hi:[1,0]
	v_exp_f32_e32 v64, v64
	v_exp_f32_e32 v62, v62
	v_exp_f32_e32 v63, v63
	v_exp_f32_e32 v65, v65
	v_exp_f32_e32 v66, v66
	v_exp_f32_e32 v67, v67
	v_pk_add_f32 v[68:69], v[68:69], 1.0 op_sel_hi:[1,0]
	v_rcp_f32_e32 v68, v68
	v_rcp_f32_e32 v69, v69
	v_pk_add_f32 v[62:63], v[62:63], 1.0 op_sel_hi:[1,0]
	v_pk_add_f32 v[64:65], v[64:65], 1.0 op_sel_hi:[1,0]
	v_rcp_f32_e32 v64, v64
	v_rcp_f32_e32 v62, v62
	v_rcp_f32_e32 v63, v63
	v_rcp_f32_e32 v65, v65
	v_pk_add_f32 v[66:67], v[66:67], 1.0 op_sel_hi:[1,0]
	v_pk_mul_f32 v[52:53], v[52:53], v[166:167] op_sel_hi:[1,0]
	v_pk_mul_f32 v[50:51], v[50:51], v[166:167] op_sel_hi:[1,0]
	v_mov_b32_e32 v162, v248
	v_rcp_f32_e32 v66, v66
	v_rcp_f32_e32 v67, v67
	v_pk_mul_f32 v[54:55], v[54:55], v[68:69]
	v_pk_mul_f32 v[50:51], v[58:59], v[50:51]
	v_pk_mul_f32 v[52:53], v[60:61], v[52:53]
	v_pk_mul_f32 v[56:57], v[56:57], v[66:67]
	v_pk_mul_f32 v[58:59], v[52:53], v[62:63]
	v_pk_mul_f32 v[52:53], v[50:51], v[64:65]
	v_cvt_pk_bf16_f32 v50, v54, v55
; #define PG8_BAR __builtin_amdgcn_s_barrier()
; __device__ __forceinline__ u32x4 pack8(const f32x4 a, const f32x4 b) { u32x4 w; w.x = pk2(a[0], a[1]); w.y = pk2(a[2], a[3]); w.z = pk2(b[0], b[1]); w.w = pk2(b[2], b[3]); return w; }
; template <class Epi, class Sched, bool ALIGN_EPI = false, bool SP2 = false>
; __device__ __forceinline__ void gemm_phase(PG8_LAS unsigned char* lds, const Gemm g, const Sched& S, const Epi& E, const int tid) {
;     ...
;         if constexpr (ALIGN_EPI) { if (wr == 0) PG8_BAR; }
;         if constexpr (!Epi::AFTER_DRAIN) { E(acc, cur, wr, wc, fr, fq); S.done(cur); }
;         if (!has_next) break;
; #pragma unroll
;         for (int a = 0; a < 2; ++a)
; #pragma unroll
;             for (int b = 0; b < 2; ++b)
; #pragma unroll
;                 for (int m = 0; m < 4; ++m)
; #pragma unroll
;                     for (int n = 0; n < 2; ++n) acc[a][b][m][n] = (f32x4){0.f, 0.f, 0.f, 0.f};
;         cur = nxt; cA = nA; cB = nB; ++ui;
;         if constexpr (ALIGN_EPI) { if (wr == 1) PG8_BAR; }
;     __device__ __forceinline__ void operator()(const Acc& acc, const Unit& u, int wr, int wc, int fr, int fq) const {
;     ...
;                 const int row = row0 + ai * 128 + m * 16; const float r1 = rs[ai * 4 + m];
;                 f32x4 o[2];
; #pragma unroll
;                 for (int n = 0; n < 2; ++n) {
;                     const f32x4 gs = acc[ai][0][m][n] * r1, us = acc[ai][1][m][n] * r1, t = gs * -1.4426950408889634f;
;                     f32x4 d; d[0] = __builtin_amdgcn_exp2f(t[0]); d[1] = __builtin_amdgcn_exp2f(t[1]); d[2] = __builtin_amdgcn_exp2f(t[2]); d[3] = __builtin_amdgcn_exp2f(t[3]);
;                     d = d + 1.0f;
;                     f32x4 r; r[0] = __builtin_amdgcn_rcpf(d[0]); r[1] = __builtin_amdgcn_rcpf(d[1]); r[2] = __builtin_amdgcn_rcpf(d[2]); r[3] = __builtin_amdgcn_rcpf(d[3]);
;                     o[n] = (gs * us) * r;
;                 }
;                 *(u32x4*)(hid + (size_t)row * FF + u.pn * 128 + wc * 32 + 8 * fq) = pack8(o[0], o[1]);
	v_mad_i64_i32 v[54:55], s[18:19], v158, s60, v[114:115]
	v_lshl_add_u64 v[54:55], v[54:55], 0, s[36:37]
	v_lshl_add_u64 v[54:55], v[54:55], 0, s[0:1]
	v_cvt_pk_bf16_f32 v51, v56, v57
	v_cvt_pk_bf16_f32 v52, v52, v53
	v_cvt_pk_bf16_f32 v53, v58, v59
	v_lshl_add_u64 v[54:55], v[54:55], 0, v[138:139]
	v_pk_mul_f32 v[46:47], v[46:47], v[162:163] op_sel_hi:[1,0]
	global_store_dwordx4 v[54:55], v[50:53], off
	v_pk_mul_f32 v[48:49], v[48:49], v[162:163] op_sel_hi:[1,0]
	v_pk_mul_f32 v[40:41], v[40:41], v[162:163] op_sel_hi:[1,0]
	v_pk_mul_f32 v[52:53], v[46:47], s[24:25] op_sel_hi:[1,0]
	v_pk_mul_f32 v[38:39], v[38:39], v[162:163] op_sel_hi:[1,0]
	v_pk_mul_f32 v[42:43], v[42:43], v[162:163] op_sel_hi:[1,0]
	v_pk_mul_f32 v[44:45], v[44:45], v[162:163] op_sel_hi:[1,0]
	v_pk_mul_f32 v[50:51], v[48:49], s[24:25] op_sel_hi:[1,0]
	v_exp_f32_e32 v52, v52
	v_exp_f32_e32 v53, v53
	v_pk_mul_f32 v[38:39], v[46:47], v[38:39]
	v_pk_mul_f32 v[40:41], v[48:49], v[40:41]
	v_pk_mul_f32 v[46:47], v[44:45], s[24:25] op_sel_hi:[1,0]
	v_pk_mul_f32 v[48:49], v[42:43], s[24:25] op_sel_hi:[1,0]
	v_exp_f32_e32 v48, v48
	v_exp_f32_e32 v46, v46
	v_exp_f32_e32 v47, v47
	v_exp_f32_e32 v49, v49
	v_exp_f32_e32 v50, v50
	v_exp_f32_e32 v51, v51
	v_pk_add_f32 v[52:53], v[52:53], 1.0 op_sel_hi:[1,0]
	v_rcp_f32_e32 v52, v52
	v_rcp_f32_e32 v53, v53
	v_pk_add_f32 v[46:47], v[46:47], 1.0 op_sel_hi:[1,0]
	v_pk_add_f32 v[48:49], v[48:49], 1.0 op_sel_hi:[1,0]
	v_rcp_f32_e32 v48, v48
	v_rcp_f32_e32 v46, v46
	v_rcp_f32_e32 v47, v47
	v_rcp_f32_e32 v49, v49
	v_pk_add_f32 v[50:51], v[50:51], 1.0 op_sel_hi:[1,0]
	v_pk_mul_f32 v[36:37], v[36:37], v[162:163] op_sel_hi:[1,0]
	v_pk_mul_f32 v[34:35], v[34:35], v[162:163] op_sel_hi:[1,0]
	v_mov_b32_e32 v160, v249
	v_rcp_f32_e32 v50, v50
	v_rcp_f32_e32 v51, v51
	v_pk_mul_f32 v[38:39], v[38:39], v[52:53]
	v_pk_mul_f32 v[34:35], v[42:43], v[34:35]
	v_pk_mul_f32 v[36:37], v[44:45], v[36:37]
	v_pk_mul_f32 v[40:41], v[40:41], v[50:51]
	v_pk_mul_f32 v[42:43], v[36:37], v[46:47]
	v_pk_mul_f32 v[36:37], v[34:35], v[48:49]
	v_cvt_pk_bf16_f32 v34, v38, v39
	v_mad_i64_i32 v[38:39], s[18:19], v154, s60, v[114:115]
	v_lshl_add_u64 v[38:39], v[38:39], 0, s[36:37]
	v_lshl_add_u64 v[38:39], v[38:39], 0, s[0:1]
	v_cvt_pk_bf16_f32 v35, v40, v41
	v_cvt_pk_bf16_f32 v36, v36, v37
	v_cvt_pk_bf16_f32 v37, v42, v43
	v_lshl_add_u64 v[38:39], v[38:39], 0, v[138:139]
	v_pk_mul_f32 v[30:31], v[30:31], v[160:161] op_sel_hi:[1,0]
	global_store_dwordx4 v[38:39], v[34:37], off
	v_pk_mul_f32 v[32:33], v[32:33], v[160:161] op_sel_hi:[1,0]
	v_pk_mul_f32 v[24:25], v[24:25], v[160:161] op_sel_hi:[1,0]
	v_pk_mul_f32 v[36:37], v[30:31], s[24:25] op_sel_hi:[1,0]
	v_pk_mul_f32 v[22:23], v[22:23], v[160:161] op_sel_hi:[1,0]
	v_pk_mul_f32 v[26:27], v[26:27], v[160:161] op_sel_hi:[1,0]
	v_pk_mul_f32 v[28:29], v[28:29], v[160:161] op_sel_hi:[1,0]
	v_pk_mul_f32 v[34:35], v[32:33], s[24:25] op_sel_hi:[1,0]
	v_exp_f32_e32 v36, v36
	v_exp_f32_e32 v37, v37
	v_pk_mul_f32 v[22:23], v[30:31], v[22:23]
	v_pk_mul_f32 v[24:25], v[32:33], v[24:25]
	v_pk_mul_f32 v[30:31], v[28:29], s[24:25] op_sel_hi:[1,0]
	v_pk_mul_f32 v[32:33], v[26:27], s[24:25] op_sel_hi:[1,0]
	v_exp_f32_e32 v32, v32
	v_exp_f32_e32 v30, v30
	v_exp_f32_e32 v31, v31
	v_exp_f32_e32 v33, v33
	v_exp_f32_e32 v34, v34
	v_exp_f32_e32 v35, v35
	v_pk_add_f32 v[36:37], v[36:37], 1.0 op_sel_hi:[1,0]
	v_rcp_f32_e32 v36, v36
	v_rcp_f32_e32 v37, v37
	v_pk_add_f32 v[30:31], v[30:31], 1.0 op_sel_hi:[1,0]
	v_pk_add_f32 v[32:33], v[32:33], 1.0 op_sel_hi:[1,0]
	v_rcp_f32_e32 v32, v32
	v_rcp_f32_e32 v30, v30
	v_rcp_f32_e32 v31, v31
	v_rcp_f32_e32 v33, v33
	v_pk_add_f32 v[34:35], v[34:35], 1.0 op_sel_hi:[1,0]
	v_pk_mul_f32 v[20:21], v[20:21], v[160:161] op_sel_hi:[1,0]
	v_pk_mul_f32 v[18:19], v[18:19], v[160:161] op_sel_hi:[1,0]
	v_mov_b32_e32 v156, v250
	v_rcp_f32_e32 v34, v34
	v_rcp_f32_e32 v35, v35
	v_pk_mul_f32 v[22:23], v[22:23], v[36:37]
	v_pk_mul_f32 v[18:19], v[26:27], v[18:19]
	v_pk_mul_f32 v[20:21], v[28:29], v[20:21]
	v_pk_mul_f32 v[24:25], v[24:25], v[34:35]
	v_pk_mul_f32 v[26:27], v[20:21], v[30:31]
	v_pk_mul_f32 v[20:21], v[18:19], v[32:33]
	v_cvt_pk_bf16_f32 v18, v22, v23
	v_mad_i64_i32 v[22:23], s[18:19], v152, s60, v[114:115]
	v_lshl_add_u64 v[22:23], v[22:23], 0, s[36:37]
	v_lshl_add_u64 v[22:23], v[22:23], 0, s[0:1]
	v_cvt_pk_bf16_f32 v19, v24, v25
	v_cvt_pk_bf16_f32 v20, v20, v21
	v_cvt_pk_bf16_f32 v21, v26, v27
	v_lshl_add_u64 v[22:23], v[22:23], 0, v[138:139]
	v_pk_mul_f32 v[14:15], v[14:15], v[156:157] op_sel_hi:[1,0]
	global_store_dwordx4 v[22:23], v[18:21], off
	v_pk_mul_f32 v[16:17], v[16:17], v[156:157] op_sel_hi:[1,0]
	v_pk_mul_f32 v[8:9], v[8:9], v[156:157] op_sel_hi:[1,0]
	v_pk_mul_f32 v[20:21], v[14:15], s[24:25] op_sel_hi:[1,0]
	v_pk_mul_f32 v[6:7], v[6:7], v[156:157] op_sel_hi:[1,0]
	v_pk_mul_f32 v[10:11], v[10:11], v[156:157] op_sel_hi:[1,0]
	v_pk_mul_f32 v[12:13], v[12:13], v[156:157] op_sel_hi:[1,0]
	v_pk_mul_f32 v[18:19], v[16:17], s[24:25] op_sel_hi:[1,0]
	v_exp_f32_e32 v20, v20
	v_exp_f32_e32 v21, v21
	v_pk_mul_f32 v[6:7], v[14:15], v[6:7]
	v_pk_mul_f32 v[8:9], v[16:17], v[8:9]
	v_pk_mul_f32 v[14:15], v[12:13], s[24:25] op_sel_hi:[1,0]
	v_pk_mul_f32 v[16:17], v[10:11], s[24:25] op_sel_hi:[1,0]
	v_exp_f32_e32 v14, v14
	v_exp_f32_e32 v16, v16
	v_exp_f32_e32 v15, v15
	v_exp_f32_e32 v17, v17
	v_pk_add_f32 v[20:21], v[20:21], 1.0 op_sel_hi:[1,0]
	v_exp_f32_e32 v18, v18
	v_exp_f32_e32 v19, v19
	v_rcp_f32_e32 v20, v20
	v_rcp_f32_e32 v21, v21
	v_pk_add_f32 v[14:15], v[14:15], 1.0 op_sel_hi:[1,0]
	v_pk_add_f32 v[16:17], v[16:17], 1.0 op_sel_hi:[1,0]
	v_rcp_f32_e32 v14, v14
	v_rcp_f32_e32 v16, v16
	v_rcp_f32_e32 v15, v15
	v_rcp_f32_e32 v17, v17
	v_pk_mul_f32 v[4:5], v[4:5], v[156:157] op_sel_hi:[1,0]
	v_pk_mul_f32 v[2:3], v[2:3], v[156:157] op_sel_hi:[1,0]
	v_pk_add_f32 v[18:19], v[18:19], 1.0 op_sel_hi:[1,0]
	v_pk_mul_f32 v[6:7], v[6:7], v[20:21]
	v_pk_mul_f32 v[2:3], v[10:11], v[2:3]
	v_pk_mul_f32 v[4:5], v[12:13], v[4:5]
	v_rcp_f32_e32 v18, v18
	v_rcp_f32_e32 v19, v19
	v_pk_mul_f32 v[10:11], v[4:5], v[14:15]
	v_pk_mul_f32 v[4:5], v[2:3], v[16:17]
	v_cvt_pk_bf16_f32 v2, v6, v7
	v_mad_i64_i32 v[6:7], s[18:19], v150, s60, v[114:115]
	v_lshl_add_u64 v[6:7], v[6:7], 0, s[36:37]
	v_lshl_add_u64 v[6:7], v[6:7], 0, s[0:1]
	v_lshl_add_u64 v[6:7], v[6:7], 0, v[138:139]
	v_pk_mul_f32 v[8:9], v[8:9], v[18:19]
	s_nop 0
	v_cvt_pk_bf16_f32 v3, v8, v9
	v_cvt_pk_bf16_f32 v4, v4, v5
	v_cvt_pk_bf16_f32 v5, v10, v11
	global_store_dwordx4 v[6:7], v[2:5], off
	s_cbranch_vccnz .LBB0_331
	s_andn2_b64 vcc, exec, s[4:5]
	s_cbranch_vccnz .LBB0_330
	s_mov_b32 s101, 1
	s_branch .LBB0_330

;     __device__ __forceinline__ bool next(int i, pg8::Unit& u) const { if (!base.next(i >> 2, u)) return false; u.sub = i & 3; return true; }
;     __host__ __device__ bool next(int i, Unit& u) const {
;         const long L = (long)i * G + c; if (L >= nwg) return false;
;         int wgid = (int)L; { const int q = nwg / NXCD, r = nwg % NXCD, xcd = wgid % NXCD, off = wgid / NXCD; wgid = (xcd < r ? xcd * (q + 1) : r * (q + 1) + (xcd - r) * q) + off; }
;         const int nig = WGM * nN, gid = wgid / nig, fm = gid * WGM, gsz = (nM - fm) < WGM ? (nM - fm) : WGM;
;         u.pm = fm + ((wgid % nig) % gsz); u.pn = (wgid % nig) / gsz; u.sub = 0; return true;
; template <class Epi, class Sched, bool ALIGN_EPI = false, bool SP2 = false>
; __device__ __forceinline__ void gemm_phase(PG8_LAS unsigned char* lds, const Gemm g, const Sched& S, const Epi& E, const int tid) {
;     ...
;     Unit cur, nxt; int ui = 0;
;     if (!S.next(0, cur)) return;
.LBB0_408:
	s_mov_b32 s101, 0
	s_add_i32 s0, 0, 0x204b0
	v_mov_b32_e32 v1, v190
	s_mov_b32 s48, s14
	s_mov_b32 s49, s16
	v_mov_b32_e32 v2, s0
	ds_read_b64 v[2:3], v2
	s_cmpk_lt_i32 s48, 0x308
	s_cselect_b64 s[0:1], -1, 0
	s_cmpk_gt_i32 s48, 0x307
	v_readfirstlane_b32 s2, v1
	s_waitcnt lgkmcnt(0)
	v_readfirstlane_b32 s25, v3
	v_readfirstlane_b32 s24, v2
	s_cbranch_scc1 .LBB0_410
	s_ashr_i32 s3, s48, 31
	s_lshr_b32 s3, s3, 29
	s_add_i32 s3, s48, s3
	s_ashr_i32 s4, s3, 3
	s_and_b32 s3, s3, -8
	s_sub_i32 s3, s48, s3
	s_cmp_lt_i32 s3, 0
	s_movk_i32 s5, 0x62
	s_cselect_b32 s5, s5, 0x61
	s_mul_i32 s3, s5, s3
	s_add_i32 s3, s3, s4
	s_ashr_i32 s4, s3, 31
	s_lshr_b32 s4, s4, 27
	s_add_i32 s4, s3, s4
	s_ashr_i32 s5, s4, 5
	s_lshl_b32 s6, s5, 3
	s_sub_i32 s5, 0xc2, s6
	s_min_u32 s7, s5, 8
	s_andn2_b32 s4, s4, 31
	s_sub_i32 s3, s3, s4
	v_cvt_f32_ubyte0_e32 v3, s7
	v_cvt_f32_i32_e32 v2, s3
	v_rcp_iflag_f32_e32 v4, v3
	s_ashr_i32 s4, s3, 30
	s_or_b32 s8, s4, 1
	v_mul_f32_e32 v4, v2, v4
	v_trunc_f32_e32 v4, v4
	v_fma_f32 v2, -v4, v3, v2
	v_cvt_i32_f32_e32 v4, v4
	v_cmp_ge_f32_e64 s[4:5], |v2|, v3
	s_and_b64 s[4:5], s[4:5], exec
	s_cselect_b32 s4, s8, 0
	v_readfirstlane_b32 s5, v4
	s_add_i32 s4, s5, s4
	s_sext_i32_i8 s46, s4
	s_mul_i32 s4, s4, s7
	s_sub_i32 s3, s3, s4
	s_sext_i32_i8 s3, s3
	s_add_i32 s44, s6, s3

; #define PG8_STAGE(bufoff, gbase, voff) do { _Pragma("unroll") for (int _i = 0; _i < 2; ++_i) \
;         __builtin_amdgcn_global_load_lds((const unsigned*)((const char*)(gbase) + (voff)[_i]), (PG8_LAS unsigned*)(lds + (bufoff) + ldsw + _i * 8192), 16, 0, 0); } while (0)
; #define PG8_LDA(dst, b, h) do { _Pragma("unroll") for (int m = 0; m < 4; ++m) _Pragma("unroll") for (int k = 0; k < 2; ++k) dst[m][k] = *(const PG8_LAS bf16x8*)(lds + PG8_SA(b, h) + aoff + m * 2048 + k * 1024); } while (0)
; #define PG8_LDB(dst, b, h) do { _Pragma("unroll") for (int n = 0; n < 2; ++n) _Pragma("unroll") for (int k = 0; k < 2; ++k) dst[n][k] = *(const PG8_LAS bf16x8*)(lds + PG8_SB(b, h) + boff + n * 2048 + k * 1024); } while (0)
; #define PG8_MMA(ai, bj, At, Bt) do { __builtin_amdgcn_s_setprio(1); _Pragma("unroll") for (int m = 0; m < 4; ++m) _Pragma("unroll") for (int n = 0; n < 2; ++n) _Pragma("unroll") for (int k = 0; k < 2; ++k) \
;         acc[ai][bj][m][n] = __builtin_amdgcn_mfma_f32_16x16x32_bf16(Bt[n][k], At[m][k], acc[ai][bj][m][n], 0, 0, 0); __builtin_amdgcn_s_setprio(0); } while (0)
; #define PG8_WAIT_V(n) asm volatile("s_waitcnt vmcnt(" #n ")" ::: "memory")
; #define PG8_WAIT_L(n) asm volatile("s_waitcnt lgkmcnt(" #n ")" ::: "memory")
; template <class Epi, class Sched, bool ALIGN_EPI = false, bool SP2 = false>
; __device__ __forceinline__ void gemm_phase(PG8_LAS unsigned char* lds, const Gemm g, const Sched& S, const Epi& E, const int tid) {
;     ...
;             const bool last = (t == nt - 2);
;             const char* a1 = cA + (size_t)(t + 1) * kstep;
;             const char* a2 = last ? nA : cA + (size_t)(t + 2) * kstep; const char* b2 = last ? nB : cB + (size_t)(t + 2) * kstep;
;             const char* a3 = a2 + kstep; const char* b3 = b2 + kstep;
;             if (last && has_next) S.a_ready(nxt);
;             if constexpr (SP2) {
;             PG8_LDB(B0, 0, 0); PG8_LDB(B1, 0, 1); PG8_SCHED; PG8_LDA(At, 0, 0); PG8_STAGE(PG8_SA(1, 1), a1 + hstep, voffA);
;             PG8_WAIT_V(8); PG8_WAIT_L(0); PG8_BAR; PG8_MMA(0, 0, At, B0); PG8_MMA(0, 1, At, B1); PG8_BAR; PG8_SCHED;
;             PG8_LDA(At, 0, 1); PG8_STAGE(PG8_SB(0, 0), b2, voffB); PG8_STAGE(PG8_SB(0, 1), b2 + hstep, voffB); PG8_STAGE(PG8_SA(0, 0), a2, voffA);
;             PG8_WAIT_V(8); PG8_WAIT_L(0); PG8_BAR; PG8_MMA(1, 0, At, B0); PG8_MMA(1, 1, At, B1); PG8_BAR; PG8_SCHED;
.LBB0_422:
	s_add_u32 s45, s8, 0x100
	s_addc_u32 s47, s9, 0
	s_mov_b32 s77, -2
	s_cmp_eq_u32 s101, 0
	s_cbranch_scc1 .Lnobar1
	s_barrier
.Lnobar1:
	ds_read_b128 v[130:133], v205
	ds_read_b128 v[134:137], v205 offset:1024
	ds_read_b128 v[138:141], v205 offset:2048
	ds_read_b128 v[142:145], v205 offset:3072
	ds_read_b128 v[146:149], v206
	ds_read_b128 v[150:153], v206 offset:1024
	ds_read_b128 v[154:157], v206 offset:2048
	ds_read_b128 v[158:161], v206 offset:3072
	s_add_u32 s8, s6, 0x100
	s_addc_u32 s9, s7, 0
	s_cmp_eq_u32 s77, 40
	s_cselect_b32 s43, s1, s9
	s_cselect_b32 s42, s0, s8
	s_cselect_b32 s11, s41, s47
	s_cselect_b32 s10, s40, s45
	v_lshl_add_u64 v[220:221], s[6:7], 0, v[176:177]
	s_add_i32 m0, s56, 0xc000
	ds_read_b128 v[182:185], v207
	ds_read_b128 v[186:189], v207 offset:1024
	ds_read_b128 v[192:195], v207 offset:2048
	ds_read_b128 v[196:199], v207 offset:3072
	ds_read_b128 v[200:203], v207 offset:4096
	ds_read_b128 v[208:211], v207 offset:5120
	ds_read_b128 v[212:215], v207 offset:6144
	ds_read_b128 v[216:219], v207 offset:7168
	global_load_lds_dwordx4 v[220:221], off
	v_lshl_add_u64 v[220:221], s[6:7], 0, v[174:175]
	s_add_i32 m0, s56, 0xe000
	s_nop 0
	global_load_lds_dwordx4 v[220:221], off
	s_waitcnt vmcnt(8)
	s_waitcnt lgkmcnt(0)
	s_barrier
	s_setprio 1
	s_waitcnt lgkmcnt(0)
	v_mfma_f32_16x16x32_bf16 v[126:129], v[130:133], v[182:185], 0
	v_mfma_f32_16x16x32_bf16 v[122:125], v[138:141], v[182:185], 0
	v_mfma_f32_16x16x32_bf16 v[110:113], v[130:133], v[192:195], 0
	v_mfma_f32_16x16x32_bf16 v[106:109], v[138:141], v[192:195], 0
	v_mfma_f32_16x16x32_bf16 v[94:97], v[130:133], v[200:203], 0
	v_mfma_f32_16x16x32_bf16 v[90:93], v[138:141], v[200:203], 0
	v_mfma_f32_16x16x32_bf16 v[78:81], v[130:133], v[212:215], 0
	v_mfma_f32_16x16x32_bf16 v[74:77], v[138:141], v[212:215], 0
	v_mfma_f32_16x16x32_bf16 v[126:129], v[134:137], v[186:189], v[126:129]
	v_mfma_f32_16x16x32_bf16 v[122:125], v[142:145], v[186:189], v[122:125]
	v_mfma_f32_16x16x32_bf16 v[110:113], v[134:137], v[196:199], v[110:113]
	v_mfma_f32_16x16x32_bf16 v[106:109], v[142:145], v[196:199], v[106:109]
	v_mfma_f32_16x16x32_bf16 v[94:97], v[134:137], v[208:211], v[94:97]
	v_mfma_f32_16x16x32_bf16 v[90:93], v[142:145], v[208:211], v[90:93]
	v_mfma_f32_16x16x32_bf16 v[78:81], v[134:137], v[216:219], v[78:81]
	v_mfma_f32_16x16x32_bf16 v[74:77], v[142:145], v[216:219], v[74:77]
	s_setprio 0
	s_setprio 1
	v_mfma_f32_16x16x32_bf16 v[118:121], v[146:149], v[182:185], 0
	v_mfma_f32_16x16x32_bf16 v[114:117], v[154:157], v[182:185], 0
	v_mfma_f32_16x16x32_bf16 v[102:105], v[146:149], v[192:195], 0
	v_mfma_f32_16x16x32_bf16 v[98:101], v[154:157], v[192:195], 0
	v_mfma_f32_16x16x32_bf16 v[86:89], v[146:149], v[200:203], 0
	v_mfma_f32_16x16x32_bf16 v[82:85], v[154:157], v[200:203], 0
	v_mfma_f32_16x16x32_bf16 v[70:73], v[146:149], v[212:215], 0
	v_mfma_f32_16x16x32_bf16 v[66:69], v[154:157], v[212:215], 0
	v_mfma_f32_16x16x32_bf16 v[118:121], v[150:153], v[186:189], v[118:121]
	v_mfma_f32_16x16x32_bf16 v[114:117], v[158:161], v[186:189], v[114:117]
	v_mfma_f32_16x16x32_bf16 v[102:105], v[150:153], v[196:199], v[102:105]
	v_mfma_f32_16x16x32_bf16 v[98:101], v[158:161], v[196:199], v[98:101]
	v_mfma_f32_16x16x32_bf16 v[86:89], v[150:153], v[208:211], v[86:89]
	v_mfma_f32_16x16x32_bf16 v[82:85], v[158:161], v[208:211], v[82:85]
	v_mfma_f32_16x16x32_bf16 v[70:73], v[150:153], v[216:219], v[70:73]
	v_mfma_f32_16x16x32_bf16 v[66:69], v[158:161], v[216:219], v[66:69]
	s_setprio 0
	s_barrier
	s_add_i32 s6, s66, s55
	v_lshl_add_u64 v[220:221], s[10:11], 0, v[164:165]
	s_mov_b32 m0, s6
	ds_read_b128 v[182:185], v207 offset:16384
	ds_read_b128 v[186:189], v207 offset:17408
	ds_read_b128 v[192:195], v207 offset:18432
	ds_read_b128 v[196:199], v207 offset:19456
	ds_read_b128 v[200:203], v207 offset:20480
	ds_read_b128 v[208:211], v207 offset:21504
	ds_read_b128 v[212:215], v207 offset:22528
	ds_read_b128 v[216:219], v207 offset:23552
	global_load_lds_dwordx4 v[220:221], off
	s_add_i32 m0, s6, 0x2000
	s_add_u32 s6, s10, 0xb0000
	v_lshl_add_u64 v[222:223], s[10:11], 0, v[168:169]
	s_addc_u32 s7, s11, 0
	s_add_i32 s15, s67, s55
	global_load_lds_dwordx4 v[222:223], off
	v_lshl_add_u64 v[224:225], s[6:7], 0, v[164:165]
	s_mov_b32 m0, s15
	v_lshl_add_u64 v[226:227], s[42:43], 0, v[166:167]
	global_load_lds_dwordx4 v[224:225], off
	v_lshl_add_u64 v[224:225], s[6:7], 0, v[168:169]
	s_add_i32 m0, s15, 0x2000
	s_nop 0
	global_load_lds_dwordx4 v[224:225], off
	v_lshl_add_u64 v[224:225], s[42:43], 0, v[162:163]
	s_mov_b32 m0, s56
	s_nop 0
	global_load_lds_dwordx4 v[224:225], off
	s_mov_b32 m0, s57
	s_nop 0
	global_load_lds_dwordx4 v[226:227], off
	s_waitcnt vmcnt(8)
	s_waitcnt lgkmcnt(0)
	s_barrier
; #define PG8_STAGE(bufoff, gbase, voff) do { _Pragma("unroll") for (int _i = 0; _i < 2; ++_i) \
;         __builtin_amdgcn_global_load_lds((const unsigned*)((const char*)(gbase) + (voff)[_i]), (PG8_LAS unsigned*)(lds + (bufoff) + ldsw + _i * 8192), 16, 0, 0); } while (0)
; #define PG8_LDA(dst, b, h) do { _Pragma("unroll") for (int m = 0; m < 4; ++m) _Pragma("unroll") for (int k = 0; k < 2; ++k) dst[m][k] = *(const PG8_LAS bf16x8*)(lds + PG8_SA(b, h) + aoff + m * 2048 + k * 1024); } while (0)
; #define PG8_LDB(dst, b, h) do { _Pragma("unroll") for (int n = 0; n < 2; ++n) _Pragma("unroll") for (int k = 0; k < 2; ++k) dst[n][k] = *(const PG8_LAS bf16x8*)(lds + PG8_SB(b, h) + boff + n * 2048 + k * 1024); } while (0)
; #define PG8_MMA(ai, bj, At, Bt) do { __builtin_amdgcn_s_setprio(1); _Pragma("unroll") for (int m = 0; m < 4; ++m) _Pragma("unroll") for (int n = 0; n < 2; ++n) _Pragma("unroll") for (int k = 0; k < 2; ++k) \
;         acc[ai][bj][m][n] = __builtin_amdgcn_mfma_f32_16x16x32_bf16(Bt[n][k], At[m][k], acc[ai][bj][m][n], 0, 0, 0); __builtin_amdgcn_s_setprio(0); } while (0)
; #define PG8_WAIT_V(n) asm volatile("s_waitcnt vmcnt(" #n ")" ::: "memory")
; #define PG8_WAIT_L(n) asm volatile("s_waitcnt lgkmcnt(" #n ")" ::: "memory")
; #define PG8_BAR __builtin_amdgcn_s_barrier()
; #define PG8_SCHED __builtin_amdgcn_sched_barrier(0)
; template <class Epi, class Sched, bool ALIGN_EPI = false, bool SP2 = false>
; __device__ __forceinline__ void gemm_phase(PG8_LAS unsigned char* lds, const Gemm g, const Sched& S, const Epi& E, const int tid) {
;     ...
;             PG8_WAIT_V(8); PG8_WAIT_L(0); PG8_BAR; PG8_MMA(1, 0, At, B0); PG8_MMA(1, 1, At, B1); PG8_BAR; PG8_SCHED;
;             PG8_LDB(B0, 1, 0); PG8_LDB(B1, 1, 1); PG8_SCHED; PG8_LDA(At, 1, 0); PG8_STAGE(PG8_SA(0, 1), a2 + hstep, voffA);
;             PG8_WAIT_V(8); PG8_WAIT_L(0); PG8_BAR; PG8_MMA(0, 0, At, B0); PG8_MMA(0, 1, At, B1); PG8_BAR; PG8_SCHED;
;             PG8_LDA(At, 1, 1); PG8_STAGE(PG8_SB(1, 0), b3, voffB); PG8_STAGE(PG8_SB(1, 1), b3 + hstep, voffB); PG8_STAGE(PG8_SA(1, 0), a3, voffA);
	s_setprio 1
	s_waitcnt lgkmcnt(0)
	v_mfma_f32_16x16x32_bf16 v[62:65], v[130:133], v[182:185], 0
	v_mfma_f32_16x16x32_bf16 v[58:61], v[138:141], v[182:185], 0
	v_mfma_f32_16x16x32_bf16 v[46:49], v[130:133], v[192:195], 0
	v_mfma_f32_16x16x32_bf16 v[42:45], v[138:141], v[192:195], 0
	v_mfma_f32_16x16x32_bf16 v[30:33], v[130:133], v[200:203], 0
	v_mfma_f32_16x16x32_bf16 v[26:29], v[138:141], v[200:203], 0
	v_mfma_f32_16x16x32_bf16 v[14:17], v[130:133], v[212:215], 0
	v_mfma_f32_16x16x32_bf16 v[10:13], v[138:141], v[212:215], 0
	v_mfma_f32_16x16x32_bf16 v[62:65], v[134:137], v[186:189], v[62:65]
	v_mfma_f32_16x16x32_bf16 v[58:61], v[142:145], v[186:189], v[58:61]
	v_mfma_f32_16x16x32_bf16 v[46:49], v[134:137], v[196:199], v[46:49]
	v_mfma_f32_16x16x32_bf16 v[42:45], v[142:145], v[196:199], v[42:45]
	v_mfma_f32_16x16x32_bf16 v[30:33], v[134:137], v[208:211], v[30:33]
	v_mfma_f32_16x16x32_bf16 v[26:29], v[142:145], v[208:211], v[26:29]
	v_mfma_f32_16x16x32_bf16 v[14:17], v[134:137], v[216:219], v[14:17]
	v_mfma_f32_16x16x32_bf16 v[10:13], v[142:145], v[216:219], v[10:13]
	s_setprio 0
	s_setprio 1
	v_mfma_f32_16x16x32_bf16 v[54:57], v[146:149], v[182:185], 0
	v_mfma_f32_16x16x32_bf16 v[50:53], v[154:157], v[182:185], 0
	v_mfma_f32_16x16x32_bf16 v[38:41], v[146:149], v[192:195], 0
	v_mfma_f32_16x16x32_bf16 v[34:37], v[154:157], v[192:195], 0
	v_mfma_f32_16x16x32_bf16 v[22:25], v[146:149], v[200:203], 0
	v_mfma_f32_16x16x32_bf16 v[18:21], v[154:157], v[200:203], 0
	v_mfma_f32_16x16x32_bf16 v[6:9], v[146:149], v[212:215], 0
	v_mfma_f32_16x16x32_bf16 v[2:5], v[154:157], v[212:215], 0
	v_mfma_f32_16x16x32_bf16 v[54:57], v[150:153], v[186:189], v[54:57]
	v_mfma_f32_16x16x32_bf16 v[50:53], v[158:161], v[186:189], v[50:53]
	v_mfma_f32_16x16x32_bf16 v[38:41], v[150:153], v[196:199], v[38:41]
	v_mfma_f32_16x16x32_bf16 v[34:37], v[158:161], v[196:199], v[34:37]
	v_mfma_f32_16x16x32_bf16 v[22:25], v[150:153], v[208:211], v[22:25]
	v_mfma_f32_16x16x32_bf16 v[18:21], v[158:161], v[208:211], v[18:21]
	v_mfma_f32_16x16x32_bf16 v[6:9], v[150:153], v[216:219], v[6:9]
	v_mfma_f32_16x16x32_bf16 v[2:5], v[158:161], v[216:219], v[2:5]
	s_setprio 0
	s_barrier
	s_add_i32 s15, 0, 0x18000
	s_add_i32 s18, 0, 0x1c000
	v_add_u32_e32 v142, s15, v204
	v_add_u32_e32 v158, s18, v204
	ds_read_b128 v[130:133], v142
	ds_read_b128 v[134:137], v142 offset:1024
	ds_read_b128 v[138:141], v142 offset:2048
	ds_read_b128 v[142:145], v142 offset:3072
	ds_read_b128 v[146:149], v158
	ds_read_b128 v[150:153], v158 offset:1024
	ds_read_b128 v[154:157], v158 offset:2048
	ds_read_b128 v[158:161], v158 offset:3072
	s_add_u32 s6, s42, 0xb0000
	s_addc_u32 s7, s43, 0
	s_mov_b32 m0, s58
	v_lshl_add_u64 v[228:229], s[6:7], 0, v[162:163]
	ds_read_b128 v[182:185], v207 offset:32768
	ds_read_b128 v[186:189], v207 offset:33792
	ds_read_b128 v[192:195], v207 offset:34816
	ds_read_b128 v[196:199], v207 offset:35840
	ds_read_b128 v[200:203], v207 offset:36864
	ds_read_b128 v[208:211], v207 offset:37888
	ds_read_b128 v[212:215], v207 offset:38912
	ds_read_b128 v[216:219], v207 offset:39936
	global_load_lds_dwordx4 v[228:229], off
	v_lshl_add_u64 v[228:229], s[6:7], 0, v[166:167]
	s_mov_b32 m0, s59
	s_nop 0
	global_load_lds_dwordx4 v[228:229], off
	s_waitcnt vmcnt(8)
	s_waitcnt lgkmcnt(0)
	s_barrier
	s_setprio 1
	s_waitcnt lgkmcnt(0)
	v_mfma_f32_16x16x32_bf16 v[126:129], v[130:133], v[182:185], v[126:129]
	v_mfma_f32_16x16x32_bf16 v[122:125], v[138:141], v[182:185], v[122:125]
	v_mfma_f32_16x16x32_bf16 v[110:113], v[130:133], v[192:195], v[110:113]
	v_mfma_f32_16x16x32_bf16 v[106:109], v[138:141], v[192:195], v[106:109]
	v_mfma_f32_16x16x32_bf16 v[94:97], v[130:133], v[200:203], v[94:97]
	v_mfma_f32_16x16x32_bf16 v[90:93], v[138:141], v[200:203], v[90:93]
	v_mfma_f32_16x16x32_bf16 v[78:81], v[130:133], v[212:215], v[78:81]
	v_mfma_f32_16x16x32_bf16 v[74:77], v[138:141], v[212:215], v[74:77]
	v_mfma_f32_16x16x32_bf16 v[126:129], v[134:137], v[186:189], v[126:129]
	v_mfma_f32_16x16x32_bf16 v[122:125], v[142:145], v[186:189], v[122:125]
	v_mfma_f32_16x16x32_bf16 v[110:113], v[134:137], v[196:199], v[110:113]
	v_mfma_f32_16x16x32_bf16 v[106:109], v[142:145], v[196:199], v[106:109]
	v_mfma_f32_16x16x32_bf16 v[94:97], v[134:137], v[208:211], v[94:97]
	v_mfma_f32_16x16x32_bf16 v[90:93], v[142:145], v[208:211], v[90:93]
	v_mfma_f32_16x16x32_bf16 v[78:81], v[134:137], v[216:219], v[78:81]
	v_mfma_f32_16x16x32_bf16 v[74:77], v[142:145], v[216:219], v[74:77]
	s_setprio 0
	s_setprio 1
	v_mfma_f32_16x16x32_bf16 v[118:121], v[146:149], v[182:185], v[118:121]
	v_mfma_f32_16x16x32_bf16 v[114:117], v[154:157], v[182:185], v[114:117]
	v_mfma_f32_16x16x32_bf16 v[102:105], v[146:149], v[192:195], v[102:105]
	v_mfma_f32_16x16x32_bf16 v[98:101], v[154:157], v[192:195], v[98:101]
	v_mfma_f32_16x16x32_bf16 v[86:89], v[146:149], v[200:203], v[86:89]
	v_mfma_f32_16x16x32_bf16 v[82:85], v[154:157], v[200:203], v[82:85]
	v_mfma_f32_16x16x32_bf16 v[70:73], v[146:149], v[212:215], v[70:73]
	v_mfma_f32_16x16x32_bf16 v[66:69], v[154:157], v[212:215], v[66:69]
	v_mfma_f32_16x16x32_bf16 v[118:121], v[150:153], v[186:189], v[118:121]
	v_mfma_f32_16x16x32_bf16 v[114:117], v[158:161], v[186:189], v[114:117]
	v_mfma_f32_16x16x32_bf16 v[102:105], v[150:153], v[196:199], v[102:105]
	v_mfma_f32_16x16x32_bf16 v[98:101], v[158:161], v[196:199], v[98:101]
	v_mfma_f32_16x16x32_bf16 v[86:89], v[150:153], v[208:211], v[86:89]
	v_mfma_f32_16x16x32_bf16 v[82:85], v[158:161], v[208:211], v[82:85]
	v_mfma_f32_16x16x32_bf16 v[70:73], v[150:153], v[216:219], v[70:73]
	v_mfma_f32_16x16x32_bf16 v[66:69], v[158:161], v[216:219], v[66:69]
	s_setprio 0
	s_barrier
; #define PG8_STAGE(bufoff, gbase, voff) do { _Pragma("unroll") for (int _i = 0; _i < 2; ++_i) \
;         __builtin_amdgcn_global_load_lds((const unsigned*)((const char*)(gbase) + (voff)[_i]), (PG8_LAS unsigned*)(lds + (bufoff) + ldsw + _i * 8192), 16, 0, 0); } while (0)
; #define PG8_LDA(dst, b, h) do { _Pragma("unroll") for (int m = 0; m < 4; ++m) _Pragma("unroll") for (int k = 0; k < 2; ++k) dst[m][k] = *(const PG8_LAS bf16x8*)(lds + PG8_SA(b, h) + aoff + m * 2048 + k * 1024); } while (0)
; #define PG8_MMA(ai, bj, At, Bt) do { __builtin_amdgcn_s_setprio(1); _Pragma("unroll") for (int m = 0; m < 4; ++m) _Pragma("unroll") for (int n = 0; n < 2; ++n) _Pragma("unroll") for (int k = 0; k < 2; ++k) \
;         acc[ai][bj][m][n] = __builtin_amdgcn_mfma_f32_16x16x32_bf16(Bt[n][k], At[m][k], acc[ai][bj][m][n], 0, 0, 0); __builtin_amdgcn_s_setprio(0); } while (0)
; #define PG8_WAIT_V(n) asm volatile("s_waitcnt vmcnt(" #n ")" ::: "memory")
; #define PG8_WAIT_L(n) asm volatile("s_waitcnt lgkmcnt(" #n ")" ::: "memory")
; #define PG8_BAR __builtin_amdgcn_s_barrier()
; #define PG8_SCHED __builtin_amdgcn_sched_barrier(0)
; template <class Epi, class Sched, bool ALIGN_EPI = false, bool SP2 = false>
; __device__ __forceinline__ void gemm_phase(PG8_LAS unsigned char* lds, const Gemm g, const Sched& S, const Epi& E, const int tid) {
;     ...
;             PG8_LDA(At, 1, 1); PG8_STAGE(PG8_SB(1, 0), b3, voffB); PG8_STAGE(PG8_SB(1, 1), b3 + hstep, voffB); PG8_STAGE(PG8_SA(1, 0), a3, voffA);
;             PG8_WAIT_V(8); PG8_WAIT_L(0); PG8_BAR; PG8_MMA(1, 0, At, B0); PG8_MMA(1, 1, At, B1); PG8_BAR; PG8_SCHED;
	s_add_i32 s6, s15, s55
	v_lshl_add_u64 v[220:221], v[220:221], 0, s[36:37]
	s_mov_b32 m0, s6
	ds_read_b128 v[182:185], v207 offset:49152
	ds_read_b128 v[186:189], v207 offset:50176
	ds_read_b128 v[192:195], v207 offset:51200
	ds_read_b128 v[196:199], v207 offset:52224
	ds_read_b128 v[200:203], v207 offset:53248
	ds_read_b128 v[208:211], v207 offset:54272
	ds_read_b128 v[212:215], v207 offset:55296
	ds_read_b128 v[216:219], v207 offset:56320
	global_load_lds_dwordx4 v[220:221], off
	s_add_i32 m0, s6, 0x2000
	s_add_u32 s6, s10, 0xb0080
	v_lshl_add_u64 v[220:221], v[222:223], 0, s[36:37]
	s_addc_u32 s7, s11, 0
	s_add_i32 s10, s18, s55
	global_load_lds_dwordx4 v[220:221], off
	v_lshl_add_u64 v[220:221], s[6:7], 0, v[164:165]
	s_mov_b32 m0, s10
	s_nop 0
	global_load_lds_dwordx4 v[220:221], off
	v_lshl_add_u64 v[220:221], s[6:7], 0, v[168:169]
	s_add_i32 m0, s10, 0x2000
	s_nop 0
	global_load_lds_dwordx4 v[220:221], off
	v_lshl_add_u64 v[220:221], v[224:225], 0, s[36:37]
	s_mov_b32 m0, s61
	s_nop 0
	global_load_lds_dwordx4 v[220:221], off
	v_lshl_add_u64 v[220:221], v[226:227], 0, s[36:37]
	s_mov_b32 m0, s62
	s_nop 0
	global_load_lds_dwordx4 v[220:221], off
	s_waitcnt vmcnt(8)
	s_waitcnt lgkmcnt(0)
	s_barrier
	s_setprio 1
	s_waitcnt lgkmcnt(0)
	v_mfma_f32_16x16x32_bf16 v[62:65], v[130:133], v[182:185], v[62:65]
	v_mfma_f32_16x16x32_bf16 v[58:61], v[138:141], v[182:185], v[58:61]
	v_mfma_f32_16x16x32_bf16 v[46:49], v[130:133], v[192:195], v[46:49]
	v_mfma_f32_16x16x32_bf16 v[42:45], v[138:141], v[192:195], v[42:45]
	v_mfma_f32_16x16x32_bf16 v[30:33], v[130:133], v[200:203], v[30:33]
	v_mfma_f32_16x16x32_bf16 v[26:29], v[138:141], v[200:203], v[26:29]
	v_mfma_f32_16x16x32_bf16 v[14:17], v[130:133], v[212:215], v[14:17]
	v_mfma_f32_16x16x32_bf16 v[10:13], v[138:141], v[212:215], v[10:13]
	v_mfma_f32_16x16x32_bf16 v[62:65], v[134:137], v[186:189], v[62:65]
	v_mfma_f32_16x16x32_bf16 v[58:61], v[142:145], v[186:189], v[58:61]
	v_mfma_f32_16x16x32_bf16 v[46:49], v[134:137], v[196:199], v[46:49]
	v_mfma_f32_16x16x32_bf16 v[42:45], v[142:145], v[196:199], v[42:45]
	v_mfma_f32_16x16x32_bf16 v[30:33], v[134:137], v[208:211], v[30:33]
	v_mfma_f32_16x16x32_bf16 v[26:29], v[142:145], v[208:211], v[26:29]
	v_mfma_f32_16x16x32_bf16 v[14:17], v[134:137], v[216:219], v[14:17]
	v_mfma_f32_16x16x32_bf16 v[10:13], v[142:145], v[216:219], v[10:13]
	s_setprio 0
	s_setprio 1
	v_mfma_f32_16x16x32_bf16 v[54:57], v[146:149], v[182:185], v[54:57]
	v_mfma_f32_16x16x32_bf16 v[50:53], v[154:157], v[182:185], v[50:53]
	v_mfma_f32_16x16x32_bf16 v[38:41], v[146:149], v[192:195], v[38:41]
	v_mfma_f32_16x16x32_bf16 v[34:37], v[154:157], v[192:195], v[34:37]
	v_mfma_f32_16x16x32_bf16 v[22:25], v[146:149], v[200:203], v[22:25]
	v_mfma_f32_16x16x32_bf16 v[18:21], v[154:157], v[200:203], v[18:21]
	v_mfma_f32_16x16x32_bf16 v[6:9], v[146:149], v[212:215], v[6:9]
	v_mfma_f32_16x16x32_bf16 v[2:5], v[154:157], v[212:215], v[2:5]
	v_mfma_f32_16x16x32_bf16 v[54:57], v[150:153], v[186:189], v[54:57]
	v_mfma_f32_16x16x32_bf16 v[50:53], v[158:161], v[186:189], v[50:53]
	v_mfma_f32_16x16x32_bf16 v[38:41], v[150:153], v[196:199], v[38:41]
	v_mfma_f32_16x16x32_bf16 v[34:37], v[158:161], v[196:199], v[34:37]
	v_mfma_f32_16x16x32_bf16 v[22:25], v[150:153], v[208:211], v[22:25]
	v_mfma_f32_16x16x32_bf16 v[18:21], v[158:161], v[208:211], v[18:21]
	v_mfma_f32_16x16x32_bf16 v[6:9], v[150:153], v[216:219], v[6:9]
	v_mfma_f32_16x16x32_bf16 v[2:5], v[158:161], v[216:219], v[2:5]
	s_setprio 0
	s_barrier
	s_add_i32 s77, s77, 2
	s_add_u32 s45, s45, 0x100
	s_addc_u32 s47, s47, 0
	s_mov_b64 s[6:7], s[8:9]

; #define PG8_BAR __builtin_amdgcn_s_barrier()
; template <class Epi, class Sched, bool ALIGN_EPI = false, bool SP2 = false>
; __device__ __forceinline__ void gemm_phase(PG8_LAS unsigned char* lds, const Gemm g, const Sched& S, const Epi& E, const int tid) {
;     ...
;         if constexpr (ALIGN_EPI) { if (wr == 0) PG8_BAR; }
;         if constexpr (!Epi::AFTER_DRAIN) { E(acc, cur, wr, wc, fr, fq); S.done(cur); }
;         if (!has_next) break;
; #pragma unroll
;         for (int a = 0; a < 2; ++a)
; #pragma unroll
;             for (int b = 0; b < 2; ++b)
; #pragma unroll
;                 for (int m = 0; m < 4; ++m)
; #pragma unroll
;                     for (int n = 0; n < 2; ++n) acc[a][b][m][n] = (f32x4){0.f, 0.f, 0.f, 0.f};
;         cur = nxt; cA = nA; cB = nB; ++ui;
;         if constexpr (ALIGN_EPI) { if (wr == 1) PG8_BAR; }
.LBB0_506:
	s_or_b64 exec, exec, s[6:7]
	s_and_b64 vcc, exec, s[4:5]
	s_mov_b64 s[4:5], -1
	s_cbranch_vccnz .LBB0_415
	s_andn2_b64 vcc, exec, s[28:29]
	s_cbranch_vccnz .LBB0_414
	s_mov_b32 s101, 1
	s_branch .LBB0_414

;     __device__ __forceinline__ bool next(int i, pg8::Unit& u) const { if (!base.next(i >> 2, u)) return false; u.sub = i & 3; return true; }
;     __host__ __device__ bool next(int i, Unit& u) const {
;         const long L = (long)i * G + c; if (L >= nwg) return false;
;         int wgid = (int)L; { const int q = nwg / NXCD, r = nwg % NXCD, xcd = wgid % NXCD, off = wgid / NXCD; wgid = (xcd < r ? xcd * (q + 1) : r * (q + 1) + (xcd - r) * q) + off; }
;         const int nig = WGM * nN, gid = wgid / nig, fm = gid * WGM, gsz = (nM - fm) < WGM ? (nM - fm) : WGM;
;         u.pm = fm + ((wgid % nig) % gsz); u.pn = (wgid % nig) / gsz; u.sub = 0; return true;
; template <class Epi, class Sched, bool ALIGN_EPI = false, bool SP2 = false>
; __device__ __forceinline__ void gemm_phase(PG8_LAS unsigned char* lds, const Gemm g, const Sched& S, const Epi& E, const int tid) {
;     ...
;     Unit cur, nxt; int ui = 0;
;     if (!S.next(0, cur)) return;
.LBB0_714:
	s_mov_b32 s101, 0
	s_add_i32 s0, 0, 0x204b0
	v_mov_b32_e32 v10, v190
	s_mov_b32 s44, s14
	s_mov_b32 s45, s16
	v_mov_b32_e32 v1, s0
	s_add_i32 s0, 0, 0x20458
	ds_read_b64 v[2:3], v1
	v_mov_b32_e32 v1, s0
	s_add_i32 s0, 0, 0x20460
	ds_read_b64 v[4:5], v1
	v_mov_b32_e32 v1, s0
	ds_read_b64 v[6:7], v1
	s_cmpk_lt_i32 s44, 0xda4
	s_waitcnt lgkmcnt(0)
	v_readfirstlane_b32 s1, v3
	v_readfirstlane_b32 s0, v2
	v_readfirstlane_b32 s46, v5
	v_readfirstlane_b32 s47, v4
	v_readfirstlane_b32 s48, v7
	v_readfirstlane_b32 s49, v6
	s_cselect_b64 s[2:3], -1, 0
	s_cmpk_gt_i32 s44, 0xda3
	v_readfirstlane_b32 s15, v10
	s_cbranch_scc1 .LBB0_720
	s_ashr_i32 s4, s44, 31
	s_lshr_b32 s4, s4, 29
	s_add_i32 s7, s44, s4
	s_and_b32 s4, s7, -8
	s_sub_i32 s6, s44, s4
	s_cmp_gt_i32 s6, 3
	s_cbranch_scc0 .LBB0_717
	s_mul_i32 s4, s6, 0x1b4
	s_add_i32 s8, s4, 4
	s_ashr_i32 s4, s7, 3
	s_cbranch_execz .LBB0_718
	s_branch .LBB0_719

; #define PG8_STAGE(bufoff, gbase, voff) do { _Pragma("unroll") for (int _i = 0; _i < 2; ++_i) \
;         __builtin_amdgcn_global_load_lds((const unsigned*)((const char*)(gbase) + (voff)[_i]), (PG8_LAS unsigned*)(lds + (bufoff) + ldsw + _i * 8192), 16, 0, 0); } while (0)
; #define PG8_LDA(dst, b, h) do { _Pragma("unroll") for (int m = 0; m < 4; ++m) _Pragma("unroll") for (int k = 0; k < 2; ++k) dst[m][k] = *(const PG8_LAS bf16x8*)(lds + PG8_SA(b, h) + aoff + m * 2048 + k * 1024); } while (0)
; #define PG8_LDB(dst, b, h) do { _Pragma("unroll") for (int n = 0; n < 2; ++n) _Pragma("unroll") for (int k = 0; k < 2; ++k) dst[n][k] = *(const PG8_LAS bf16x8*)(lds + PG8_SB(b, h) + boff + n * 2048 + k * 1024); } while (0)
; #define PG8_MMA(ai, bj, At, Bt) do { __builtin_amdgcn_s_setprio(1); _Pragma("unroll") for (int m = 0; m < 4; ++m) _Pragma("unroll") for (int n = 0; n < 2; ++n) _Pragma("unroll") for (int k = 0; k < 2; ++k) \
;         acc[ai][bj][m][n] = __builtin_amdgcn_mfma_f32_16x16x32_bf16(Bt[n][k], At[m][k], acc[ai][bj][m][n], 0, 0, 0); __builtin_amdgcn_s_setprio(0); } while (0)
; #define PG8_WAIT_V(n) asm volatile("s_waitcnt vmcnt(" #n ")" ::: "memory")
; #define PG8_WAIT_L(n) asm volatile("s_waitcnt lgkmcnt(" #n ")" ::: "memory")
; template <class Epi, class Sched, bool ALIGN_EPI = false, bool SP2 = false>
; __device__ __forceinline__ void gemm_phase(PG8_LAS unsigned char* lds, const Gemm g, const Sched& S, const Epi& E, const int tid) {
;     ...
;             const bool last = (t == nt - 2);
;             const char* a1 = cA + (size_t)(t + 1) * kstep;
;             const char* a2 = last ? nA : cA + (size_t)(t + 2) * kstep; const char* b2 = last ? nB : cB + (size_t)(t + 2) * kstep;
;             const char* a3 = a2 + kstep; const char* b3 = b2 + kstep;
;             if (last && has_next) S.a_ready(nxt);
;             if constexpr (SP2) {
;             PG8_LDB(B0, 0, 0); PG8_LDB(B1, 0, 1); PG8_SCHED; PG8_LDA(At, 0, 0); PG8_STAGE(PG8_SA(1, 1), a1 + hstep, voffA);
;             PG8_WAIT_V(8); PG8_WAIT_L(0); PG8_BAR; PG8_MMA(0, 0, At, B0); PG8_MMA(0, 1, At, B1); PG8_BAR; PG8_SCHED;
;             PG8_LDA(At, 0, 1); PG8_STAGE(PG8_SB(0, 0), b2, voffB); PG8_STAGE(PG8_SB(0, 1), b2 + hstep, voffB); PG8_STAGE(PG8_SA(0, 0), a2, voffA);
;             PG8_WAIT_V(8); PG8_WAIT_L(0); PG8_BAR; PG8_MMA(1, 0, At, B0); PG8_MMA(1, 1, At, B1); PG8_BAR; PG8_SCHED;
.LBB0_732:
	s_ashr_i32 s29, s28, 31
	s_lshl_b64 s[18:19], s[28:29], 19
	s_add_u32 s30, s50, s18
	s_addc_u32 s31, s51, s19
	s_and_b64 s[18:19], s[2:3], exec
	s_cselect_b32 s29, s31, s41
	s_cselect_b32 s37, s30, s40
	s_ashr_i32 s27, s26, 31
	s_lshl_b64 s[18:19], s[26:27], 19
	s_add_u32 s34, s52, s18
	s_addc_u32 s35, s53, s19
	s_and_b64 s[18:19], s[2:3], exec
	s_cselect_b32 s27, s35, s39
	s_cselect_b32 s79, s34, s38
	s_add_u32 s80, s38, 0x100
	s_addc_u32 s81, s39, 0
	s_add_u32 s38, s40, 0x40080
	s_addc_u32 s39, s41, 0
	s_mov_b32 s82, -2
	s_cmp_eq_u32 s101, 0
	s_cbranch_scc1 .Lnobar2
	s_barrier
.Lnobar2:
	ds_read_b128 v[130:133], v191
	ds_read_b128 v[134:137], v191 offset:1024
	ds_read_b128 v[138:141], v191 offset:2048
	ds_read_b128 v[142:145], v191 offset:3072
	ds_read_b128 v[146:149], v193
	ds_read_b128 v[150:153], v193 offset:1024
	ds_read_b128 v[154:157], v193 offset:2048
	ds_read_b128 v[158:161], v193 offset:3072
	s_add_u32 s15, s38, 0xfffc0080
	s_addc_u32 s18, s39, -1
	s_cmp_eq_u32 s82, 12
	s_cselect_b32 s43, s29, s18
	s_cselect_b32 s42, s37, s15
	s_cselect_b32 s41, s27, s81
	s_cselect_b32 s40, s79, s80
	v_lshl_add_u64 v[194:195], s[38:39], 0, v[180:181]
	s_add_i32 m0, s55, 0xc000
	ds_read_b128 v[186:189], v197
	ds_read_b128 v[198:201], v197 offset:1024
	ds_read_b128 v[206:209], v197 offset:2048
	ds_read_b128 v[212:215], v197 offset:3072
	ds_read_b128 v[216:219], v197 offset:4096
	ds_read_b128 v[220:223], v197 offset:5120
	ds_read_b128 v[224:227], v197 offset:6144
	ds_read_b128 v[228:231], v197 offset:7168
	global_load_lds_dwordx4 v[194:195], off
	v_lshl_add_u64 v[194:195], s[38:39], 0, v[178:179]
	s_add_i32 m0, s55, 0xe000
	s_nop 0
	global_load_lds_dwordx4 v[194:195], off
	s_waitcnt vmcnt(8)
	s_waitcnt lgkmcnt(0)
	s_barrier
	s_setprio 1
	s_waitcnt lgkmcnt(0)
	v_mfma_f32_16x16x32_bf16 v[126:129], v[130:133], v[186:189], 0
	v_mfma_f32_16x16x32_bf16 v[122:125], v[138:141], v[186:189], 0
	v_mfma_f32_16x16x32_bf16 v[110:113], v[130:133], v[206:209], 0
	v_mfma_f32_16x16x32_bf16 v[106:109], v[138:141], v[206:209], 0
	v_mfma_f32_16x16x32_bf16 v[94:97], v[130:133], v[216:219], 0
	v_mfma_f32_16x16x32_bf16 v[90:93], v[138:141], v[216:219], 0
	v_mfma_f32_16x16x32_bf16 v[78:81], v[130:133], v[224:227], 0
	v_mfma_f32_16x16x32_bf16 v[74:77], v[138:141], v[224:227], 0
	v_mfma_f32_16x16x32_bf16 v[126:129], v[134:137], v[198:201], v[126:129]
	v_mfma_f32_16x16x32_bf16 v[122:125], v[142:145], v[198:201], v[122:125]
	v_mfma_f32_16x16x32_bf16 v[110:113], v[134:137], v[212:215], v[110:113]
	v_mfma_f32_16x16x32_bf16 v[106:109], v[142:145], v[212:215], v[106:109]
	v_mfma_f32_16x16x32_bf16 v[94:97], v[134:137], v[220:223], v[94:97]
	v_mfma_f32_16x16x32_bf16 v[90:93], v[142:145], v[220:223], v[90:93]
	v_mfma_f32_16x16x32_bf16 v[78:81], v[134:137], v[228:231], v[78:81]
	v_mfma_f32_16x16x32_bf16 v[74:77], v[142:145], v[228:231], v[74:77]
	s_setprio 0
	s_setprio 1
	v_mfma_f32_16x16x32_bf16 v[118:121], v[146:149], v[186:189], 0
	v_mfma_f32_16x16x32_bf16 v[114:117], v[154:157], v[186:189], 0
	v_mfma_f32_16x16x32_bf16 v[102:105], v[146:149], v[206:209], 0
	v_mfma_f32_16x16x32_bf16 v[98:101], v[154:157], v[206:209], 0
	v_mfma_f32_16x16x32_bf16 v[86:89], v[146:149], v[216:219], 0
	v_mfma_f32_16x16x32_bf16 v[82:85], v[154:157], v[216:219], 0
	v_mfma_f32_16x16x32_bf16 v[70:73], v[146:149], v[224:227], 0
	v_mfma_f32_16x16x32_bf16 v[66:69], v[154:157], v[224:227], 0
	v_mfma_f32_16x16x32_bf16 v[118:121], v[150:153], v[198:201], v[118:121]
	v_mfma_f32_16x16x32_bf16 v[114:117], v[158:161], v[198:201], v[114:117]
	v_mfma_f32_16x16x32_bf16 v[102:105], v[150:153], v[212:215], v[102:105]
	v_mfma_f32_16x16x32_bf16 v[98:101], v[158:161], v[212:215], v[98:101]
	v_mfma_f32_16x16x32_bf16 v[86:89], v[150:153], v[220:223], v[86:89]
	v_mfma_f32_16x16x32_bf16 v[82:85], v[158:161], v[220:223], v[82:85]
	v_mfma_f32_16x16x32_bf16 v[70:73], v[150:153], v[228:231], v[70:73]
	v_mfma_f32_16x16x32_bf16 v[66:69], v[158:161], v[228:231], v[66:69]
	s_setprio 0
	s_barrier
	s_add_i32 s15, s66, s54
	v_lshl_add_u64 v[194:195], s[40:41], 0, v[164:165]
	s_mov_b32 m0, s15
	ds_read_b128 v[186:189], v197 offset:16384
	ds_read_b128 v[198:201], v197 offset:17408
	ds_read_b128 v[206:209], v197 offset:18432
	ds_read_b128 v[212:215], v197 offset:19456
	ds_read_b128 v[216:219], v197 offset:20480
	ds_read_b128 v[220:223], v197 offset:21504
	ds_read_b128 v[224:227], v197 offset:22528
	ds_read_b128 v[228:231], v197 offset:23552
	global_load_lds_dwordx4 v[194:195], off
	s_add_i32 m0, s15, 0x2000
	s_add_u32 s18, s40, 0x40000
	v_lshl_add_u64 v[232:233], s[40:41], 0, v[168:169]
	s_addc_u32 s19, s41, 0
	s_add_i32 s15, s67, s54
	global_load_lds_dwordx4 v[232:233], off
	v_lshl_add_u64 v[234:235], s[18:19], 0, v[164:165]
	s_mov_b32 m0, s15
	v_lshl_add_u64 v[236:237], s[42:43], 0, v[166:167]
	global_load_lds_dwordx4 v[234:235], off
	v_lshl_add_u64 v[234:235], s[18:19], 0, v[168:169]
	s_add_i32 m0, s15, 0x2000
	s_nop 0
	global_load_lds_dwordx4 v[234:235], off
	v_lshl_add_u64 v[234:235], s[42:43], 0, v[162:163]
	s_mov_b32 m0, s55
	s_nop 0
	global_load_lds_dwordx4 v[234:235], off
	s_mov_b32 m0, s56
	s_nop 0
	global_load_lds_dwordx4 v[236:237], off
	s_waitcnt vmcnt(8)
	s_waitcnt lgkmcnt(0)
	s_barrier
; #define PG8_STAGE(bufoff, gbase, voff) do { _Pragma("unroll") for (int _i = 0; _i < 2; ++_i) \
;         __builtin_amdgcn_global_load_lds((const unsigned*)((const char*)(gbase) + (voff)[_i]), (PG8_LAS unsigned*)(lds + (bufoff) + ldsw + _i * 8192), 16, 0, 0); } while (0)
; #define PG8_LDA(dst, b, h) do { _Pragma("unroll") for (int m = 0; m < 4; ++m) _Pragma("unroll") for (int k = 0; k < 2; ++k) dst[m][k] = *(const PG8_LAS bf16x8*)(lds + PG8_SA(b, h) + aoff + m * 2048 + k * 1024); } while (0)
; #define PG8_LDB(dst, b, h) do { _Pragma("unroll") for (int n = 0; n < 2; ++n) _Pragma("unroll") for (int k = 0; k < 2; ++k) dst[n][k] = *(const PG8_LAS bf16x8*)(lds + PG8_SB(b, h) + boff + n * 2048 + k * 1024); } while (0)
; #define PG8_MMA(ai, bj, At, Bt) do { __builtin_amdgcn_s_setprio(1); _Pragma("unroll") for (int m = 0; m < 4; ++m) _Pragma("unroll") for (int n = 0; n < 2; ++n) _Pragma("unroll") for (int k = 0; k < 2; ++k) \
;         acc[ai][bj][m][n] = __builtin_amdgcn_mfma_f32_16x16x32_bf16(Bt[n][k], At[m][k], acc[ai][bj][m][n], 0, 0, 0); __builtin_amdgcn_s_setprio(0); } while (0)
; #define PG8_WAIT_V(n) asm volatile("s_waitcnt vmcnt(" #n ")" ::: "memory")
; #define PG8_WAIT_L(n) asm volatile("s_waitcnt lgkmcnt(" #n ")" ::: "memory")
; #define PG8_BAR __builtin_amdgcn_s_barrier()
; #define PG8_SCHED __builtin_amdgcn_sched_barrier(0)
; template <class Epi, class Sched, bool ALIGN_EPI = false, bool SP2 = false>
; __device__ __forceinline__ void gemm_phase(PG8_LAS unsigned char* lds, const Gemm g, const Sched& S, const Epi& E, const int tid) {
;     ...
;             PG8_WAIT_V(8); PG8_WAIT_L(0); PG8_BAR; PG8_MMA(1, 0, At, B0); PG8_MMA(1, 1, At, B1); PG8_BAR; PG8_SCHED;
;             PG8_LDB(B0, 1, 0); PG8_LDB(B1, 1, 1); PG8_SCHED; PG8_LDA(At, 1, 0); PG8_STAGE(PG8_SA(0, 1), a2 + hstep, voffA);
;             PG8_WAIT_V(8); PG8_WAIT_L(0); PG8_BAR; PG8_MMA(0, 0, At, B0); PG8_MMA(0, 1, At, B1); PG8_BAR; PG8_SCHED;
	s_setprio 1
	s_waitcnt lgkmcnt(0)
	v_mfma_f32_16x16x32_bf16 v[62:65], v[130:133], v[186:189], 0
	v_mfma_f32_16x16x32_bf16 v[58:61], v[138:141], v[186:189], 0
	v_mfma_f32_16x16x32_bf16 v[46:49], v[130:133], v[206:209], 0
	v_mfma_f32_16x16x32_bf16 v[42:45], v[138:141], v[206:209], 0
	v_mfma_f32_16x16x32_bf16 v[30:33], v[130:133], v[216:219], 0
	v_mfma_f32_16x16x32_bf16 v[26:29], v[138:141], v[216:219], 0
	v_mfma_f32_16x16x32_bf16 v[14:17], v[130:133], v[224:227], 0
	v_mfma_f32_16x16x32_bf16 v[10:13], v[138:141], v[224:227], 0
	v_mfma_f32_16x16x32_bf16 v[62:65], v[134:137], v[198:201], v[62:65]
	v_mfma_f32_16x16x32_bf16 v[58:61], v[142:145], v[198:201], v[58:61]
	v_mfma_f32_16x16x32_bf16 v[46:49], v[134:137], v[212:215], v[46:49]
	v_mfma_f32_16x16x32_bf16 v[42:45], v[142:145], v[212:215], v[42:45]
	v_mfma_f32_16x16x32_bf16 v[30:33], v[134:137], v[220:223], v[30:33]
	v_mfma_f32_16x16x32_bf16 v[26:29], v[142:145], v[220:223], v[26:29]
	v_mfma_f32_16x16x32_bf16 v[14:17], v[134:137], v[228:231], v[14:17]
	v_mfma_f32_16x16x32_bf16 v[10:13], v[142:145], v[228:231], v[10:13]
	s_setprio 0
	s_setprio 1
	v_mfma_f32_16x16x32_bf16 v[54:57], v[146:149], v[186:189], 0
	v_mfma_f32_16x16x32_bf16 v[50:53], v[154:157], v[186:189], 0
	v_mfma_f32_16x16x32_bf16 v[38:41], v[146:149], v[206:209], 0
	v_mfma_f32_16x16x32_bf16 v[34:37], v[154:157], v[206:209], 0
	v_mfma_f32_16x16x32_bf16 v[22:25], v[146:149], v[216:219], 0
	v_mfma_f32_16x16x32_bf16 v[18:21], v[154:157], v[216:219], 0
	v_mfma_f32_16x16x32_bf16 v[6:9], v[146:149], v[224:227], 0
	v_mfma_f32_16x16x32_bf16 v[2:5], v[154:157], v[224:227], 0
	v_mfma_f32_16x16x32_bf16 v[54:57], v[150:153], v[198:201], v[54:57]
	v_mfma_f32_16x16x32_bf16 v[50:53], v[158:161], v[198:201], v[50:53]
	v_mfma_f32_16x16x32_bf16 v[38:41], v[150:153], v[212:215], v[38:41]
	v_mfma_f32_16x16x32_bf16 v[34:37], v[158:161], v[212:215], v[34:37]
	v_mfma_f32_16x16x32_bf16 v[22:25], v[150:153], v[220:223], v[22:25]
	v_mfma_f32_16x16x32_bf16 v[18:21], v[158:161], v[220:223], v[18:21]
	v_mfma_f32_16x16x32_bf16 v[6:9], v[150:153], v[228:231], v[6:9]
	v_mfma_f32_16x16x32_bf16 v[2:5], v[158:161], v[228:231], v[2:5]
	s_setprio 0
	s_barrier
	s_add_i32 s15, 0, 0x18000
	s_add_i32 s83, 0, 0x1c000
	v_add_u32_e32 v142, s15, v173
	v_add_u32_e32 v158, s83, v173
	ds_read_b128 v[130:133], v142
	ds_read_b128 v[134:137], v142 offset:1024
	ds_read_b128 v[138:141], v142 offset:2048
	ds_read_b128 v[142:145], v142 offset:3072
	ds_read_b128 v[146:149], v158
	ds_read_b128 v[150:153], v158 offset:1024
	ds_read_b128 v[154:157], v158 offset:2048
	ds_read_b128 v[158:161], v158 offset:3072
	s_add_u32 s18, s42, 0x40000
	s_addc_u32 s19, s43, 0
	s_mov_b32 m0, s57
	v_lshl_add_u64 v[238:239], s[18:19], 0, v[162:163]
	ds_read_b128 v[186:189], v197 offset:32768
	ds_read_b128 v[198:201], v197 offset:33792
	ds_read_b128 v[206:209], v197 offset:34816
	ds_read_b128 v[212:215], v197 offset:35840
	ds_read_b128 v[216:219], v197 offset:36864
	ds_read_b128 v[220:223], v197 offset:37888
	ds_read_b128 v[224:227], v197 offset:38912
	ds_read_b128 v[228:231], v197 offset:39936
	global_load_lds_dwordx4 v[238:239], off
	v_lshl_add_u64 v[238:239], s[18:19], 0, v[166:167]
	s_mov_b32 m0, s58
	s_nop 0
	global_load_lds_dwordx4 v[238:239], off
	s_waitcnt vmcnt(8)
	s_waitcnt lgkmcnt(0)
	s_barrier
	s_setprio 1
	s_waitcnt lgkmcnt(0)
	v_mfma_f32_16x16x32_bf16 v[126:129], v[130:133], v[186:189], v[126:129]
	v_mfma_f32_16x16x32_bf16 v[122:125], v[138:141], v[186:189], v[122:125]
	v_mfma_f32_16x16x32_bf16 v[110:113], v[130:133], v[206:209], v[110:113]
	v_mfma_f32_16x16x32_bf16 v[106:109], v[138:141], v[206:209], v[106:109]
	v_mfma_f32_16x16x32_bf16 v[94:97], v[130:133], v[216:219], v[94:97]
	v_mfma_f32_16x16x32_bf16 v[90:93], v[138:141], v[216:219], v[90:93]
	v_mfma_f32_16x16x32_bf16 v[78:81], v[130:133], v[224:227], v[78:81]
	v_mfma_f32_16x16x32_bf16 v[74:77], v[138:141], v[224:227], v[74:77]
	v_mfma_f32_16x16x32_bf16 v[126:129], v[134:137], v[198:201], v[126:129]
	v_mfma_f32_16x16x32_bf16 v[122:125], v[142:145], v[198:201], v[122:125]
	v_mfma_f32_16x16x32_bf16 v[110:113], v[134:137], v[212:215], v[110:113]
	v_mfma_f32_16x16x32_bf16 v[106:109], v[142:145], v[212:215], v[106:109]
	v_mfma_f32_16x16x32_bf16 v[94:97], v[134:137], v[220:223], v[94:97]
	v_mfma_f32_16x16x32_bf16 v[90:93], v[142:145], v[220:223], v[90:93]
	v_mfma_f32_16x16x32_bf16 v[78:81], v[134:137], v[228:231], v[78:81]
	v_mfma_f32_16x16x32_bf16 v[74:77], v[142:145], v[228:231], v[74:77]
	s_setprio 0
	s_setprio 1
	v_mfma_f32_16x16x32_bf16 v[118:121], v[146:149], v[186:189], v[118:121]
	v_mfma_f32_16x16x32_bf16 v[114:117], v[154:157], v[186:189], v[114:117]
	v_mfma_f32_16x16x32_bf16 v[102:105], v[146:149], v[206:209], v[102:105]
	v_mfma_f32_16x16x32_bf16 v[98:101], v[154:157], v[206:209], v[98:101]
	v_mfma_f32_16x16x32_bf16 v[86:89], v[146:149], v[216:219], v[86:89]
	v_mfma_f32_16x16x32_bf16 v[82:85], v[154:157], v[216:219], v[82:85]
	v_mfma_f32_16x16x32_bf16 v[70:73], v[146:149], v[224:227], v[70:73]
	v_mfma_f32_16x16x32_bf16 v[66:69], v[154:157], v[224:227], v[66:69]
	v_mfma_f32_16x16x32_bf16 v[118:121], v[150:153], v[198:201], v[118:121]
	v_mfma_f32_16x16x32_bf16 v[114:117], v[158:161], v[198:201], v[114:117]
	v_mfma_f32_16x16x32_bf16 v[102:105], v[150:153], v[212:215], v[102:105]
	v_mfma_f32_16x16x32_bf16 v[98:101], v[158:161], v[212:215], v[98:101]
	v_mfma_f32_16x16x32_bf16 v[86:89], v[150:153], v[220:223], v[86:89]
	v_mfma_f32_16x16x32_bf16 v[82:85], v[158:161], v[220:223], v[82:85]
	v_mfma_f32_16x16x32_bf16 v[70:73], v[150:153], v[228:231], v[70:73]
	v_mfma_f32_16x16x32_bf16 v[66:69], v[158:161], v[228:231], v[66:69]
	s_setprio 0
	s_barrier
; #define PG8_STAGE(bufoff, gbase, voff) do { _Pragma("unroll") for (int _i = 0; _i < 2; ++_i) \
;         __builtin_amdgcn_global_load_lds((const unsigned*)((const char*)(gbase) + (voff)[_i]), (PG8_LAS unsigned*)(lds + (bufoff) + ldsw + _i * 8192), 16, 0, 0); } while (0)
; #define PG8_LDA(dst, b, h) do { _Pragma("unroll") for (int m = 0; m < 4; ++m) _Pragma("unroll") for (int k = 0; k < 2; ++k) dst[m][k] = *(const PG8_LAS bf16x8*)(lds + PG8_SA(b, h) + aoff + m * 2048 + k * 1024); } while (0)
; #define PG8_MMA(ai, bj, At, Bt) do { __builtin_amdgcn_s_setprio(1); _Pragma("unroll") for (int m = 0; m < 4; ++m) _Pragma("unroll") for (int n = 0; n < 2; ++n) _Pragma("unroll") for (int k = 0; k < 2; ++k) \
;         acc[ai][bj][m][n] = __builtin_amdgcn_mfma_f32_16x16x32_bf16(Bt[n][k], At[m][k], acc[ai][bj][m][n], 0, 0, 0); __builtin_amdgcn_s_setprio(0); } while (0)
; #define PG8_WAIT_V(n) asm volatile("s_waitcnt vmcnt(" #n ")" ::: "memory")
; #define PG8_WAIT_L(n) asm volatile("s_waitcnt lgkmcnt(" #n ")" ::: "memory")
; #define PG8_BAR __builtin_amdgcn_s_barrier()
; #define PG8_SCHED __builtin_amdgcn_sched_barrier(0)
; template <class Epi, class Sched, bool ALIGN_EPI = false, bool SP2 = false>
; __device__ __forceinline__ void gemm_phase(PG8_LAS unsigned char* lds, const Gemm g, const Sched& S, const Epi& E, const int tid) {
;     ...
;         for (int t = 0; t < nt; t += 2) {
;     ...
;             PG8_LDA(At, 1, 1); PG8_STAGE(PG8_SB(1, 0), b3, voffB); PG8_STAGE(PG8_SB(1, 1), b3 + hstep, voffB); PG8_STAGE(PG8_SA(1, 0), a3, voffA);
;             PG8_WAIT_V(8); PG8_WAIT_L(0); PG8_BAR; PG8_MMA(1, 0, At, B0); PG8_MMA(1, 1, At, B1); PG8_BAR; PG8_SCHED;
	s_add_i32 s15, s15, s54
	v_lshl_add_u64 v[194:195], v[194:195], 0, s[10:11]
	s_mov_b32 m0, s15
	ds_read_b128 v[186:189], v197 offset:49152
	ds_read_b128 v[198:201], v197 offset:50176
	ds_read_b128 v[206:209], v197 offset:51200
	ds_read_b128 v[212:215], v197 offset:52224
	ds_read_b128 v[216:219], v197 offset:53248
	ds_read_b128 v[220:223], v197 offset:54272
	ds_read_b128 v[224:227], v197 offset:55296
	ds_read_b128 v[228:231], v197 offset:56320
	global_load_lds_dwordx4 v[194:195], off
	s_add_i32 m0, s15, 0x2000
	s_add_u32 s18, s40, 0x40080
	v_lshl_add_u64 v[194:195], v[232:233], 0, s[10:11]
	s_addc_u32 s19, s41, 0
	s_add_i32 s15, s83, s54
	global_load_lds_dwordx4 v[194:195], off
	v_lshl_add_u64 v[194:195], s[18:19], 0, v[164:165]
	s_mov_b32 m0, s15
	s_nop 0
	global_load_lds_dwordx4 v[194:195], off
	v_lshl_add_u64 v[194:195], s[18:19], 0, v[168:169]
	s_add_i32 m0, s15, 0x2000
	s_nop 0
	global_load_lds_dwordx4 v[194:195], off
	v_lshl_add_u64 v[194:195], v[234:235], 0, s[10:11]
	s_mov_b32 m0, s61
	s_nop 0
	global_load_lds_dwordx4 v[194:195], off
	v_lshl_add_u64 v[194:195], v[236:237], 0, s[10:11]
	s_mov_b32 m0, s62
	s_nop 0
	global_load_lds_dwordx4 v[194:195], off
	s_waitcnt vmcnt(8)
	s_waitcnt lgkmcnt(0)
	s_barrier
	s_setprio 1
	s_waitcnt lgkmcnt(0)
	v_mfma_f32_16x16x32_bf16 v[62:65], v[130:133], v[186:189], v[62:65]
	v_mfma_f32_16x16x32_bf16 v[58:61], v[138:141], v[186:189], v[58:61]
	v_mfma_f32_16x16x32_bf16 v[46:49], v[130:133], v[206:209], v[46:49]
	v_mfma_f32_16x16x32_bf16 v[42:45], v[138:141], v[206:209], v[42:45]
	v_mfma_f32_16x16x32_bf16 v[30:33], v[130:133], v[216:219], v[30:33]
	v_mfma_f32_16x16x32_bf16 v[26:29], v[138:141], v[216:219], v[26:29]
	v_mfma_f32_16x16x32_bf16 v[14:17], v[130:133], v[224:227], v[14:17]
	v_mfma_f32_16x16x32_bf16 v[10:13], v[138:141], v[224:227], v[10:13]
	v_mfma_f32_16x16x32_bf16 v[62:65], v[134:137], v[198:201], v[62:65]
	v_mfma_f32_16x16x32_bf16 v[58:61], v[142:145], v[198:201], v[58:61]
	v_mfma_f32_16x16x32_bf16 v[46:49], v[134:137], v[212:215], v[46:49]
	v_mfma_f32_16x16x32_bf16 v[42:45], v[142:145], v[212:215], v[42:45]
	v_mfma_f32_16x16x32_bf16 v[30:33], v[134:137], v[220:223], v[30:33]
	v_mfma_f32_16x16x32_bf16 v[26:29], v[142:145], v[220:223], v[26:29]
	v_mfma_f32_16x16x32_bf16 v[14:17], v[134:137], v[228:231], v[14:17]
	v_mfma_f32_16x16x32_bf16 v[10:13], v[142:145], v[228:231], v[10:13]
	s_setprio 0
	s_setprio 1
	v_mfma_f32_16x16x32_bf16 v[54:57], v[146:149], v[186:189], v[54:57]
	v_mfma_f32_16x16x32_bf16 v[50:53], v[154:157], v[186:189], v[50:53]
	v_mfma_f32_16x16x32_bf16 v[38:41], v[146:149], v[206:209], v[38:41]
	v_mfma_f32_16x16x32_bf16 v[34:37], v[154:157], v[206:209], v[34:37]
	v_mfma_f32_16x16x32_bf16 v[22:25], v[146:149], v[216:219], v[22:25]
	v_mfma_f32_16x16x32_bf16 v[18:21], v[154:157], v[216:219], v[18:21]
	v_mfma_f32_16x16x32_bf16 v[6:9], v[146:149], v[224:227], v[6:9]
	v_mfma_f32_16x16x32_bf16 v[2:5], v[154:157], v[224:227], v[2:5]
	v_mfma_f32_16x16x32_bf16 v[54:57], v[150:153], v[198:201], v[54:57]
	v_mfma_f32_16x16x32_bf16 v[50:53], v[158:161], v[198:201], v[50:53]
	v_mfma_f32_16x16x32_bf16 v[38:41], v[150:153], v[212:215], v[38:41]
	v_mfma_f32_16x16x32_bf16 v[34:37], v[158:161], v[212:215], v[34:37]
	v_mfma_f32_16x16x32_bf16 v[22:25], v[150:153], v[220:223], v[22:25]
	v_mfma_f32_16x16x32_bf16 v[18:21], v[158:161], v[220:223], v[18:21]
	v_mfma_f32_16x16x32_bf16 v[6:9], v[150:153], v[228:231], v[6:9]
	v_mfma_f32_16x16x32_bf16 v[2:5], v[158:161], v[228:231], v[2:5]
	s_setprio 0
	s_barrier
	s_add_i32 s82, s82, 2
	s_add_u32 s80, s80, 0x100
	s_addc_u32 s81, s81, 0
	s_add_u32 s38, s38, 0x100
	s_addc_u32 s39, s39, 0

; #define PG8_BAR __builtin_amdgcn_s_barrier()
; template <class Epi, class Sched, bool ALIGN_EPI = false, bool SP2 = false>
; __device__ __forceinline__ void gemm_phase(PG8_LAS unsigned char* lds, const Gemm g, const Sched& S, const Epi& E, const int tid) {
;     ...
;         if (!has_next) break;
; #pragma unroll
;         for (int a = 0; a < 2; ++a)
; #pragma unroll
;             for (int b = 0; b < 2; ++b)
; #pragma unroll
;                 for (int m = 0; m < 4; ++m)
; #pragma unroll
;                     for (int n = 0; n < 2; ++n) acc[a][b][m][n] = (f32x4){0.f, 0.f, 0.f, 0.f};
;         cur = nxt; cA = nA; cB = nB; ++ui;
;         if constexpr (ALIGN_EPI) { if (wr == 1) PG8_BAR; }
;     }
.LBB0_789:
	s_andn2_b64 vcc, exec, s[6:7]
	s_cbranch_vccnz .LBB0_724
	s_mov_b32 s101, 1
	s_branch .LBB0_724

;     __device__ __forceinline__ bool next(int i, pg8::Unit& u) const { if (!base.next(i >> 2, u)) return false; u.sub = i & 3; return true; }
;     __host__ __device__ bool next(int i, Unit& u) const {
;         const long L = (long)i * G + c; if (L >= nwg) return false;
;         int wgid = (int)L; { const int q = nwg / NXCD, r = nwg % NXCD, xcd = wgid % NXCD, off = wgid / NXCD; wgid = (xcd < r ? xcd * (q + 1) : r * (q + 1) + (xcd - r) * q) + off; }
;         const int nig = WGM * nN, gid = wgid / nig, fm = gid * WGM, gsz = (nM - fm) < WGM ? (nM - fm) : WGM;
;         u.pm = fm + ((wgid % nig) % gsz); u.pn = (wgid % nig) / gsz; u.sub = 0; return true;
; template <class Epi, class Sched, bool ALIGN_EPI = false, bool SP2 = false>
; __device__ __forceinline__ void gemm_phase(PG8_LAS unsigned char* lds, const Gemm g, const Sched& S, const Epi& E, const int tid) {
;     ...
;     Unit cur, nxt; int ui = 0;
;     if (!S.next(0, cur)) return;
.LBB0_1085:
	s_mov_b32 s101, 0
	s_add_i32 s0, 0, 0x204b0
	v_mov_b32_e32 v138, v190
	s_mov_b32 s8, s14
	s_mov_b32 s64, s16
	v_mov_b32_e32 v1, s0
	s_waitcnt vmcnt(0)
	ds_read_b64 v[2:3], v1
	s_ashr_i32 s9, s8, 31
	s_cmpk_lt_i32 s8, 0x308
	s_cselect_b64 s[0:1], -1, 0
	s_cmpk_gt_i32 s8, 0x307
	s_waitcnt lgkmcnt(0)
	v_readfirstlane_b32 s7, v3
	v_readfirstlane_b32 s6, v2
	v_readfirstlane_b32 s2, v138
	s_cbranch_scc1 .LBB0_1087
	s_ashr_i32 s3, s8, 31
	s_lshr_b32 s3, s3, 29
	s_add_i32 s3, s8, s3
	s_ashr_i32 s4, s3, 3
	s_and_b32 s3, s3, -8
	s_sub_i32 s3, s8, s3
	s_cmp_lt_i32 s3, 0
	s_movk_i32 s5, 0x62
	s_cselect_b32 s5, s5, 0x61
	s_mul_i32 s3, s5, s3
	s_add_i32 s3, s3, s4
	s_ashr_i32 s4, s3, 31
	s_lshr_b32 s4, s4, 27
	s_add_i32 s4, s3, s4
	s_ashr_i32 s5, s4, 5
	s_lshl_b32 s10, s5, 3
	s_sub_i32 s5, 0xc2, s10
	s_min_u32 s11, s5, 8
	s_andn2_b32 s4, s4, 31
	s_sub_i32 s3, s3, s4
	v_cvt_f32_ubyte0_e32 v2, s11
	v_cvt_f32_i32_e32 v1, s3
	v_rcp_iflag_f32_e32 v3, v2
	s_ashr_i32 s4, s3, 30
	s_or_b32 s15, s4, 1
	v_mul_f32_e32 v3, v1, v3
	v_trunc_f32_e32 v3, v3
	v_fma_f32 v1, -v3, v2, v1
	v_cvt_i32_f32_e32 v3, v3
	v_cmp_ge_f32_e64 s[4:5], |v1|, v2
	s_and_b64 s[4:5], s[4:5], exec
	s_cselect_b32 s4, s15, 0
	v_readfirstlane_b32 s5, v3
	s_add_i32 s5, s5, s4
	s_sext_i32_i8 s4, s5
	s_mul_i32 s5, s5, s11
	s_sub_i32 s3, s3, s5
	s_sext_i32_i8 s3, s3
	s_add_i32 s54, s10, s3

; #define PG8_STAGE(bufoff, gbase, voff) do { _Pragma("unroll") for (int _i = 0; _i < 2; ++_i) \
;         __builtin_amdgcn_global_load_lds((const unsigned*)((const char*)(gbase) + (voff)[_i]), (PG8_LAS unsigned*)(lds + (bufoff) + ldsw + _i * 8192), 16, 0, 0); } while (0)
; #define PG8_LDA(dst, b, h) do { _Pragma("unroll") for (int m = 0; m < 4; ++m) _Pragma("unroll") for (int k = 0; k < 2; ++k) dst[m][k] = *(const PG8_LAS bf16x8*)(lds + PG8_SA(b, h) + aoff + m * 2048 + k * 1024); } while (0)
; #define PG8_LDB(dst, b, h) do { _Pragma("unroll") for (int n = 0; n < 2; ++n) _Pragma("unroll") for (int k = 0; k < 2; ++k) dst[n][k] = *(const PG8_LAS bf16x8*)(lds + PG8_SB(b, h) + boff + n * 2048 + k * 1024); } while (0)
; #define PG8_WAIT_V(n) asm volatile("s_waitcnt vmcnt(" #n ")" ::: "memory")
; #define PG8_WAIT_L(n) asm volatile("s_waitcnt lgkmcnt(" #n ")" ::: "memory")
; #define PG8_BAR __builtin_amdgcn_s_barrier()
; #define PG8_SCHED __builtin_amdgcn_sched_barrier(0)
; template <class Epi, class Sched, bool ALIGN_EPI = false, bool SP2 = false>
; __device__ __forceinline__ void gemm_phase(PG8_LAS unsigned char* lds, const Gemm g, const Sched& S, const Epi& E, const int tid) {
;     ...
;         const bool has_next = S.next(ui + 1, nxt);
;         const char* nA = has_next ? S.aptr(nxt) : cA; const char* nB = has_next ? S.bptr(nxt) : cB;
;         for (int t = 0; t < nt; t += 2) {
;             const bool last = (t == nt - 2);
;             const char* a1 = cA + (size_t)(t + 1) * kstep;
;             const char* a2 = last ? nA : cA + (size_t)(t + 2) * kstep; const char* b2 = last ? nB : cB + (size_t)(t + 2) * kstep;
;             const char* a3 = a2 + kstep; const char* b3 = b2 + kstep;
;             if (last && has_next) S.a_ready(nxt);
;             if constexpr (SP2) {
;             PG8_LDB(B0, 0, 0); PG8_LDB(B1, 0, 1); PG8_SCHED; PG8_LDA(At, 0, 0); PG8_STAGE(PG8_SA(1, 1), a1 + hstep, voffA);
;             PG8_WAIT_V(8); PG8_WAIT_L(0); PG8_BAR; PG8_MMA(0, 0, At, B0); PG8_MMA(0, 1, At, B1); PG8_BAR; PG8_SCHED;
;             PG8_LDA(At, 0, 1); PG8_STAGE(PG8_SB(0, 0), b2, voffB); PG8_STAGE(PG8_SB(0, 1), b2 + hstep, voffB); PG8_STAGE(PG8_SA(0, 0), a2, voffA);
;             PG8_WAIT_V(8); PG8_WAIT_L(0); PG8_BAR; PG8_MMA(1, 0, At, B0); PG8_MMA(1, 1, At, B1); PG8_BAR; PG8_SCHED;
.LBB0_1121:
	s_add_u32 s5, s56, 0x100
	s_addc_u32 s49, s57, 0
	s_add_u32 s56, s58, 0x40080
	s_addc_u32 s57, s59, 0
	s_mov_b32 s51, -2
	s_cmp_eq_u32 s101, 0
	s_cbranch_scc1 .Lnobar3
	s_barrier
.Lnobar3:
	ds_read_b128 v[130:133], v139
	ds_read_b128 v[134:137], v139 offset:1024
	ds_read_b128 v[162:165], v139 offset:2048
	ds_read_b128 v[166:169], v139 offset:3072
	ds_read_b128 v[176:179], v173
	ds_read_b128 v[180:183], v173 offset:1024
	ds_read_b128 v[184:187], v173 offset:2048
	ds_read_b128 v[192:195], v173 offset:3072
	s_add_u32 s15, s56, 0xfffc0080
	s_addc_u32 s18, s57, -1
	s_cmp_eq_u32 s51, 12
	s_cselect_b32 s61, s1, s18
	s_cselect_b32 s60, s0, s15
	s_cselect_b32 s59, s53, s49
	s_cselect_b32 s58, s52, s5
	v_lshl_add_u64 v[170:171], s[56:57], 0, v[156:157]
	s_add_i32 m0, s67, 0xc000
	ds_read_b128 v[196:199], v174
	ds_read_b128 v[200:203], v174 offset:1024
	ds_read_b128 v[204:207], v174 offset:2048
	ds_read_b128 v[208:211], v174 offset:3072
	ds_read_b128 v[212:215], v174 offset:4096
	ds_read_b128 v[216:219], v174 offset:5120
	ds_read_b128 v[220:223], v174 offset:6144
	ds_read_b128 v[224:227], v174 offset:7168
	global_load_lds_dwordx4 v[170:171], off
	v_lshl_add_u64 v[170:171], s[56:57], 0, v[154:155]
	s_add_i32 m0, s67, 0xe000
	s_nop 0
	global_load_lds_dwordx4 v[170:171], off
	s_waitcnt vmcnt(8)
	s_waitcnt lgkmcnt(0)
	s_barrier
	s_setprio 1
	s_waitcnt lgkmcnt(0)
	v_mfma_f32_16x16x32_bf16 v[126:129], v[130:133], v[196:199], 0
	v_mfma_f32_16x16x32_bf16 v[122:125], v[162:165], v[196:199], 0
	v_mfma_f32_16x16x32_bf16 v[110:113], v[130:133], v[204:207], 0
	v_mfma_f32_16x16x32_bf16 v[106:109], v[162:165], v[204:207], 0
	v_mfma_f32_16x16x32_bf16 v[94:97], v[130:133], v[212:215], 0
	v_mfma_f32_16x16x32_bf16 v[90:93], v[162:165], v[212:215], 0
	v_mfma_f32_16x16x32_bf16 v[78:81], v[130:133], v[220:223], 0
	v_mfma_f32_16x16x32_bf16 v[74:77], v[162:165], v[220:223], 0
	v_mfma_f32_16x16x32_bf16 v[126:129], v[134:137], v[200:203], v[126:129]
	v_mfma_f32_16x16x32_bf16 v[122:125], v[166:169], v[200:203], v[122:125]
	v_mfma_f32_16x16x32_bf16 v[110:113], v[134:137], v[208:211], v[110:113]
	v_mfma_f32_16x16x32_bf16 v[106:109], v[166:169], v[208:211], v[106:109]
	v_mfma_f32_16x16x32_bf16 v[94:97], v[134:137], v[216:219], v[94:97]
	v_mfma_f32_16x16x32_bf16 v[90:93], v[166:169], v[216:219], v[90:93]
	v_mfma_f32_16x16x32_bf16 v[78:81], v[134:137], v[224:227], v[78:81]
	v_mfma_f32_16x16x32_bf16 v[74:77], v[166:169], v[224:227], v[74:77]
	s_setprio 0
	s_setprio 1
	v_mfma_f32_16x16x32_bf16 v[118:121], v[176:179], v[196:199], 0
	v_mfma_f32_16x16x32_bf16 v[114:117], v[184:187], v[196:199], 0
	v_mfma_f32_16x16x32_bf16 v[102:105], v[176:179], v[204:207], 0
	v_mfma_f32_16x16x32_bf16 v[98:101], v[184:187], v[204:207], 0
	v_mfma_f32_16x16x32_bf16 v[86:89], v[176:179], v[212:215], 0
	v_mfma_f32_16x16x32_bf16 v[82:85], v[184:187], v[212:215], 0
	v_mfma_f32_16x16x32_bf16 v[70:73], v[176:179], v[220:223], 0
	v_mfma_f32_16x16x32_bf16 v[66:69], v[184:187], v[220:223], 0
	v_mfma_f32_16x16x32_bf16 v[118:121], v[180:183], v[200:203], v[118:121]
	v_mfma_f32_16x16x32_bf16 v[114:117], v[192:195], v[200:203], v[114:117]
	v_mfma_f32_16x16x32_bf16 v[102:105], v[180:183], v[208:211], v[102:105]
	v_mfma_f32_16x16x32_bf16 v[98:101], v[192:195], v[208:211], v[98:101]
	v_mfma_f32_16x16x32_bf16 v[86:89], v[180:183], v[216:219], v[86:89]
	v_mfma_f32_16x16x32_bf16 v[82:85], v[192:195], v[216:219], v[82:85]
	v_mfma_f32_16x16x32_bf16 v[70:73], v[180:183], v[224:227], v[70:73]
	v_mfma_f32_16x16x32_bf16 v[66:69], v[192:195], v[224:227], v[66:69]
	s_setprio 0
	s_barrier
	s_add_i32 s15, s86, s66
	v_lshl_add_u64 v[170:171], s[58:59], 0, v[142:143]
	s_mov_b32 m0, s15
	ds_read_b128 v[196:199], v174 offset:16384
	ds_read_b128 v[200:203], v174 offset:17408
	ds_read_b128 v[204:207], v174 offset:18432
	ds_read_b128 v[208:211], v174 offset:19456
	ds_read_b128 v[212:215], v174 offset:20480
	ds_read_b128 v[216:219], v174 offset:21504
	ds_read_b128 v[220:223], v174 offset:22528
	ds_read_b128 v[224:227], v174 offset:23552
	global_load_lds_dwordx4 v[170:171], off
	s_add_i32 m0, s15, 0x2000
	s_add_u32 s18, s58, 0x40000
	v_lshl_add_u64 v[188:189], s[58:59], 0, v[146:147]
	s_addc_u32 s19, s59, 0
	s_add_i32 s15, s87, s66
	global_load_lds_dwordx4 v[188:189], off
	v_lshl_add_u64 v[228:229], s[18:19], 0, v[142:143]
	s_mov_b32 m0, s15
	v_lshl_add_u64 v[230:231], s[60:61], 0, v[144:145]
	global_load_lds_dwordx4 v[228:229], off
	v_lshl_add_u64 v[228:229], s[18:19], 0, v[146:147]
	s_add_i32 m0, s15, 0x2000
	s_nop 0
	global_load_lds_dwordx4 v[228:229], off
	v_lshl_add_u64 v[228:229], s[60:61], 0, v[140:141]
	s_mov_b32 m0, s67
	s_nop 0
	global_load_lds_dwordx4 v[228:229], off
	s_mov_b32 m0, s68
	s_nop 0
	global_load_lds_dwordx4 v[230:231], off
	s_waitcnt vmcnt(8)
	s_waitcnt lgkmcnt(0)
	s_barrier
; #define PG8_STAGE(bufoff, gbase, voff) do { _Pragma("unroll") for (int _i = 0; _i < 2; ++_i) \
;         __builtin_amdgcn_global_load_lds((const unsigned*)((const char*)(gbase) + (voff)[_i]), (PG8_LAS unsigned*)(lds + (bufoff) + ldsw + _i * 8192), 16, 0, 0); } while (0)
; #define PG8_LDA(dst, b, h) do { _Pragma("unroll") for (int m = 0; m < 4; ++m) _Pragma("unroll") for (int k = 0; k < 2; ++k) dst[m][k] = *(const PG8_LAS bf16x8*)(lds + PG8_SA(b, h) + aoff + m * 2048 + k * 1024); } while (0)
; #define PG8_LDB(dst, b, h) do { _Pragma("unroll") for (int n = 0; n < 2; ++n) _Pragma("unroll") for (int k = 0; k < 2; ++k) dst[n][k] = *(const PG8_LAS bf16x8*)(lds + PG8_SB(b, h) + boff + n * 2048 + k * 1024); } while (0)
; #define PG8_MMA(ai, bj, At, Bt) do { __builtin_amdgcn_s_setprio(1); _Pragma("unroll") for (int m = 0; m < 4; ++m) _Pragma("unroll") for (int n = 0; n < 2; ++n) _Pragma("unroll") for (int k = 0; k < 2; ++k) \
;         acc[ai][bj][m][n] = __builtin_amdgcn_mfma_f32_16x16x32_bf16(Bt[n][k], At[m][k], acc[ai][bj][m][n], 0, 0, 0); __builtin_amdgcn_s_setprio(0); } while (0)
; #define PG8_WAIT_V(n) asm volatile("s_waitcnt vmcnt(" #n ")" ::: "memory")
; #define PG8_WAIT_L(n) asm volatile("s_waitcnt lgkmcnt(" #n ")" ::: "memory")
; #define PG8_BAR __builtin_amdgcn_s_barrier()
; #define PG8_SCHED __builtin_amdgcn_sched_barrier(0)
; template <class Epi, class Sched, bool ALIGN_EPI = false, bool SP2 = false>
; __device__ __forceinline__ void gemm_phase(PG8_LAS unsigned char* lds, const Gemm g, const Sched& S, const Epi& E, const int tid) {
;     ...
;             PG8_WAIT_V(8); PG8_WAIT_L(0); PG8_BAR; PG8_MMA(1, 0, At, B0); PG8_MMA(1, 1, At, B1); PG8_BAR; PG8_SCHED;
;             PG8_LDB(B0, 1, 0); PG8_LDB(B1, 1, 1); PG8_SCHED; PG8_LDA(At, 1, 0); PG8_STAGE(PG8_SA(0, 1), a2 + hstep, voffA);
;             PG8_WAIT_V(8); PG8_WAIT_L(0); PG8_BAR; PG8_MMA(0, 0, At, B0); PG8_MMA(0, 1, At, B1); PG8_BAR; PG8_SCHED;
	s_setprio 1
	s_waitcnt lgkmcnt(0)
	v_mfma_f32_16x16x32_bf16 v[62:65], v[130:133], v[196:199], 0
	v_mfma_f32_16x16x32_bf16 v[58:61], v[162:165], v[196:199], 0
	v_mfma_f32_16x16x32_bf16 v[46:49], v[130:133], v[204:207], 0
	v_mfma_f32_16x16x32_bf16 v[42:45], v[162:165], v[204:207], 0
	v_mfma_f32_16x16x32_bf16 v[30:33], v[130:133], v[212:215], 0
	v_mfma_f32_16x16x32_bf16 v[26:29], v[162:165], v[212:215], 0
	v_mfma_f32_16x16x32_bf16 v[14:17], v[130:133], v[220:223], 0
	v_mfma_f32_16x16x32_bf16 v[10:13], v[162:165], v[220:223], 0
	v_mfma_f32_16x16x32_bf16 v[62:65], v[134:137], v[200:203], v[62:65]
	v_mfma_f32_16x16x32_bf16 v[58:61], v[166:169], v[200:203], v[58:61]
	v_mfma_f32_16x16x32_bf16 v[46:49], v[134:137], v[208:211], v[46:49]
	v_mfma_f32_16x16x32_bf16 v[42:45], v[166:169], v[208:211], v[42:45]
	v_mfma_f32_16x16x32_bf16 v[30:33], v[134:137], v[216:219], v[30:33]
	v_mfma_f32_16x16x32_bf16 v[26:29], v[166:169], v[216:219], v[26:29]
	v_mfma_f32_16x16x32_bf16 v[14:17], v[134:137], v[224:227], v[14:17]
	v_mfma_f32_16x16x32_bf16 v[10:13], v[166:169], v[224:227], v[10:13]
	s_setprio 0
	s_setprio 1
	v_mfma_f32_16x16x32_bf16 v[54:57], v[176:179], v[196:199], 0
	v_mfma_f32_16x16x32_bf16 v[50:53], v[184:187], v[196:199], 0
	v_mfma_f32_16x16x32_bf16 v[38:41], v[176:179], v[204:207], 0
	v_mfma_f32_16x16x32_bf16 v[34:37], v[184:187], v[204:207], 0
	v_mfma_f32_16x16x32_bf16 v[22:25], v[176:179], v[212:215], 0
	v_mfma_f32_16x16x32_bf16 v[18:21], v[184:187], v[212:215], 0
	v_mfma_f32_16x16x32_bf16 v[6:9], v[176:179], v[220:223], 0
	v_mfma_f32_16x16x32_bf16 v[2:5], v[184:187], v[220:223], 0
	v_mfma_f32_16x16x32_bf16 v[54:57], v[180:183], v[200:203], v[54:57]
	v_mfma_f32_16x16x32_bf16 v[50:53], v[192:195], v[200:203], v[50:53]
	v_mfma_f32_16x16x32_bf16 v[38:41], v[180:183], v[208:211], v[38:41]
	v_mfma_f32_16x16x32_bf16 v[34:37], v[192:195], v[208:211], v[34:37]
	v_mfma_f32_16x16x32_bf16 v[22:25], v[180:183], v[216:219], v[22:25]
	v_mfma_f32_16x16x32_bf16 v[18:21], v[192:195], v[216:219], v[18:21]
	v_mfma_f32_16x16x32_bf16 v[6:9], v[180:183], v[224:227], v[6:9]
	v_mfma_f32_16x16x32_bf16 v[2:5], v[192:195], v[224:227], v[2:5]
	s_setprio 0
	s_barrier
	s_add_i32 s15, 0, 0x18000
	s_add_i32 s62, 0, 0x1c000
	v_add_u32_e32 v166, s15, v172
	v_add_u32_e32 v191, s62, v172
	ds_read_b128 v[130:133], v166
	ds_read_b128 v[134:137], v166 offset:1024
	ds_read_b128 v[162:165], v166 offset:2048
	ds_read_b128 v[166:169], v166 offset:3072
	ds_read_b128 v[176:179], v191
	ds_read_b128 v[180:183], v191 offset:1024
	ds_read_b128 v[184:187], v191 offset:2048
	ds_read_b128 v[192:195], v191 offset:3072
	s_add_u32 s18, s60, 0x40000
	s_addc_u32 s19, s61, 0
	s_mov_b32 m0, s69
	v_lshl_add_u64 v[232:233], s[18:19], 0, v[140:141]
	ds_read_b128 v[196:199], v174 offset:32768
	ds_read_b128 v[200:203], v174 offset:33792
	ds_read_b128 v[204:207], v174 offset:34816
	ds_read_b128 v[208:211], v174 offset:35840
	ds_read_b128 v[212:215], v174 offset:36864
	ds_read_b128 v[216:219], v174 offset:37888
	ds_read_b128 v[220:223], v174 offset:38912
	ds_read_b128 v[224:227], v174 offset:39936
	global_load_lds_dwordx4 v[232:233], off
	v_lshl_add_u64 v[232:233], s[18:19], 0, v[144:145]
	s_mov_b32 m0, s71
	s_nop 0
	global_load_lds_dwordx4 v[232:233], off
	s_waitcnt vmcnt(8)
	s_waitcnt lgkmcnt(0)
	s_barrier
	s_setprio 1
	s_waitcnt lgkmcnt(0)
	v_mfma_f32_16x16x32_bf16 v[126:129], v[130:133], v[196:199], v[126:129]
	v_mfma_f32_16x16x32_bf16 v[122:125], v[162:165], v[196:199], v[122:125]
	v_mfma_f32_16x16x32_bf16 v[110:113], v[130:133], v[204:207], v[110:113]
	v_mfma_f32_16x16x32_bf16 v[106:109], v[162:165], v[204:207], v[106:109]
	v_mfma_f32_16x16x32_bf16 v[94:97], v[130:133], v[212:215], v[94:97]
	v_mfma_f32_16x16x32_bf16 v[90:93], v[162:165], v[212:215], v[90:93]
	v_mfma_f32_16x16x32_bf16 v[78:81], v[130:133], v[220:223], v[78:81]
	v_mfma_f32_16x16x32_bf16 v[74:77], v[162:165], v[220:223], v[74:77]
	v_mfma_f32_16x16x32_bf16 v[126:129], v[134:137], v[200:203], v[126:129]
	v_mfma_f32_16x16x32_bf16 v[122:125], v[166:169], v[200:203], v[122:125]
	v_mfma_f32_16x16x32_bf16 v[110:113], v[134:137], v[208:211], v[110:113]
	v_mfma_f32_16x16x32_bf16 v[106:109], v[166:169], v[208:211], v[106:109]
	v_mfma_f32_16x16x32_bf16 v[94:97], v[134:137], v[216:219], v[94:97]
	v_mfma_f32_16x16x32_bf16 v[90:93], v[166:169], v[216:219], v[90:93]
	v_mfma_f32_16x16x32_bf16 v[78:81], v[134:137], v[224:227], v[78:81]
	v_mfma_f32_16x16x32_bf16 v[74:77], v[166:169], v[224:227], v[74:77]
	s_setprio 0
	s_setprio 1
	v_mfma_f32_16x16x32_bf16 v[118:121], v[176:179], v[196:199], v[118:121]
	v_mfma_f32_16x16x32_bf16 v[114:117], v[184:187], v[196:199], v[114:117]
	v_mfma_f32_16x16x32_bf16 v[102:105], v[176:179], v[204:207], v[102:105]
	v_mfma_f32_16x16x32_bf16 v[98:101], v[184:187], v[204:207], v[98:101]
	v_mfma_f32_16x16x32_bf16 v[86:89], v[176:179], v[212:215], v[86:89]
	v_mfma_f32_16x16x32_bf16 v[82:85], v[184:187], v[212:215], v[82:85]
	v_mfma_f32_16x16x32_bf16 v[70:73], v[176:179], v[220:223], v[70:73]
	v_mfma_f32_16x16x32_bf16 v[66:69], v[184:187], v[220:223], v[66:69]
	v_mfma_f32_16x16x32_bf16 v[118:121], v[180:183], v[200:203], v[118:121]
	v_mfma_f32_16x16x32_bf16 v[114:117], v[192:195], v[200:203], v[114:117]
	v_mfma_f32_16x16x32_bf16 v[102:105], v[180:183], v[208:211], v[102:105]
	v_mfma_f32_16x16x32_bf16 v[98:101], v[192:195], v[208:211], v[98:101]
	v_mfma_f32_16x16x32_bf16 v[86:89], v[180:183], v[216:219], v[86:89]
	v_mfma_f32_16x16x32_bf16 v[82:85], v[192:195], v[216:219], v[82:85]
	v_mfma_f32_16x16x32_bf16 v[70:73], v[180:183], v[224:227], v[70:73]
	v_mfma_f32_16x16x32_bf16 v[66:69], v[192:195], v[224:227], v[66:69]
	s_setprio 0
	s_barrier
; #define PG8_STAGE(bufoff, gbase, voff) do { _Pragma("unroll") for (int _i = 0; _i < 2; ++_i) \
;         __builtin_amdgcn_global_load_lds((const unsigned*)((const char*)(gbase) + (voff)[_i]), (PG8_LAS unsigned*)(lds + (bufoff) + ldsw + _i * 8192), 16, 0, 0); } while (0)
; #define PG8_LDA(dst, b, h) do { _Pragma("unroll") for (int m = 0; m < 4; ++m) _Pragma("unroll") for (int k = 0; k < 2; ++k) dst[m][k] = *(const PG8_LAS bf16x8*)(lds + PG8_SA(b, h) + aoff + m * 2048 + k * 1024); } while (0)
; #define PG8_MMA(ai, bj, At, Bt) do { __builtin_amdgcn_s_setprio(1); _Pragma("unroll") for (int m = 0; m < 4; ++m) _Pragma("unroll") for (int n = 0; n < 2; ++n) _Pragma("unroll") for (int k = 0; k < 2; ++k) \
;         acc[ai][bj][m][n] = __builtin_amdgcn_mfma_f32_16x16x32_bf16(Bt[n][k], At[m][k], acc[ai][bj][m][n], 0, 0, 0); __builtin_amdgcn_s_setprio(0); } while (0)
; #define PG8_WAIT_V(n) asm volatile("s_waitcnt vmcnt(" #n ")" ::: "memory")
; #define PG8_WAIT_L(n) asm volatile("s_waitcnt lgkmcnt(" #n ")" ::: "memory")
; #define PG8_BAR __builtin_amdgcn_s_barrier()
; #define PG8_SCHED __builtin_amdgcn_sched_barrier(0)
; template <class Epi, class Sched, bool ALIGN_EPI = false, bool SP2 = false>
; __device__ __forceinline__ void gemm_phase(PG8_LAS unsigned char* lds, const Gemm g, const Sched& S, const Epi& E, const int tid) {
;     ...
;         for (int t = 0; t < nt; t += 2) {
;     ...
;             PG8_LDA(At, 1, 1); PG8_STAGE(PG8_SB(1, 0), b3, voffB); PG8_STAGE(PG8_SB(1, 1), b3 + hstep, voffB); PG8_STAGE(PG8_SA(1, 0), a3, voffA);
;             PG8_WAIT_V(8); PG8_WAIT_L(0); PG8_BAR; PG8_MMA(1, 0, At, B0); PG8_MMA(1, 1, At, B1); PG8_BAR; PG8_SCHED;
	s_add_i32 s15, s15, s66
	v_lshl_add_u64 v[170:171], v[170:171], 0, s[44:45]
	s_mov_b32 m0, s15
	ds_read_b128 v[196:199], v174 offset:49152
	ds_read_b128 v[200:203], v174 offset:50176
	ds_read_b128 v[204:207], v174 offset:51200
	ds_read_b128 v[208:211], v174 offset:52224
	ds_read_b128 v[212:215], v174 offset:53248
	ds_read_b128 v[216:219], v174 offset:54272
	ds_read_b128 v[220:223], v174 offset:55296
	ds_read_b128 v[224:227], v174 offset:56320
	global_load_lds_dwordx4 v[170:171], off
	s_add_i32 m0, s15, 0x2000
	s_add_u32 s18, s58, 0x40080
	v_lshl_add_u64 v[170:171], v[188:189], 0, s[44:45]
	s_addc_u32 s19, s59, 0
	s_add_i32 s15, s62, s66
	global_load_lds_dwordx4 v[170:171], off
	v_lshl_add_u64 v[170:171], s[18:19], 0, v[142:143]
	s_mov_b32 m0, s15
	s_nop 0
	global_load_lds_dwordx4 v[170:171], off
	v_lshl_add_u64 v[170:171], s[18:19], 0, v[146:147]
	s_add_i32 m0, s15, 0x2000
	s_nop 0
	global_load_lds_dwordx4 v[170:171], off
	v_lshl_add_u64 v[170:171], v[228:229], 0, s[44:45]
	s_mov_b32 m0, s77
	s_nop 0
	global_load_lds_dwordx4 v[170:171], off
	v_lshl_add_u64 v[170:171], v[230:231], 0, s[44:45]
	s_mov_b32 m0, s78
	s_nop 0
	global_load_lds_dwordx4 v[170:171], off
	s_waitcnt vmcnt(8)
	s_waitcnt lgkmcnt(0)
	s_barrier
	s_setprio 1
	s_waitcnt lgkmcnt(0)
	v_mfma_f32_16x16x32_bf16 v[62:65], v[130:133], v[196:199], v[62:65]
	v_mfma_f32_16x16x32_bf16 v[58:61], v[162:165], v[196:199], v[58:61]
	v_mfma_f32_16x16x32_bf16 v[46:49], v[130:133], v[204:207], v[46:49]
	v_mfma_f32_16x16x32_bf16 v[42:45], v[162:165], v[204:207], v[42:45]
	v_mfma_f32_16x16x32_bf16 v[30:33], v[130:133], v[212:215], v[30:33]
	v_mfma_f32_16x16x32_bf16 v[26:29], v[162:165], v[212:215], v[26:29]
	v_mfma_f32_16x16x32_bf16 v[14:17], v[130:133], v[220:223], v[14:17]
	v_mfma_f32_16x16x32_bf16 v[10:13], v[162:165], v[220:223], v[10:13]
	v_mfma_f32_16x16x32_bf16 v[62:65], v[134:137], v[200:203], v[62:65]
	v_mfma_f32_16x16x32_bf16 v[58:61], v[166:169], v[200:203], v[58:61]
	v_mfma_f32_16x16x32_bf16 v[46:49], v[134:137], v[208:211], v[46:49]
	v_mfma_f32_16x16x32_bf16 v[42:45], v[166:169], v[208:211], v[42:45]
	v_mfma_f32_16x16x32_bf16 v[30:33], v[134:137], v[216:219], v[30:33]
	v_mfma_f32_16x16x32_bf16 v[26:29], v[166:169], v[216:219], v[26:29]
	v_mfma_f32_16x16x32_bf16 v[14:17], v[134:137], v[224:227], v[14:17]
	v_mfma_f32_16x16x32_bf16 v[10:13], v[166:169], v[224:227], v[10:13]
	s_setprio 0
	s_setprio 1
	v_mfma_f32_16x16x32_bf16 v[54:57], v[176:179], v[196:199], v[54:57]
	v_mfma_f32_16x16x32_bf16 v[50:53], v[184:187], v[196:199], v[50:53]
	v_mfma_f32_16x16x32_bf16 v[38:41], v[176:179], v[204:207], v[38:41]
	v_mfma_f32_16x16x32_bf16 v[34:37], v[184:187], v[204:207], v[34:37]
	v_mfma_f32_16x16x32_bf16 v[22:25], v[176:179], v[212:215], v[22:25]
	v_mfma_f32_16x16x32_bf16 v[18:21], v[184:187], v[212:215], v[18:21]
	v_mfma_f32_16x16x32_bf16 v[6:9], v[176:179], v[220:223], v[6:9]
	v_mfma_f32_16x16x32_bf16 v[2:5], v[184:187], v[220:223], v[2:5]
	v_mfma_f32_16x16x32_bf16 v[54:57], v[180:183], v[200:203], v[54:57]
	v_mfma_f32_16x16x32_bf16 v[50:53], v[192:195], v[200:203], v[50:53]
	v_mfma_f32_16x16x32_bf16 v[38:41], v[180:183], v[208:211], v[38:41]
	v_mfma_f32_16x16x32_bf16 v[34:37], v[192:195], v[208:211], v[34:37]
	v_mfma_f32_16x16x32_bf16 v[22:25], v[180:183], v[216:219], v[22:25]
	v_mfma_f32_16x16x32_bf16 v[18:21], v[192:195], v[216:219], v[18:21]
	v_mfma_f32_16x16x32_bf16 v[6:9], v[180:183], v[224:227], v[6:9]
	v_mfma_f32_16x16x32_bf16 v[2:5], v[192:195], v[224:227], v[2:5]
	s_setprio 0
	s_barrier
	s_add_i32 s51, s51, 2
	s_add_u32 s5, s5, 0x100
	s_addc_u32 s49, s49, 0
	s_add_u32 s56, s56, 0x100
	s_addc_u32 s57, s57, 0

; #define PG8_BAR __builtin_amdgcn_s_barrier()
; template <class Epi, class Sched, bool ALIGN_EPI = false, bool SP2 = false>
; __device__ __forceinline__ void gemm_phase(PG8_LAS unsigned char* lds, const Gemm g, const Sched& S, const Epi& E, const int tid) {
;     ...
;         if (!has_next) break;
; #pragma unroll
;         for (int a = 0; a < 2; ++a)
; #pragma unroll
;             for (int b = 0; b < 2; ++b)
; #pragma unroll
;                 for (int m = 0; m < 4; ++m)
; #pragma unroll
;                     for (int n = 0; n < 2; ++n) acc[a][b][m][n] = (f32x4){0.f, 0.f, 0.f, 0.f};
;         cur = nxt; cA = nA; cB = nB; ++ui;
;         if constexpr (ALIGN_EPI) { if (wr == 1) PG8_BAR; }
;     }
.LBB0_1180:
	s_and_b64 vcc, exec, s[2:3]
	s_mov_b64 s[2:3], -1
	s_cbranch_vccnz .LBB0_1092
	s_andn2_b64 vcc, exec, s[28:29]
	s_cbranch_vccnz .LBB0_1091
	s_mov_b32 s101, 1
	s_branch .LBB0_1091

;     __device__ __forceinline__ bool next(int i, pg8::Unit& u) const { if (!base.next(i >> 2, u)) return false; u.sub = i & 3; return true; }
;     __host__ __device__ bool next(int i, Unit& u) const {
;         const long L = (long)i * G + c; if (L >= nwg) return false;
;         int wgid = (int)L; { const int q = nwg / NXCD, r = nwg % NXCD, xcd = wgid % NXCD, off = wgid / NXCD; wgid = (xcd < r ? xcd * (q + 1) : r * (q + 1) + (xcd - r) * q) + off; }
;         const int nig = WGM * nN, gid = wgid / nig, fm = gid * WGM, gsz = (nM - fm) < WGM ? (nM - fm) : WGM;
;         u.pm = fm + ((wgid % nig) % gsz); u.pn = (wgid % nig) / gsz; u.sub = 0; return true;
; template <class Epi, class Sched, bool ALIGN_EPI = false, bool SP2 = false>
; __device__ __forceinline__ void gemm_phase(PG8_LAS unsigned char* lds, const Gemm g, const Sched& S, const Epi& E, const int tid) {
;     ...
;     Unit cur, nxt; int ui = 0;
;     if (!S.next(0, cur)) return;
.LBB0_1363:
	s_mov_b32 s101, 0
	s_add_i32 s0, 0, 0x204b0
	s_waitcnt vmcnt(0)
	v_mov_b32_e32 v10, v190
	s_mov_b32 s50, s14
	s_mov_b32 s51, s16
	v_mov_b32_e32 v1, s0
	ds_read_b64 v[2:3], v1
	s_cmpk_lt_i32 s50, 0x308
	s_cselect_b64 s[0:1], -1, 0
	s_cmpk_gt_i32 s50, 0x307
	v_readfirstlane_b32 s2, v10
	s_waitcnt lgkmcnt(0)
	v_readfirstlane_b32 s3, v3
	v_readfirstlane_b32 s4, v2
	s_cbranch_scc1 .LBB0_1365
	s_ashr_i32 s5, s50, 31
	s_lshr_b32 s5, s5, 29
	s_add_i32 s5, s50, s5
	s_ashr_i32 s6, s5, 3
	s_and_b32 s5, s5, -8
	s_sub_i32 s5, s50, s5
	s_cmp_lt_i32 s5, 0
	s_movk_i32 s7, 0x62
	s_cselect_b32 s7, s7, 0x61
	s_mul_i32 s5, s7, s5
	s_add_i32 s5, s5, s6
	s_ashr_i32 s6, s5, 31
	s_lshr_b32 s6, s6, 27
	s_add_i32 s6, s5, s6
	s_ashr_i32 s7, s6, 5
	s_lshl_b32 s8, s7, 3
	s_sub_i32 s7, 0xc2, s8
	s_min_u32 s9, s7, 8
	s_andn2_b32 s6, s6, 31
	s_sub_i32 s5, s5, s6
	v_cvt_f32_ubyte0_e32 v2, s9
	v_cvt_f32_i32_e32 v1, s5
	v_rcp_iflag_f32_e32 v3, v2
	s_ashr_i32 s6, s5, 30
	s_or_b32 s10, s6, 1
	v_mul_f32_e32 v3, v1, v3
	v_trunc_f32_e32 v3, v3
	v_fma_f32 v1, -v3, v2, v1
	v_cvt_i32_f32_e32 v3, v3
	v_cmp_ge_f32_e64 s[6:7], |v1|, v2
	s_and_b64 s[6:7], s[6:7], exec
	s_cselect_b32 s6, s10, 0
	v_readfirstlane_b32 s7, v3
	s_add_i32 s6, s7, s6
	s_sext_i32_i8 s44, s6
	s_mul_i32 s6, s6, s9
	s_sub_i32 s5, s5, s6
	s_sext_i32_i8 s5, s5
	s_add_i32 s6, s8, s5

; #define PG8_STAGE(bufoff, gbase, voff) do { _Pragma("unroll") for (int _i = 0; _i < 2; ++_i) \
;         __builtin_amdgcn_global_load_lds((const unsigned*)((const char*)(gbase) + (voff)[_i]), (PG8_LAS unsigned*)(lds + (bufoff) + ldsw + _i * 8192), 16, 0, 0); } while (0)
; #define PG8_LDA(dst, b, h) do { _Pragma("unroll") for (int m = 0; m < 4; ++m) _Pragma("unroll") for (int k = 0; k < 2; ++k) dst[m][k] = *(const PG8_LAS bf16x8*)(lds + PG8_SA(b, h) + aoff + m * 2048 + k * 1024); } while (0)
; #define PG8_LDB(dst, b, h) do { _Pragma("unroll") for (int n = 0; n < 2; ++n) _Pragma("unroll") for (int k = 0; k < 2; ++k) dst[n][k] = *(const PG8_LAS bf16x8*)(lds + PG8_SB(b, h) + boff + n * 2048 + k * 1024); } while (0)
; #define PG8_WAIT_V(n) asm volatile("s_waitcnt vmcnt(" #n ")" ::: "memory")
; #define PG8_WAIT_L(n) asm volatile("s_waitcnt lgkmcnt(" #n ")" ::: "memory")
; #define PG8_BAR __builtin_amdgcn_s_barrier()
; #define PG8_SCHED __builtin_amdgcn_sched_barrier(0)
; template <class Epi, class Sched, bool ALIGN_EPI = false, bool SP2 = false>
; __device__ __forceinline__ void gemm_phase(PG8_LAS unsigned char* lds, const Gemm g, const Sched& S, const Epi& E, const int tid) {
;     ...
;         const bool has_next = S.next(ui + 1, nxt);
;         const char* nA = has_next ? S.aptr(nxt) : cA; const char* nB = has_next ? S.bptr(nxt) : cB;
;         for (int t = 0; t < nt; t += 2) {
;             const bool last = (t == nt - 2);
;             const char* a1 = cA + (size_t)(t + 1) * kstep;
;             const char* a2 = last ? nA : cA + (size_t)(t + 2) * kstep; const char* b2 = last ? nB : cB + (size_t)(t + 2) * kstep;
;             const char* a3 = a2 + kstep; const char* b3 = b2 + kstep;
;             if (last && has_next) S.a_ready(nxt);
;             if constexpr (SP2) {
;             PG8_LDB(B0, 0, 0); PG8_LDB(B1, 0, 1); PG8_SCHED; PG8_LDA(At, 0, 0); PG8_STAGE(PG8_SA(1, 1), a1 + hstep, voffA);
;             PG8_WAIT_V(8); PG8_WAIT_L(0); PG8_BAR; PG8_MMA(0, 0, At, B0); PG8_MMA(0, 1, At, B1); PG8_BAR; PG8_SCHED;
;             PG8_LDA(At, 0, 1); PG8_STAGE(PG8_SB(0, 0), b2, voffB); PG8_STAGE(PG8_SB(0, 1), b2 + hstep, voffB); PG8_STAGE(PG8_SA(0, 0), a2, voffA);
;             PG8_WAIT_V(8); PG8_WAIT_L(0); PG8_BAR; PG8_MMA(1, 0, At, B0); PG8_MMA(1, 1, At, B1); PG8_BAR; PG8_SCHED;
.LBB0_1373:
	s_ashr_i32 s39, s38, 31
	s_lshl_b64 s[18:19], s[38:39], 19
	s_add_u32 s40, s52, s18
	s_addc_u32 s41, s53, s19
	s_and_b64 s[18:19], s[4:5], exec
	s_cselect_b32 s7, s41, s11
	s_cselect_b32 s39, s40, s10
	s_ashr_i32 s37, s36, 31
	s_lshl_b64 s[18:19], s[36:37], 19
	s_add_u32 s42, s54, s18
	s_addc_u32 s43, s55, s19
	s_and_b64 s[18:19], s[4:5], exec
	s_cselect_b32 s37, s43, s9
	s_cselect_b32 s45, s42, s8
	s_add_u32 s48, s8, 0x100
	s_addc_u32 s49, s9, 0
	s_add_u32 s8, s10, 0x40080
	s_addc_u32 s9, s11, 0
	s_mov_b32 s76, -2
	s_cmp_eq_u32 s101, 0
	s_cbranch_scc1 .Lnobar4
	s_barrier
.Lnobar4:
	ds_read_b128 v[130:133], v204
	ds_read_b128 v[134:137], v204 offset:1024
	ds_read_b128 v[138:141], v204 offset:2048
	ds_read_b128 v[142:145], v204 offset:3072
	ds_read_b128 v[146:149], v205
	ds_read_b128 v[150:153], v205 offset:1024
	ds_read_b128 v[154:157], v205 offset:2048
	ds_read_b128 v[158:161], v205 offset:3072
	s_add_u32 s10, s8, 0xfffc0080
	s_addc_u32 s11, s9, -1
	s_cmp_eq_u32 s76, 12
	s_cselect_b32 s47, s7, s11
	s_cselect_b32 s46, s39, s10
	s_cselect_b32 s11, s37, s49
	s_cselect_b32 s10, s45, s48
	v_lshl_add_u64 v[220:221], s[8:9], 0, v[176:177]
	s_add_i32 m0, s57, 0xc000
	ds_read_b128 v[182:185], v206
	ds_read_b128 v[186:189], v206 offset:1024
	ds_read_b128 v[192:195], v206 offset:2048
	ds_read_b128 v[196:199], v206 offset:3072
	ds_read_b128 v[200:203], v206 offset:4096
	ds_read_b128 v[208:211], v206 offset:5120
	ds_read_b128 v[212:215], v206 offset:6144
	ds_read_b128 v[216:219], v206 offset:7168
	global_load_lds_dwordx4 v[220:221], off
	v_lshl_add_u64 v[220:221], s[8:9], 0, v[174:175]
	s_add_i32 m0, s57, 0xe000
	s_nop 0
	global_load_lds_dwordx4 v[220:221], off
	s_waitcnt vmcnt(8)
	s_waitcnt lgkmcnt(0)
	s_barrier
	s_setprio 1
	s_waitcnt lgkmcnt(0)
	v_mfma_f32_16x16x32_bf16 v[126:129], v[130:133], v[182:185], 0
	v_mfma_f32_16x16x32_bf16 v[122:125], v[138:141], v[182:185], 0
	v_mfma_f32_16x16x32_bf16 v[110:113], v[130:133], v[192:195], 0
	v_mfma_f32_16x16x32_bf16 v[106:109], v[138:141], v[192:195], 0
	v_mfma_f32_16x16x32_bf16 v[94:97], v[130:133], v[200:203], 0
	v_mfma_f32_16x16x32_bf16 v[90:93], v[138:141], v[200:203], 0
	v_mfma_f32_16x16x32_bf16 v[78:81], v[130:133], v[212:215], 0
	v_mfma_f32_16x16x32_bf16 v[74:77], v[138:141], v[212:215], 0
	v_mfma_f32_16x16x32_bf16 v[126:129], v[134:137], v[186:189], v[126:129]
	v_mfma_f32_16x16x32_bf16 v[122:125], v[142:145], v[186:189], v[122:125]
	v_mfma_f32_16x16x32_bf16 v[110:113], v[134:137], v[196:199], v[110:113]
	v_mfma_f32_16x16x32_bf16 v[106:109], v[142:145], v[196:199], v[106:109]
	v_mfma_f32_16x16x32_bf16 v[94:97], v[134:137], v[208:211], v[94:97]
	v_mfma_f32_16x16x32_bf16 v[90:93], v[142:145], v[208:211], v[90:93]
	v_mfma_f32_16x16x32_bf16 v[78:81], v[134:137], v[216:219], v[78:81]
	v_mfma_f32_16x16x32_bf16 v[74:77], v[142:145], v[216:219], v[74:77]
	s_setprio 0
	s_setprio 1
	v_mfma_f32_16x16x32_bf16 v[118:121], v[146:149], v[182:185], 0
	v_mfma_f32_16x16x32_bf16 v[114:117], v[154:157], v[182:185], 0
	v_mfma_f32_16x16x32_bf16 v[102:105], v[146:149], v[192:195], 0
	v_mfma_f32_16x16x32_bf16 v[98:101], v[154:157], v[192:195], 0
	v_mfma_f32_16x16x32_bf16 v[86:89], v[146:149], v[200:203], 0
	v_mfma_f32_16x16x32_bf16 v[82:85], v[154:157], v[200:203], 0
	v_mfma_f32_16x16x32_bf16 v[70:73], v[146:149], v[212:215], 0
	v_mfma_f32_16x16x32_bf16 v[66:69], v[154:157], v[212:215], 0
	v_mfma_f32_16x16x32_bf16 v[118:121], v[150:153], v[186:189], v[118:121]
	v_mfma_f32_16x16x32_bf16 v[114:117], v[158:161], v[186:189], v[114:117]
	v_mfma_f32_16x16x32_bf16 v[102:105], v[150:153], v[196:199], v[102:105]
	v_mfma_f32_16x16x32_bf16 v[98:101], v[158:161], v[196:199], v[98:101]
	v_mfma_f32_16x16x32_bf16 v[86:89], v[150:153], v[208:211], v[86:89]
	v_mfma_f32_16x16x32_bf16 v[82:85], v[158:161], v[208:211], v[82:85]
	v_mfma_f32_16x16x32_bf16 v[70:73], v[150:153], v[216:219], v[70:73]
	v_mfma_f32_16x16x32_bf16 v[66:69], v[158:161], v[216:219], v[66:69]
	s_setprio 0
	s_barrier
	s_add_i32 s15, s67, s56
	v_lshl_add_u64 v[220:221], s[10:11], 0, v[164:165]
	s_mov_b32 m0, s15
	ds_read_b128 v[182:185], v206 offset:16384
	ds_read_b128 v[186:189], v206 offset:17408
	ds_read_b128 v[192:195], v206 offset:18432
	ds_read_b128 v[196:199], v206 offset:19456
	ds_read_b128 v[200:203], v206 offset:20480
	ds_read_b128 v[208:211], v206 offset:21504
	ds_read_b128 v[212:215], v206 offset:22528
	ds_read_b128 v[216:219], v206 offset:23552
	global_load_lds_dwordx4 v[220:221], off
	s_add_i32 m0, s15, 0x2000
	s_add_u32 s18, s10, 0x40000
	v_lshl_add_u64 v[222:223], s[10:11], 0, v[168:169]
	s_addc_u32 s19, s11, 0
	s_add_i32 s15, s68, s56
	global_load_lds_dwordx4 v[222:223], off
	v_lshl_add_u64 v[224:225], s[18:19], 0, v[164:165]
	s_mov_b32 m0, s15
	v_lshl_add_u64 v[226:227], s[46:47], 0, v[166:167]
	global_load_lds_dwordx4 v[224:225], off
	v_lshl_add_u64 v[224:225], s[18:19], 0, v[168:169]
	s_add_i32 m0, s15, 0x2000
	s_nop 0
	global_load_lds_dwordx4 v[224:225], off
	v_lshl_add_u64 v[224:225], s[46:47], 0, v[162:163]
	s_mov_b32 m0, s57
	s_nop 0
	global_load_lds_dwordx4 v[224:225], off
	s_mov_b32 m0, s58
	s_nop 0
	global_load_lds_dwordx4 v[226:227], off
	s_waitcnt vmcnt(8)
	s_waitcnt lgkmcnt(0)
	s_barrier
; #define PG8_STAGE(bufoff, gbase, voff) do { _Pragma("unroll") for (int _i = 0; _i < 2; ++_i) \
;         __builtin_amdgcn_global_load_lds((const unsigned*)((const char*)(gbase) + (voff)[_i]), (PG8_LAS unsigned*)(lds + (bufoff) + ldsw + _i * 8192), 16, 0, 0); } while (0)
; #define PG8_LDA(dst, b, h) do { _Pragma("unroll") for (int m = 0; m < 4; ++m) _Pragma("unroll") for (int k = 0; k < 2; ++k) dst[m][k] = *(const PG8_LAS bf16x8*)(lds + PG8_SA(b, h) + aoff + m * 2048 + k * 1024); } while (0)
; #define PG8_LDB(dst, b, h) do { _Pragma("unroll") for (int n = 0; n < 2; ++n) _Pragma("unroll") for (int k = 0; k < 2; ++k) dst[n][k] = *(const PG8_LAS bf16x8*)(lds + PG8_SB(b, h) + boff + n * 2048 + k * 1024); } while (0)
; #define PG8_MMA(ai, bj, At, Bt) do { __builtin_amdgcn_s_setprio(1); _Pragma("unroll") for (int m = 0; m < 4; ++m) _Pragma("unroll") for (int n = 0; n < 2; ++n) _Pragma("unroll") for (int k = 0; k < 2; ++k) \
;         acc[ai][bj][m][n] = __builtin_amdgcn_mfma_f32_16x16x32_bf16(Bt[n][k], At[m][k], acc[ai][bj][m][n], 0, 0, 0); __builtin_amdgcn_s_setprio(0); } while (0)
; #define PG8_WAIT_V(n) asm volatile("s_waitcnt vmcnt(" #n ")" ::: "memory")
; #define PG8_WAIT_L(n) asm volatile("s_waitcnt lgkmcnt(" #n ")" ::: "memory")
; #define PG8_BAR __builtin_amdgcn_s_barrier()
; #define PG8_SCHED __builtin_amdgcn_sched_barrier(0)
; template <class Epi, class Sched, bool ALIGN_EPI = false, bool SP2 = false>
; __device__ __forceinline__ void gemm_phase(PG8_LAS unsigned char* lds, const Gemm g, const Sched& S, const Epi& E, const int tid) {
;     ...
;             PG8_WAIT_V(8); PG8_WAIT_L(0); PG8_BAR; PG8_MMA(1, 0, At, B0); PG8_MMA(1, 1, At, B1); PG8_BAR; PG8_SCHED;
;             PG8_LDB(B0, 1, 0); PG8_LDB(B1, 1, 1); PG8_SCHED; PG8_LDA(At, 1, 0); PG8_STAGE(PG8_SA(0, 1), a2 + hstep, voffA);
;             PG8_WAIT_V(8); PG8_WAIT_L(0); PG8_BAR; PG8_MMA(0, 0, At, B0); PG8_MMA(0, 1, At, B1); PG8_BAR; PG8_SCHED;
	s_setprio 1
	s_waitcnt lgkmcnt(0)
	v_mfma_f32_16x16x32_bf16 v[62:65], v[130:133], v[182:185], 0
	v_mfma_f32_16x16x32_bf16 v[58:61], v[138:141], v[182:185], 0
	v_mfma_f32_16x16x32_bf16 v[46:49], v[130:133], v[192:195], 0
	v_mfma_f32_16x16x32_bf16 v[42:45], v[138:141], v[192:195], 0
	v_mfma_f32_16x16x32_bf16 v[30:33], v[130:133], v[200:203], 0
	v_mfma_f32_16x16x32_bf16 v[26:29], v[138:141], v[200:203], 0
	v_mfma_f32_16x16x32_bf16 v[14:17], v[130:133], v[212:215], 0
	v_mfma_f32_16x16x32_bf16 v[10:13], v[138:141], v[212:215], 0
	v_mfma_f32_16x16x32_bf16 v[62:65], v[134:137], v[186:189], v[62:65]
	v_mfma_f32_16x16x32_bf16 v[58:61], v[142:145], v[186:189], v[58:61]
	v_mfma_f32_16x16x32_bf16 v[46:49], v[134:137], v[196:199], v[46:49]
	v_mfma_f32_16x16x32_bf16 v[42:45], v[142:145], v[196:199], v[42:45]
	v_mfma_f32_16x16x32_bf16 v[30:33], v[134:137], v[208:211], v[30:33]
	v_mfma_f32_16x16x32_bf16 v[26:29], v[142:145], v[208:211], v[26:29]
	v_mfma_f32_16x16x32_bf16 v[14:17], v[134:137], v[216:219], v[14:17]
	v_mfma_f32_16x16x32_bf16 v[10:13], v[142:145], v[216:219], v[10:13]
	s_setprio 0
	s_setprio 1
	v_mfma_f32_16x16x32_bf16 v[54:57], v[146:149], v[182:185], 0
	v_mfma_f32_16x16x32_bf16 v[50:53], v[154:157], v[182:185], 0
	v_mfma_f32_16x16x32_bf16 v[38:41], v[146:149], v[192:195], 0
	v_mfma_f32_16x16x32_bf16 v[34:37], v[154:157], v[192:195], 0
	v_mfma_f32_16x16x32_bf16 v[22:25], v[146:149], v[200:203], 0
	v_mfma_f32_16x16x32_bf16 v[18:21], v[154:157], v[200:203], 0
	v_mfma_f32_16x16x32_bf16 v[6:9], v[146:149], v[212:215], 0
	v_mfma_f32_16x16x32_bf16 v[2:5], v[154:157], v[212:215], 0
	v_mfma_f32_16x16x32_bf16 v[54:57], v[150:153], v[186:189], v[54:57]
	v_mfma_f32_16x16x32_bf16 v[50:53], v[158:161], v[186:189], v[50:53]
	v_mfma_f32_16x16x32_bf16 v[38:41], v[150:153], v[196:199], v[38:41]
	v_mfma_f32_16x16x32_bf16 v[34:37], v[158:161], v[196:199], v[34:37]
	v_mfma_f32_16x16x32_bf16 v[22:25], v[150:153], v[208:211], v[22:25]
	v_mfma_f32_16x16x32_bf16 v[18:21], v[158:161], v[208:211], v[18:21]
	v_mfma_f32_16x16x32_bf16 v[6:9], v[150:153], v[216:219], v[6:9]
	v_mfma_f32_16x16x32_bf16 v[2:5], v[158:161], v[216:219], v[2:5]
	s_setprio 0
	s_barrier
	s_add_i32 s15, 0, 0x18000
	s_add_i32 s77, 0, 0x1c000
	v_add_u32_e32 v142, s15, v191
	v_add_u32_e32 v158, s77, v191
	ds_read_b128 v[130:133], v142
	ds_read_b128 v[134:137], v142 offset:1024
	ds_read_b128 v[138:141], v142 offset:2048
	ds_read_b128 v[142:145], v142 offset:3072
	ds_read_b128 v[146:149], v158
	ds_read_b128 v[150:153], v158 offset:1024
	ds_read_b128 v[154:157], v158 offset:2048
	ds_read_b128 v[158:161], v158 offset:3072
	s_add_u32 s18, s46, 0x40000
	s_addc_u32 s19, s47, 0
	s_mov_b32 m0, s59
	v_lshl_add_u64 v[228:229], s[18:19], 0, v[162:163]
	ds_read_b128 v[182:185], v206 offset:32768
	ds_read_b128 v[186:189], v206 offset:33792
	ds_read_b128 v[192:195], v206 offset:34816
	ds_read_b128 v[196:199], v206 offset:35840
	ds_read_b128 v[200:203], v206 offset:36864
	ds_read_b128 v[208:211], v206 offset:37888
	ds_read_b128 v[212:215], v206 offset:38912
	ds_read_b128 v[216:219], v206 offset:39936
	global_load_lds_dwordx4 v[228:229], off
	v_lshl_add_u64 v[228:229], s[18:19], 0, v[166:167]
	s_mov_b32 m0, s60
	s_nop 0
	global_load_lds_dwordx4 v[228:229], off
	s_waitcnt vmcnt(8)
	s_waitcnt lgkmcnt(0)
	s_barrier
	s_setprio 1
	s_waitcnt lgkmcnt(0)
	v_mfma_f32_16x16x32_bf16 v[126:129], v[130:133], v[182:185], v[126:129]
	v_mfma_f32_16x16x32_bf16 v[122:125], v[138:141], v[182:185], v[122:125]
	v_mfma_f32_16x16x32_bf16 v[110:113], v[130:133], v[192:195], v[110:113]
	v_mfma_f32_16x16x32_bf16 v[106:109], v[138:141], v[192:195], v[106:109]
	v_mfma_f32_16x16x32_bf16 v[94:97], v[130:133], v[200:203], v[94:97]
	v_mfma_f32_16x16x32_bf16 v[90:93], v[138:141], v[200:203], v[90:93]
	v_mfma_f32_16x16x32_bf16 v[78:81], v[130:133], v[212:215], v[78:81]
	v_mfma_f32_16x16x32_bf16 v[74:77], v[138:141], v[212:215], v[74:77]
	v_mfma_f32_16x16x32_bf16 v[126:129], v[134:137], v[186:189], v[126:129]
	v_mfma_f32_16x16x32_bf16 v[122:125], v[142:145], v[186:189], v[122:125]
	v_mfma_f32_16x16x32_bf16 v[110:113], v[134:137], v[196:199], v[110:113]
	v_mfma_f32_16x16x32_bf16 v[106:109], v[142:145], v[196:199], v[106:109]
	v_mfma_f32_16x16x32_bf16 v[94:97], v[134:137], v[208:211], v[94:97]
	v_mfma_f32_16x16x32_bf16 v[90:93], v[142:145], v[208:211], v[90:93]
	v_mfma_f32_16x16x32_bf16 v[78:81], v[134:137], v[216:219], v[78:81]
	v_mfma_f32_16x16x32_bf16 v[74:77], v[142:145], v[216:219], v[74:77]
	s_setprio 0
	s_setprio 1
	v_mfma_f32_16x16x32_bf16 v[118:121], v[146:149], v[182:185], v[118:121]
	v_mfma_f32_16x16x32_bf16 v[114:117], v[154:157], v[182:185], v[114:117]
	v_mfma_f32_16x16x32_bf16 v[102:105], v[146:149], v[192:195], v[102:105]
	v_mfma_f32_16x16x32_bf16 v[98:101], v[154:157], v[192:195], v[98:101]
	v_mfma_f32_16x16x32_bf16 v[86:89], v[146:149], v[200:203], v[86:89]
	v_mfma_f32_16x16x32_bf16 v[82:85], v[154:157], v[200:203], v[82:85]
	v_mfma_f32_16x16x32_bf16 v[70:73], v[146:149], v[212:215], v[70:73]
	v_mfma_f32_16x16x32_bf16 v[66:69], v[154:157], v[212:215], v[66:69]
	v_mfma_f32_16x16x32_bf16 v[118:121], v[150:153], v[186:189], v[118:121]
	v_mfma_f32_16x16x32_bf16 v[114:117], v[158:161], v[186:189], v[114:117]
	v_mfma_f32_16x16x32_bf16 v[102:105], v[150:153], v[196:199], v[102:105]
	v_mfma_f32_16x16x32_bf16 v[98:101], v[158:161], v[196:199], v[98:101]
	v_mfma_f32_16x16x32_bf16 v[86:89], v[150:153], v[208:211], v[86:89]
	v_mfma_f32_16x16x32_bf16 v[82:85], v[158:161], v[208:211], v[82:85]
	v_mfma_f32_16x16x32_bf16 v[70:73], v[150:153], v[216:219], v[70:73]
	v_mfma_f32_16x16x32_bf16 v[66:69], v[158:161], v[216:219], v[66:69]
	s_setprio 0
	s_barrier
; #define PG8_STAGE(bufoff, gbase, voff) do { _Pragma("unroll") for (int _i = 0; _i < 2; ++_i) \
;         __builtin_amdgcn_global_load_lds((const unsigned*)((const char*)(gbase) + (voff)[_i]), (PG8_LAS unsigned*)(lds + (bufoff) + ldsw + _i * 8192), 16, 0, 0); } while (0)
; #define PG8_LDA(dst, b, h) do { _Pragma("unroll") for (int m = 0; m < 4; ++m) _Pragma("unroll") for (int k = 0; k < 2; ++k) dst[m][k] = *(const PG8_LAS bf16x8*)(lds + PG8_SA(b, h) + aoff + m * 2048 + k * 1024); } while (0)
; #define PG8_MMA(ai, bj, At, Bt) do { __builtin_amdgcn_s_setprio(1); _Pragma("unroll") for (int m = 0; m < 4; ++m) _Pragma("unroll") for (int n = 0; n < 2; ++n) _Pragma("unroll") for (int k = 0; k < 2; ++k) \
;         acc[ai][bj][m][n] = __builtin_amdgcn_mfma_f32_16x16x32_bf16(Bt[n][k], At[m][k], acc[ai][bj][m][n], 0, 0, 0); __builtin_amdgcn_s_setprio(0); } while (0)
; #define PG8_WAIT_V(n) asm volatile("s_waitcnt vmcnt(" #n ")" ::: "memory")
; #define PG8_WAIT_L(n) asm volatile("s_waitcnt lgkmcnt(" #n ")" ::: "memory")
; #define PG8_BAR __builtin_amdgcn_s_barrier()
; #define PG8_SCHED __builtin_amdgcn_sched_barrier(0)
; template <class Epi, class Sched, bool ALIGN_EPI = false, bool SP2 = false>
; __device__ __forceinline__ void gemm_phase(PG8_LAS unsigned char* lds, const Gemm g, const Sched& S, const Epi& E, const int tid) {
;     ...
;         for (int t = 0; t < nt; t += 2) {
;     ...
;             PG8_LDA(At, 1, 1); PG8_STAGE(PG8_SB(1, 0), b3, voffB); PG8_STAGE(PG8_SB(1, 1), b3 + hstep, voffB); PG8_STAGE(PG8_SA(1, 0), a3, voffA);
;             PG8_WAIT_V(8); PG8_WAIT_L(0); PG8_BAR; PG8_MMA(1, 0, At, B0); PG8_MMA(1, 1, At, B1); PG8_BAR; PG8_SCHED;
	s_add_i32 s15, s15, s56
	v_lshl_add_u64 v[220:221], v[220:221], 0, s[30:31]
	s_mov_b32 m0, s15
	ds_read_b128 v[182:185], v206 offset:49152
	ds_read_b128 v[186:189], v206 offset:50176
	ds_read_b128 v[192:195], v206 offset:51200
	ds_read_b128 v[196:199], v206 offset:52224
	ds_read_b128 v[200:203], v206 offset:53248
	ds_read_b128 v[208:211], v206 offset:54272
	ds_read_b128 v[212:215], v206 offset:55296
	ds_read_b128 v[216:219], v206 offset:56320
	global_load_lds_dwordx4 v[220:221], off
	s_add_i32 m0, s15, 0x2000
	s_add_u32 s10, s10, 0x40080
	v_lshl_add_u64 v[220:221], v[222:223], 0, s[30:31]
	s_addc_u32 s11, s11, 0
	s_add_i32 s15, s77, s56
	global_load_lds_dwordx4 v[220:221], off
	v_lshl_add_u64 v[220:221], s[10:11], 0, v[164:165]
	s_mov_b32 m0, s15
	s_nop 0
	global_load_lds_dwordx4 v[220:221], off
	v_lshl_add_u64 v[220:221], s[10:11], 0, v[168:169]
	s_add_i32 m0, s15, 0x2000
	s_nop 0
	global_load_lds_dwordx4 v[220:221], off
	v_lshl_add_u64 v[220:221], v[224:225], 0, s[30:31]
	s_mov_b32 m0, s62
	s_nop 0
	global_load_lds_dwordx4 v[220:221], off
	v_lshl_add_u64 v[220:221], v[226:227], 0, s[30:31]
	s_mov_b32 m0, s63
	s_nop 0
	global_load_lds_dwordx4 v[220:221], off
	s_waitcnt vmcnt(8)
	s_waitcnt lgkmcnt(0)
	s_barrier
	s_setprio 1
	s_waitcnt lgkmcnt(0)
	v_mfma_f32_16x16x32_bf16 v[62:65], v[130:133], v[182:185], v[62:65]
	v_mfma_f32_16x16x32_bf16 v[58:61], v[138:141], v[182:185], v[58:61]
	v_mfma_f32_16x16x32_bf16 v[46:49], v[130:133], v[192:195], v[46:49]
	v_mfma_f32_16x16x32_bf16 v[42:45], v[138:141], v[192:195], v[42:45]
	v_mfma_f32_16x16x32_bf16 v[30:33], v[130:133], v[200:203], v[30:33]
	v_mfma_f32_16x16x32_bf16 v[26:29], v[138:141], v[200:203], v[26:29]
	v_mfma_f32_16x16x32_bf16 v[14:17], v[130:133], v[212:215], v[14:17]
	v_mfma_f32_16x16x32_bf16 v[10:13], v[138:141], v[212:215], v[10:13]
	v_mfma_f32_16x16x32_bf16 v[62:65], v[134:137], v[186:189], v[62:65]
	v_mfma_f32_16x16x32_bf16 v[58:61], v[142:145], v[186:189], v[58:61]
	v_mfma_f32_16x16x32_bf16 v[46:49], v[134:137], v[196:199], v[46:49]
	v_mfma_f32_16x16x32_bf16 v[42:45], v[142:145], v[196:199], v[42:45]
	v_mfma_f32_16x16x32_bf16 v[30:33], v[134:137], v[208:211], v[30:33]
	v_mfma_f32_16x16x32_bf16 v[26:29], v[142:145], v[208:211], v[26:29]
	v_mfma_f32_16x16x32_bf16 v[14:17], v[134:137], v[216:219], v[14:17]
	v_mfma_f32_16x16x32_bf16 v[10:13], v[142:145], v[216:219], v[10:13]
	s_setprio 0
	s_setprio 1
	v_mfma_f32_16x16x32_bf16 v[54:57], v[146:149], v[182:185], v[54:57]
	v_mfma_f32_16x16x32_bf16 v[50:53], v[154:157], v[182:185], v[50:53]
	v_mfma_f32_16x16x32_bf16 v[38:41], v[146:149], v[192:195], v[38:41]
	v_mfma_f32_16x16x32_bf16 v[34:37], v[154:157], v[192:195], v[34:37]
	v_mfma_f32_16x16x32_bf16 v[22:25], v[146:149], v[200:203], v[22:25]
	v_mfma_f32_16x16x32_bf16 v[18:21], v[154:157], v[200:203], v[18:21]
	v_mfma_f32_16x16x32_bf16 v[6:9], v[146:149], v[212:215], v[6:9]
	v_mfma_f32_16x16x32_bf16 v[2:5], v[154:157], v[212:215], v[2:5]
	v_mfma_f32_16x16x32_bf16 v[54:57], v[150:153], v[186:189], v[54:57]
	v_mfma_f32_16x16x32_bf16 v[50:53], v[158:161], v[186:189], v[50:53]
	v_mfma_f32_16x16x32_bf16 v[38:41], v[150:153], v[196:199], v[38:41]
	v_mfma_f32_16x16x32_bf16 v[34:37], v[158:161], v[196:199], v[34:37]
	v_mfma_f32_16x16x32_bf16 v[22:25], v[150:153], v[208:211], v[22:25]
	v_mfma_f32_16x16x32_bf16 v[18:21], v[158:161], v[208:211], v[18:21]
	v_mfma_f32_16x16x32_bf16 v[6:9], v[150:153], v[216:219], v[6:9]
	v_mfma_f32_16x16x32_bf16 v[2:5], v[158:161], v[216:219], v[2:5]
	s_setprio 0
	s_barrier
	s_add_i32 s76, s76, 2
	s_add_u32 s48, s48, 0x100
	s_addc_u32 s49, s49, 0
	s_add_u32 s8, s8, 0x100
	s_addc_u32 s9, s9, 0

; #define PG8_BAR __builtin_amdgcn_s_barrier()
; template <class Epi, class Sched, bool ALIGN_EPI = false, bool SP2 = false>
; __device__ __forceinline__ void gemm_phase(PG8_LAS unsigned char* lds, const Gemm g, const Sched& S, const Epi& E, const int tid) {
;     ...
;         if (!has_next) break;
; #pragma unroll
;         for (int a = 0; a < 2; ++a)
; #pragma unroll
;             for (int b = 0; b < 2; ++b)
; #pragma unroll
;                 for (int m = 0; m < 4; ++m)
; #pragma unroll
;                     for (int n = 0; n < 2; ++n) acc[a][b][m][n] = (f32x4){0.f, 0.f, 0.f, 0.f};
;         cur = nxt; cA = nA; cB = nB; ++ui;
;         if constexpr (ALIGN_EPI) { if (wr == 1) PG8_BAR; }
;     }
.LBB0_1457:
	s_or_b64 exec, exec, s[6:7]
	s_andn2_b64 vcc, exec, s[4:5]
	s_mov_b64 s[4:5], -1
	s_cbranch_vccnz .LBB0_1370
	s_andn2_b64 vcc, exec, s[24:25]
	s_cbranch_vccnz .LBB0_1369
	s_mov_b32 s101, 1
	s_branch .LBB0_1369

;     __device__ __forceinline__ bool next(int i, pg8::Unit& u) const { if (!base.next(i >> 2, u)) return false; u.sub = i & 3; return true; }
;     __host__ __device__ bool next(int i, Unit& u) const {
;         const long L = (long)i * G + c; if (L >= nwg) return false;
;         int wgid = (int)L; { const int q = nwg / NXCD, r = nwg % NXCD, xcd = wgid % NXCD, off = wgid / NXCD; wgid = (xcd < r ? xcd * (q + 1) : r * (q + 1) + (xcd - r) * q) + off; }
;         const int nig = WGM * nN, gid = wgid / nig, fm = gid * WGM, gsz = (nM - fm) < WGM ? (nM - fm) : WGM;
;         u.pm = fm + ((wgid % nig) % gsz); u.pn = (wgid % nig) / gsz; u.sub = 0; return true;
; template <int STEP>
; __device__ __forceinline__ void run_step(const PT pt, unsigned char* lds, cg::grid_group& grid, XcdBarrier& bar, const int ph_lo, const int ph_hi) {
;     ...
;         } else if constexpr (ph == 1 || ph == 7) {
;             constexpr int f = ph == 7;
;             PlainOrder S; S.init(TPAD, 2 * FF, G, bid); S.A = (const char*)hb; S.Bt = (const char*)(wl + (f ? W_GU2 : W_GU1)); S.tstep = (size_t)256 * 1024 * 2;
;             pg8::Gemm g{nullptr, nullptr, TPAD, 2 * FF, 1024};
.LBB0_1523:
	s_mov_b32 s101, 0
	s_add_i32 s0, 0, 0x204b0
	s_waitcnt vmcnt(0)
	v_mov_b32_e32 v10, v190
	s_mov_b32 s25, s14
	s_mov_b32 s44, s16
	v_mov_b32_e32 v1, s0
	ds_read_b64 v[2:3], v1
	s_cmpk_gt_i32 s25, 0x10ab
	v_readfirstlane_b32 s10, v10
	s_waitcnt lgkmcnt(0)
	v_readfirstlane_b32 s3, v3
	v_readfirstlane_b32 s2, v2
	s_cbranch_scc1 .LBB0_1547
	s_ashr_i32 s45, s25, 31
	s_lshr_b32 s0, s45, 29
	s_add_i32 s6, s25, s0
	s_and_b32 s0, s6, -8
	s_sub_i32 s5, s25, s0
	s_cmp_gt_i32 s5, 3
	s_cbranch_scc0 .LBB0_1526
	s_mul_i32 s0, s5, 0x215
	s_add_i32 s4, s0, 4
	s_ashr_i32 s0, s6, 3
	s_cbranch_execz .LBB0_1527
	s_branch .LBB0_1528

;     __device__ __forceinline__ bool next(int i, pg8::Unit& u) const { if (!base.next(i >> 2, u)) return false; u.sub = i & 3; return true; }
;     __host__ __device__ bool next(int i, Unit& u) const {
;         const long L = (long)i * G + c; if (L >= nwg) return false;
;         int wgid = (int)L; { const int q = nwg / NXCD, r = nwg % NXCD, xcd = wgid % NXCD, off = wgid / NXCD; wgid = (xcd < r ? xcd * (q + 1) : r * (q + 1) + (xcd - r) * q) + off; }
;         const int nig = WGM * nN, gid = wgid / nig, fm = gid * WGM, gsz = (nM - fm) < WGM ? (nM - fm) : WGM;
;         u.pm = fm + ((wgid % nig) % gsz); u.pn = (wgid % nig) / gsz; u.sub = 0; return true;
; template <class Epi, class Sched, bool ALIGN_EPI = false, bool SP2 = false>
; __device__ __forceinline__ void gemm_phase(PG8_LAS unsigned char* lds, const Gemm g, const Sched& S, const Epi& E, const int tid) {
;     ...
;     Unit cur, nxt; int ui = 0;
;     if (!S.next(0, cur)) return;
.LBB0_1609:
	s_mov_b32 s101, 0
	s_add_i32 s0, 0, 0x204b0
	v_mov_b32_e32 v1, v190
	s_mov_b32 s48, s14
	s_mov_b32 s49, s16
	s_waitcnt vmcnt(0)
	v_mov_b32_e32 v2, s0
	ds_read_b64 v[2:3], v2
	s_cmpk_lt_i32 s48, 0x308
	s_cselect_b64 s[0:1], -1, 0
	s_cmpk_gt_i32 s48, 0x307
	v_readfirstlane_b32 s2, v1
	s_waitcnt lgkmcnt(0)
	v_readfirstlane_b32 s25, v3
	v_readfirstlane_b32 s24, v2
	s_cbranch_scc1 .LBB0_1611
	s_ashr_i32 s3, s48, 31
	s_lshr_b32 s3, s3, 29
	s_add_i32 s3, s48, s3
	s_ashr_i32 s4, s3, 3
	s_and_b32 s3, s3, -8
	s_sub_i32 s3, s48, s3
	s_cmp_lt_i32 s3, 0
	s_movk_i32 s5, 0x62
	s_cselect_b32 s5, s5, 0x61
	s_mul_i32 s3, s5, s3
	s_add_i32 s3, s3, s4
	s_ashr_i32 s4, s3, 31
	s_lshr_b32 s4, s4, 27
	s_add_i32 s4, s3, s4
	s_ashr_i32 s5, s4, 5
	s_lshl_b32 s6, s5, 3
	s_sub_i32 s5, 0xc2, s6
	s_min_u32 s7, s5, 8
	s_andn2_b32 s4, s4, 31
	s_sub_i32 s3, s3, s4
	v_cvt_f32_ubyte0_e32 v3, s7
	v_cvt_f32_i32_e32 v2, s3
	v_rcp_iflag_f32_e32 v4, v3
	s_ashr_i32 s4, s3, 30
	s_or_b32 s8, s4, 1
	v_mul_f32_e32 v4, v2, v4
	v_trunc_f32_e32 v4, v4
	v_fma_f32 v2, -v4, v3, v2
	v_cvt_i32_f32_e32 v4, v4
	v_cmp_ge_f32_e64 s[4:5], |v2|, v3
	s_and_b64 s[4:5], s[4:5], exec
	s_cselect_b32 s4, s8, 0
	v_readfirstlane_b32 s5, v4
	s_add_i32 s4, s5, s4
	s_sext_i32_i8 s46, s4
	s_mul_i32 s4, s4, s7
	s_sub_i32 s3, s3, s4
	s_sext_i32_i8 s3, s3
	s_add_i32 s44, s6, s3

;     __device__ __forceinline__ bool next(int i, pg8::Unit& u) const { if (!base.next(i >> 2, u)) return false; u.sub = i & 3; return true; }
;     __device__ __forceinline__ const float* in(int i) const { return (const float*)(const GAS float*)get(i); }
;     __device__ __forceinline__ unsigned char* ws() const { return (unsigned char*)(GAS unsigned char*)get(22); }
;     __host__ __device__ bool next(int i, Unit& u) const {
;         const long L = (long)i * G + c; if (L >= nwg) return false;
;         int wgid = (int)L; { const int q = nwg / NXCD, r = nwg % NXCD, xcd = wgid % NXCD, off = wgid / NXCD; wgid = (xcd < r ? xcd * (q + 1) : r * (q + 1) + (xcd - r) * q) + off; }
;         const int nig = WGM * nN, gid = wgid / nig, fm = gid * WGM, gsz = (nM - fm) < WGM ? (nM - fm) : WGM;
;         u.pm = fm + ((wgid % nig) % gsz); u.pn = (wgid % nig) / gsz; u.sub = 0; return true;
; template <int STEP>
; __device__ __forceinline__ void run_step(const PT pt, unsigned char* lds, cg::grid_group& grid, XcdBarrier& bar, const int ph_lo, const int ph_hi) {
;     ...
;         } else if constexpr (ph == 3) {
;             PlainOrder S; S.init(TPAD, NWIN, G, bid); S.A = (const char*)hb; S.Bt = (const char*)(wl + W_IN); S.tstep = (size_t)256 * 1024 * 2;
;             pg8::Gemm g{nullptr, nullptr, TPAD, NWIN, 1024};
;             EpiWin E{(bf16_t*)(ws + WS_Q), (bf16_t*)(ws + WS_K), (bf16_t*)(ws + WS_V), (bf16_t*)(ws + WS_CB), (bf16_t*)(ws + WS_Z), ssq,
;                      (const float*)(ws + WS_ROPE), pt.in(11) + l * 64, pt.in(12) + l * 64};
.LBB0_2313:
	s_mov_b32 s101, 0
	s_add_i32 s0, 0, 0x204b0
	s_waitcnt vmcnt(0)
	v_mov_b32_e32 v10, v190
	s_mov_b32 s44, s14
	s_mov_b32 s45, s16
	v_mov_b32_e32 v1, s0
	s_add_i32 s0, 0, 0x20458
	ds_read_b64 v[2:3], v1
	v_mov_b32_e32 v1, s0
	s_add_i32 s0, 0, 0x20460
	ds_read_b64 v[4:5], v1
	v_mov_b32_e32 v1, s0
	ds_read_b64 v[6:7], v1
	s_cmpk_lt_i32 s44, 0xda4
	s_waitcnt lgkmcnt(2)
	v_readfirstlane_b32 s1, v3
	v_readfirstlane_b32 s0, v2
	s_waitcnt lgkmcnt(1)
	v_readfirstlane_b32 s46, v5
	v_readfirstlane_b32 s47, v4
	s_waitcnt lgkmcnt(0)
	v_readfirstlane_b32 s48, v7
	v_readfirstlane_b32 s49, v6
	s_cselect_b64 s[2:3], -1, 0
	s_cmpk_gt_i32 s44, 0xda3
	v_readfirstlane_b32 s15, v10
	s_cbranch_scc1 .LBB0_2319
	s_ashr_i32 s4, s44, 31
	s_lshr_b32 s4, s4, 29
	s_add_i32 s7, s44, s4
	s_and_b32 s4, s7, -8
	s_sub_i32 s6, s44, s4
	s_cmp_gt_i32 s6, 3
	s_cbranch_scc0 .LBB0_2316
	s_mul_i32 s4, s6, 0x1b4
	s_add_i32 s8, s4, 4
	s_ashr_i32 s4, s7, 3
	s_cbranch_execz .LBB0_2317
	s_branch .LBB0_2318

;     __device__ __forceinline__ bool next(int i, pg8::Unit& u) const { if (!base.next(i >> 2, u)) return false; u.sub = i & 3; return true; }
;     __host__ __device__ bool next(int i, Unit& u) const {
;         const long L = (long)i * G + c; if (L >= nwg) return false;
;         int wgid = (int)L; { const int q = nwg / NXCD, r = nwg % NXCD, xcd = wgid % NXCD, off = wgid / NXCD; wgid = (xcd < r ? xcd * (q + 1) : r * (q + 1) + (xcd - r) * q) + off; }
;         const int nig = WGM * nN, gid = wgid / nig, fm = gid * WGM, gsz = (nM - fm) < WGM ? (nM - fm) : WGM;
;         u.pm = fm + ((wgid % nig) % gsz); u.pn = (wgid % nig) / gsz; u.sub = 0; return true;
; template <class Epi, class Sched, bool ALIGN_EPI = false, bool SP2 = false>
; __device__ __forceinline__ void gemm_phase(PG8_LAS unsigned char* lds, const Gemm g, const Sched& S, const Epi& E, const int tid) {
;     ...
;     Unit cur, nxt; int ui = 0;
;     if (!S.next(0, cur)) return;
.LBB0_5205:
	s_mov_b32 s101, 0
	s_add_i32 s0, 0, 0x204b0
	s_waitcnt vmcnt(0)
	v_mov_b32_e32 v10, v190
	s_mov_b32 s46, s14
	s_mov_b32 s47, s16
	v_mov_b32_e32 v1, s0
	ds_read_b64 v[2:3], v1
	s_cmpk_lt_i32 s46, 0x308
	s_cselect_b64 s[0:1], -1, 0
	s_cmpk_gt_i32 s46, 0x307
	v_readfirstlane_b32 s2, v10
	s_waitcnt lgkmcnt(0)
	v_readfirstlane_b32 s3, v3
	v_readfirstlane_b32 s4, v2
	s_cbranch_scc1 .LBB0_5207
	s_ashr_i32 s5, s46, 31
	s_lshr_b32 s5, s5, 29
	s_add_i32 s5, s46, s5
	s_ashr_i32 s6, s5, 3
	s_and_b32 s5, s5, -8
	s_sub_i32 s5, s46, s5
	s_cmp_lt_i32 s5, 0
	s_movk_i32 s7, 0x62
	s_cselect_b32 s7, s7, 0x61
	s_mul_i32 s5, s7, s5
	s_add_i32 s5, s5, s6
	s_ashr_i32 s6, s5, 31
	s_lshr_b32 s6, s6, 27
	s_add_i32 s6, s5, s6
	s_ashr_i32 s7, s6, 5
	s_lshl_b32 s8, s7, 3
	s_sub_i32 s7, 0xc2, s8
	s_min_u32 s9, s7, 8
	s_andn2_b32 s6, s6, 31
	s_sub_i32 s5, s5, s6
	v_cvt_f32_ubyte0_e32 v2, s9
	v_cvt_f32_i32_e32 v1, s5
	v_rcp_iflag_f32_e32 v3, v2
	s_ashr_i32 s6, s5, 30
	s_or_b32 s10, s6, 1
	v_mul_f32_e32 v3, v1, v3
	v_trunc_f32_e32 v3, v3
	v_fma_f32 v1, -v3, v2, v1
	v_cvt_i32_f32_e32 v3, v3
	v_cmp_ge_f32_e64 s[6:7], |v1|, v2
	s_and_b64 s[6:7], s[6:7], exec
	s_cselect_b32 s6, s10, 0
	v_readfirstlane_b32 s7, v3
	s_add_i32 s6, s7, s6
	s_sext_i32_i8 s44, s6
	s_mul_i32 s6, s6, s9
	s_sub_i32 s5, s5, s6
	s_sext_i32_i8 s5, s5
	s_add_i32 s42, s8, s5

; #define PG8_STAGE(bufoff, gbase, voff) do { _Pragma("unroll") for (int _i = 0; _i < 2; ++_i) \
;         __builtin_amdgcn_global_load_lds((const unsigned*)((const char*)(gbase) + (voff)[_i]), (PG8_LAS unsigned*)(lds + (bufoff) + ldsw + _i * 8192), 16, 0, 0); } while (0)
; #define PG8_LDA(dst, b, h) do { _Pragma("unroll") for (int m = 0; m < 4; ++m) _Pragma("unroll") for (int k = 0; k < 2; ++k) dst[m][k] = *(const PG8_LAS bf16x8*)(lds + PG8_SA(b, h) + aoff + m * 2048 + k * 1024); } while (0)
; #define PG8_LDB(dst, b, h) do { _Pragma("unroll") for (int n = 0; n < 2; ++n) _Pragma("unroll") for (int k = 0; k < 2; ++k) dst[n][k] = *(const PG8_LAS bf16x8*)(lds + PG8_SB(b, h) + boff + n * 2048 + k * 1024); } while (0)
; #define PG8_WAIT_V(n) asm volatile("s_waitcnt vmcnt(" #n ")" ::: "memory")
; #define PG8_WAIT_L(n) asm volatile("s_waitcnt lgkmcnt(" #n ")" ::: "memory")
; #define PG8_BAR __builtin_amdgcn_s_barrier()
; #define PG8_SCHED __builtin_amdgcn_sched_barrier(0)
; template <class Epi, class Sched, bool ALIGN_EPI = false, bool SP2 = false>
; __device__ __forceinline__ void gemm_phase(PG8_LAS unsigned char* lds, const Gemm g, const Sched& S, const Epi& E, const int tid) {
;     ...
;         const bool has_next = S.next(ui + 1, nxt);
;         const char* nA = has_next ? S.aptr(nxt) : cA; const char* nB = has_next ? S.bptr(nxt) : cB;
;         for (int t = 0; t < nt; t += 2) {
;             const bool last = (t == nt - 2);
;             const char* a1 = cA + (size_t)(t + 1) * kstep;
;             const char* a2 = last ? nA : cA + (size_t)(t + 2) * kstep; const char* b2 = last ? nB : cB + (size_t)(t + 2) * kstep;
;             const char* a3 = a2 + kstep; const char* b3 = b2 + kstep;
;             if (last && has_next) S.a_ready(nxt);
;             if constexpr (SP2) {
;             PG8_LDB(B0, 0, 0); PG8_LDB(B1, 0, 1); PG8_SCHED; PG8_LDA(At, 0, 0); PG8_STAGE(PG8_SA(1, 1), a1 + hstep, voffA);
;             PG8_WAIT_V(8); PG8_WAIT_L(0); PG8_BAR; PG8_MMA(0, 0, At, B0); PG8_MMA(0, 1, At, B1); PG8_BAR; PG8_SCHED;
;             PG8_LDA(At, 0, 1); PG8_STAGE(PG8_SB(0, 0), b2, voffB); PG8_STAGE(PG8_SB(0, 1), b2 + hstep, voffB); PG8_STAGE(PG8_SA(0, 0), a2, voffA);
;             PG8_WAIT_V(8); PG8_WAIT_L(0); PG8_BAR; PG8_MMA(1, 0, At, B0); PG8_MMA(1, 1, At, B1); PG8_BAR; PG8_SCHED;
.LBB0_5219:
	s_add_u32 s43, s8, 0x100
	s_addc_u32 s45, s9, 0
	s_mov_b32 s74, -2
	s_cmp_eq_u32 s101, 0
	s_cbranch_scc1 .Lnobar22
	s_barrier
.Lnobar22:
	ds_read_b128 v[130:133], v204
	ds_read_b128 v[134:137], v204 offset:1024
	ds_read_b128 v[138:141], v204 offset:2048
	ds_read_b128 v[142:145], v204 offset:3072
	ds_read_b128 v[146:149], v205
	ds_read_b128 v[150:153], v205 offset:1024
	ds_read_b128 v[154:157], v205 offset:2048
	ds_read_b128 v[158:161], v205 offset:3072
	s_add_u32 s8, s6, 0x100
	s_addc_u32 s9, s7, 0
	s_cmp_eq_u32 s74, 40
	s_cselect_b32 s41, s1, s9
	s_cselect_b32 s40, s0, s8
	s_cselect_b32 s11, s39, s45
	s_cselect_b32 s10, s38, s43
	v_lshl_add_u64 v[220:221], s[6:7], 0, v[176:177]
	s_add_i32 m0, s53, 0xc000
	ds_read_b128 v[182:185], v206
	ds_read_b128 v[186:189], v206 offset:1024
	ds_read_b128 v[192:195], v206 offset:2048
	ds_read_b128 v[196:199], v206 offset:3072
	ds_read_b128 v[200:203], v206 offset:4096
	ds_read_b128 v[208:211], v206 offset:5120
	ds_read_b128 v[212:215], v206 offset:6144
	ds_read_b128 v[216:219], v206 offset:7168
	global_load_lds_dwordx4 v[220:221], off
	v_lshl_add_u64 v[220:221], s[6:7], 0, v[174:175]
	s_add_i32 m0, s53, 0xe000
	s_nop 0
	global_load_lds_dwordx4 v[220:221], off
	s_waitcnt vmcnt(8)
	s_waitcnt lgkmcnt(0)
	s_barrier
	s_setprio 1
	s_waitcnt lgkmcnt(0)
	v_mfma_f32_16x16x32_bf16 v[126:129], v[130:133], v[182:185], 0
	v_mfma_f32_16x16x32_bf16 v[122:125], v[138:141], v[182:185], 0
	v_mfma_f32_16x16x32_bf16 v[110:113], v[130:133], v[192:195], 0
	v_mfma_f32_16x16x32_bf16 v[106:109], v[138:141], v[192:195], 0
	v_mfma_f32_16x16x32_bf16 v[94:97], v[130:133], v[200:203], 0
	v_mfma_f32_16x16x32_bf16 v[90:93], v[138:141], v[200:203], 0
	v_mfma_f32_16x16x32_bf16 v[78:81], v[130:133], v[212:215], 0
	v_mfma_f32_16x16x32_bf16 v[74:77], v[138:141], v[212:215], 0
	v_mfma_f32_16x16x32_bf16 v[126:129], v[134:137], v[186:189], v[126:129]
	v_mfma_f32_16x16x32_bf16 v[122:125], v[142:145], v[186:189], v[122:125]
	v_mfma_f32_16x16x32_bf16 v[110:113], v[134:137], v[196:199], v[110:113]
	v_mfma_f32_16x16x32_bf16 v[106:109], v[142:145], v[196:199], v[106:109]
	v_mfma_f32_16x16x32_bf16 v[94:97], v[134:137], v[208:211], v[94:97]
	v_mfma_f32_16x16x32_bf16 v[90:93], v[142:145], v[208:211], v[90:93]
	v_mfma_f32_16x16x32_bf16 v[78:81], v[134:137], v[216:219], v[78:81]
	v_mfma_f32_16x16x32_bf16 v[74:77], v[142:145], v[216:219], v[74:77]
	s_setprio 0
	s_setprio 1
	v_mfma_f32_16x16x32_bf16 v[118:121], v[146:149], v[182:185], 0
	v_mfma_f32_16x16x32_bf16 v[114:117], v[154:157], v[182:185], 0
	v_mfma_f32_16x16x32_bf16 v[102:105], v[146:149], v[192:195], 0
	v_mfma_f32_16x16x32_bf16 v[98:101], v[154:157], v[192:195], 0
	v_mfma_f32_16x16x32_bf16 v[86:89], v[146:149], v[200:203], 0
	v_mfma_f32_16x16x32_bf16 v[82:85], v[154:157], v[200:203], 0
	v_mfma_f32_16x16x32_bf16 v[70:73], v[146:149], v[212:215], 0
	v_mfma_f32_16x16x32_bf16 v[66:69], v[154:157], v[212:215], 0
	v_mfma_f32_16x16x32_bf16 v[118:121], v[150:153], v[186:189], v[118:121]
	v_mfma_f32_16x16x32_bf16 v[114:117], v[158:161], v[186:189], v[114:117]
	v_mfma_f32_16x16x32_bf16 v[102:105], v[150:153], v[196:199], v[102:105]
	v_mfma_f32_16x16x32_bf16 v[98:101], v[158:161], v[196:199], v[98:101]
	v_mfma_f32_16x16x32_bf16 v[86:89], v[150:153], v[208:211], v[86:89]
	v_mfma_f32_16x16x32_bf16 v[82:85], v[158:161], v[208:211], v[82:85]
	v_mfma_f32_16x16x32_bf16 v[70:73], v[150:153], v[216:219], v[70:73]
	v_mfma_f32_16x16x32_bf16 v[66:69], v[158:161], v[216:219], v[66:69]
	s_setprio 0
	s_barrier
	s_add_i32 s6, s63, s52
	v_lshl_add_u64 v[220:221], s[10:11], 0, v[164:165]
	s_mov_b32 m0, s6
	ds_read_b128 v[182:185], v206 offset:16384
	ds_read_b128 v[186:189], v206 offset:17408
	ds_read_b128 v[192:195], v206 offset:18432
	ds_read_b128 v[196:199], v206 offset:19456
	ds_read_b128 v[200:203], v206 offset:20480
	ds_read_b128 v[208:211], v206 offset:21504
	ds_read_b128 v[212:215], v206 offset:22528
	ds_read_b128 v[216:219], v206 offset:23552
	global_load_lds_dwordx4 v[220:221], off
	s_add_i32 m0, s6, 0x2000
	s_add_u32 s6, s10, 0xb0000
	v_lshl_add_u64 v[222:223], s[10:11], 0, v[168:169]
	s_addc_u32 s7, s11, 0
	s_add_i32 s15, s64, s52
	global_load_lds_dwordx4 v[222:223], off
	v_lshl_add_u64 v[224:225], s[6:7], 0, v[164:165]
	s_mov_b32 m0, s15
	v_lshl_add_u64 v[226:227], s[40:41], 0, v[166:167]
	global_load_lds_dwordx4 v[224:225], off
	v_lshl_add_u64 v[224:225], s[6:7], 0, v[168:169]
	s_add_i32 m0, s15, 0x2000
	s_nop 0
	global_load_lds_dwordx4 v[224:225], off
	v_lshl_add_u64 v[224:225], s[40:41], 0, v[162:163]
	s_mov_b32 m0, s53
	s_nop 0
	global_load_lds_dwordx4 v[224:225], off
	s_mov_b32 m0, s54
	s_nop 0
	global_load_lds_dwordx4 v[226:227], off
	s_waitcnt vmcnt(8)
	s_waitcnt lgkmcnt(0)
	s_barrier
; #define PG8_STAGE(bufoff, gbase, voff) do { _Pragma("unroll") for (int _i = 0; _i < 2; ++_i) \
;         __builtin_amdgcn_global_load_lds((const unsigned*)((const char*)(gbase) + (voff)[_i]), (PG8_LAS unsigned*)(lds + (bufoff) + ldsw + _i * 8192), 16, 0, 0); } while (0)
; #define PG8_LDA(dst, b, h) do { _Pragma("unroll") for (int m = 0; m < 4; ++m) _Pragma("unroll") for (int k = 0; k < 2; ++k) dst[m][k] = *(const PG8_LAS bf16x8*)(lds + PG8_SA(b, h) + aoff + m * 2048 + k * 1024); } while (0)
; #define PG8_LDB(dst, b, h) do { _Pragma("unroll") for (int n = 0; n < 2; ++n) _Pragma("unroll") for (int k = 0; k < 2; ++k) dst[n][k] = *(const PG8_LAS bf16x8*)(lds + PG8_SB(b, h) + boff + n * 2048 + k * 1024); } while (0)
; #define PG8_MMA(ai, bj, At, Bt) do { __builtin_amdgcn_s_setprio(1); _Pragma("unroll") for (int m = 0; m < 4; ++m) _Pragma("unroll") for (int n = 0; n < 2; ++n) _Pragma("unroll") for (int k = 0; k < 2; ++k) \
;         acc[ai][bj][m][n] = __builtin_amdgcn_mfma_f32_16x16x32_bf16(Bt[n][k], At[m][k], acc[ai][bj][m][n], 0, 0, 0); __builtin_amdgcn_s_setprio(0); } while (0)
; #define PG8_WAIT_V(n) asm volatile("s_waitcnt vmcnt(" #n ")" ::: "memory")
; #define PG8_WAIT_L(n) asm volatile("s_waitcnt lgkmcnt(" #n ")" ::: "memory")
; #define PG8_BAR __builtin_amdgcn_s_barrier()
; #define PG8_SCHED __builtin_amdgcn_sched_barrier(0)
; template <class Epi, class Sched, bool ALIGN_EPI = false, bool SP2 = false>
; __device__ __forceinline__ void gemm_phase(PG8_LAS unsigned char* lds, const Gemm g, const Sched& S, const Epi& E, const int tid) {
;     ...
;             PG8_WAIT_V(8); PG8_WAIT_L(0); PG8_BAR; PG8_MMA(1, 0, At, B0); PG8_MMA(1, 1, At, B1); PG8_BAR; PG8_SCHED;
;             PG8_LDB(B0, 1, 0); PG8_LDB(B1, 1, 1); PG8_SCHED; PG8_LDA(At, 1, 0); PG8_STAGE(PG8_SA(0, 1), a2 + hstep, voffA);
;             PG8_WAIT_V(8); PG8_WAIT_L(0); PG8_BAR; PG8_MMA(0, 0, At, B0); PG8_MMA(0, 1, At, B1); PG8_BAR; PG8_SCHED;
	s_setprio 1
	s_waitcnt lgkmcnt(0)
	v_mfma_f32_16x16x32_bf16 v[62:65], v[130:133], v[182:185], 0
	v_mfma_f32_16x16x32_bf16 v[58:61], v[138:141], v[182:185], 0
	v_mfma_f32_16x16x32_bf16 v[46:49], v[130:133], v[192:195], 0
	v_mfma_f32_16x16x32_bf16 v[42:45], v[138:141], v[192:195], 0
	v_mfma_f32_16x16x32_bf16 v[30:33], v[130:133], v[200:203], 0
	v_mfma_f32_16x16x32_bf16 v[26:29], v[138:141], v[200:203], 0
	v_mfma_f32_16x16x32_bf16 v[14:17], v[130:133], v[212:215], 0
	v_mfma_f32_16x16x32_bf16 v[10:13], v[138:141], v[212:215], 0
	v_mfma_f32_16x16x32_bf16 v[62:65], v[134:137], v[186:189], v[62:65]
	v_mfma_f32_16x16x32_bf16 v[58:61], v[142:145], v[186:189], v[58:61]
	v_mfma_f32_16x16x32_bf16 v[46:49], v[134:137], v[196:199], v[46:49]
	v_mfma_f32_16x16x32_bf16 v[42:45], v[142:145], v[196:199], v[42:45]
	v_mfma_f32_16x16x32_bf16 v[30:33], v[134:137], v[208:211], v[30:33]
	v_mfma_f32_16x16x32_bf16 v[26:29], v[142:145], v[208:211], v[26:29]
	v_mfma_f32_16x16x32_bf16 v[14:17], v[134:137], v[216:219], v[14:17]
	v_mfma_f32_16x16x32_bf16 v[10:13], v[142:145], v[216:219], v[10:13]
	s_setprio 0
	s_setprio 1
	v_mfma_f32_16x16x32_bf16 v[54:57], v[146:149], v[182:185], 0
	v_mfma_f32_16x16x32_bf16 v[50:53], v[154:157], v[182:185], 0
	v_mfma_f32_16x16x32_bf16 v[38:41], v[146:149], v[192:195], 0
	v_mfma_f32_16x16x32_bf16 v[34:37], v[154:157], v[192:195], 0
	v_mfma_f32_16x16x32_bf16 v[22:25], v[146:149], v[200:203], 0
	v_mfma_f32_16x16x32_bf16 v[18:21], v[154:157], v[200:203], 0
	v_mfma_f32_16x16x32_bf16 v[6:9], v[146:149], v[212:215], 0
	v_mfma_f32_16x16x32_bf16 v[2:5], v[154:157], v[212:215], 0
	v_mfma_f32_16x16x32_bf16 v[54:57], v[150:153], v[186:189], v[54:57]
	v_mfma_f32_16x16x32_bf16 v[50:53], v[158:161], v[186:189], v[50:53]
	v_mfma_f32_16x16x32_bf16 v[38:41], v[150:153], v[196:199], v[38:41]
	v_mfma_f32_16x16x32_bf16 v[34:37], v[158:161], v[196:199], v[34:37]
	v_mfma_f32_16x16x32_bf16 v[22:25], v[150:153], v[208:211], v[22:25]
	v_mfma_f32_16x16x32_bf16 v[18:21], v[158:161], v[208:211], v[18:21]
	v_mfma_f32_16x16x32_bf16 v[6:9], v[150:153], v[216:219], v[6:9]
	v_mfma_f32_16x16x32_bf16 v[2:5], v[158:161], v[216:219], v[2:5]
	s_setprio 0
	s_barrier
	s_add_i32 s15, 0, 0x18000
	s_add_i32 s18, 0, 0x1c000
	v_add_u32_e32 v142, s15, v191
	v_add_u32_e32 v158, s18, v191
	ds_read_b128 v[130:133], v142
	ds_read_b128 v[134:137], v142 offset:1024
	ds_read_b128 v[138:141], v142 offset:2048
	ds_read_b128 v[142:145], v142 offset:3072
	ds_read_b128 v[146:149], v158
	ds_read_b128 v[150:153], v158 offset:1024
	ds_read_b128 v[154:157], v158 offset:2048
	ds_read_b128 v[158:161], v158 offset:3072
	s_add_u32 s6, s40, 0xb0000
	s_addc_u32 s7, s41, 0
	s_mov_b32 m0, s55
	v_lshl_add_u64 v[228:229], s[6:7], 0, v[162:163]
	ds_read_b128 v[182:185], v206 offset:32768
	ds_read_b128 v[186:189], v206 offset:33792
	ds_read_b128 v[192:195], v206 offset:34816
	ds_read_b128 v[196:199], v206 offset:35840
	ds_read_b128 v[200:203], v206 offset:36864
	ds_read_b128 v[208:211], v206 offset:37888
	ds_read_b128 v[212:215], v206 offset:38912
	ds_read_b128 v[216:219], v206 offset:39936
	global_load_lds_dwordx4 v[228:229], off
	v_lshl_add_u64 v[228:229], s[6:7], 0, v[166:167]
	s_mov_b32 m0, s56
	s_nop 0
	global_load_lds_dwordx4 v[228:229], off
	s_waitcnt vmcnt(8)
	s_waitcnt lgkmcnt(0)
	s_barrier
	s_setprio 1
	s_waitcnt lgkmcnt(0)
	v_mfma_f32_16x16x32_bf16 v[126:129], v[130:133], v[182:185], v[126:129]
	v_mfma_f32_16x16x32_bf16 v[122:125], v[138:141], v[182:185], v[122:125]
	v_mfma_f32_16x16x32_bf16 v[110:113], v[130:133], v[192:195], v[110:113]
	v_mfma_f32_16x16x32_bf16 v[106:109], v[138:141], v[192:195], v[106:109]
	v_mfma_f32_16x16x32_bf16 v[94:97], v[130:133], v[200:203], v[94:97]
	v_mfma_f32_16x16x32_bf16 v[90:93], v[138:141], v[200:203], v[90:93]
	v_mfma_f32_16x16x32_bf16 v[78:81], v[130:133], v[212:215], v[78:81]
	v_mfma_f32_16x16x32_bf16 v[74:77], v[138:141], v[212:215], v[74:77]
	v_mfma_f32_16x16x32_bf16 v[126:129], v[134:137], v[186:189], v[126:129]
	v_mfma_f32_16x16x32_bf16 v[122:125], v[142:145], v[186:189], v[122:125]
	v_mfma_f32_16x16x32_bf16 v[110:113], v[134:137], v[196:199], v[110:113]
	v_mfma_f32_16x16x32_bf16 v[106:109], v[142:145], v[196:199], v[106:109]
	v_mfma_f32_16x16x32_bf16 v[94:97], v[134:137], v[208:211], v[94:97]
	v_mfma_f32_16x16x32_bf16 v[90:93], v[142:145], v[208:211], v[90:93]
	v_mfma_f32_16x16x32_bf16 v[78:81], v[134:137], v[216:219], v[78:81]
	v_mfma_f32_16x16x32_bf16 v[74:77], v[142:145], v[216:219], v[74:77]
	s_setprio 0
	s_setprio 1
	v_mfma_f32_16x16x32_bf16 v[118:121], v[146:149], v[182:185], v[118:121]
	v_mfma_f32_16x16x32_bf16 v[114:117], v[154:157], v[182:185], v[114:117]
	v_mfma_f32_16x16x32_bf16 v[102:105], v[146:149], v[192:195], v[102:105]
	v_mfma_f32_16x16x32_bf16 v[98:101], v[154:157], v[192:195], v[98:101]
	v_mfma_f32_16x16x32_bf16 v[86:89], v[146:149], v[200:203], v[86:89]
	v_mfma_f32_16x16x32_bf16 v[82:85], v[154:157], v[200:203], v[82:85]
	v_mfma_f32_16x16x32_bf16 v[70:73], v[146:149], v[212:215], v[70:73]
	v_mfma_f32_16x16x32_bf16 v[66:69], v[154:157], v[212:215], v[66:69]
	v_mfma_f32_16x16x32_bf16 v[118:121], v[150:153], v[186:189], v[118:121]
	v_mfma_f32_16x16x32_bf16 v[114:117], v[158:161], v[186:189], v[114:117]
	v_mfma_f32_16x16x32_bf16 v[102:105], v[150:153], v[196:199], v[102:105]
	v_mfma_f32_16x16x32_bf16 v[98:101], v[158:161], v[196:199], v[98:101]
	v_mfma_f32_16x16x32_bf16 v[86:89], v[150:153], v[208:211], v[86:89]
	v_mfma_f32_16x16x32_bf16 v[82:85], v[158:161], v[208:211], v[82:85]
	v_mfma_f32_16x16x32_bf16 v[70:73], v[150:153], v[216:219], v[70:73]
	v_mfma_f32_16x16x32_bf16 v[66:69], v[158:161], v[216:219], v[66:69]
	s_setprio 0
	s_barrier
; #define PG8_STAGE(bufoff, gbase, voff) do { _Pragma("unroll") for (int _i = 0; _i < 2; ++_i) \
;         __builtin_amdgcn_global_load_lds((const unsigned*)((const char*)(gbase) + (voff)[_i]), (PG8_LAS unsigned*)(lds + (bufoff) + ldsw + _i * 8192), 16, 0, 0); } while (0)
; #define PG8_LDA(dst, b, h) do { _Pragma("unroll") for (int m = 0; m < 4; ++m) _Pragma("unroll") for (int k = 0; k < 2; ++k) dst[m][k] = *(const PG8_LAS bf16x8*)(lds + PG8_SA(b, h) + aoff + m * 2048 + k * 1024); } while (0)
; #define PG8_MMA(ai, bj, At, Bt) do { __builtin_amdgcn_s_setprio(1); _Pragma("unroll") for (int m = 0; m < 4; ++m) _Pragma("unroll") for (int n = 0; n < 2; ++n) _Pragma("unroll") for (int k = 0; k < 2; ++k) \
;         acc[ai][bj][m][n] = __builtin_amdgcn_mfma_f32_16x16x32_bf16(Bt[n][k], At[m][k], acc[ai][bj][m][n], 0, 0, 0); __builtin_amdgcn_s_setprio(0); } while (0)
; #define PG8_WAIT_V(n) asm volatile("s_waitcnt vmcnt(" #n ")" ::: "memory")
; #define PG8_WAIT_L(n) asm volatile("s_waitcnt lgkmcnt(" #n ")" ::: "memory")
; #define PG8_BAR __builtin_amdgcn_s_barrier()
; #define PG8_SCHED __builtin_amdgcn_sched_barrier(0)
; template <class Epi, class Sched, bool ALIGN_EPI = false, bool SP2 = false>
; __device__ __forceinline__ void gemm_phase(PG8_LAS unsigned char* lds, const Gemm g, const Sched& S, const Epi& E, const int tid) {
;     ...
;         for (int t = 0; t < nt; t += 2) {
;     ...
;             PG8_LDA(At, 1, 1); PG8_STAGE(PG8_SB(1, 0), b3, voffB); PG8_STAGE(PG8_SB(1, 1), b3 + hstep, voffB); PG8_STAGE(PG8_SA(1, 0), a3, voffA);
;             PG8_WAIT_V(8); PG8_WAIT_L(0); PG8_BAR; PG8_MMA(1, 0, At, B0); PG8_MMA(1, 1, At, B1); PG8_BAR; PG8_SCHED;
	s_add_i32 s6, s15, s52
	v_lshl_add_u64 v[220:221], v[220:221], 0, s[34:35]
	s_mov_b32 m0, s6
	ds_read_b128 v[182:185], v206 offset:49152
	ds_read_b128 v[186:189], v206 offset:50176
	ds_read_b128 v[192:195], v206 offset:51200
	ds_read_b128 v[196:199], v206 offset:52224
	ds_read_b128 v[200:203], v206 offset:53248
	ds_read_b128 v[208:211], v206 offset:54272
	ds_read_b128 v[212:215], v206 offset:55296
	ds_read_b128 v[216:219], v206 offset:56320
	global_load_lds_dwordx4 v[220:221], off
	s_add_i32 m0, s6, 0x2000
	s_add_u32 s6, s10, 0xb0080
	v_lshl_add_u64 v[220:221], v[222:223], 0, s[34:35]
	s_addc_u32 s7, s11, 0
	s_add_i32 s10, s18, s52
	global_load_lds_dwordx4 v[220:221], off
	v_lshl_add_u64 v[220:221], s[6:7], 0, v[164:165]
	s_mov_b32 m0, s10
	s_nop 0
	global_load_lds_dwordx4 v[220:221], off
	v_lshl_add_u64 v[220:221], s[6:7], 0, v[168:169]
	s_add_i32 m0, s10, 0x2000
	s_nop 0
	global_load_lds_dwordx4 v[220:221], off
	v_lshl_add_u64 v[220:221], v[224:225], 0, s[34:35]
	s_mov_b32 m0, s58
	s_nop 0
	global_load_lds_dwordx4 v[220:221], off
	v_lshl_add_u64 v[220:221], v[226:227], 0, s[34:35]
	s_mov_b32 m0, s59
	s_nop 0
	global_load_lds_dwordx4 v[220:221], off
	s_waitcnt vmcnt(8)
	s_waitcnt lgkmcnt(0)
	s_barrier
	s_setprio 1
	s_waitcnt lgkmcnt(0)
	v_mfma_f32_16x16x32_bf16 v[62:65], v[130:133], v[182:185], v[62:65]
	v_mfma_f32_16x16x32_bf16 v[58:61], v[138:141], v[182:185], v[58:61]
	v_mfma_f32_16x16x32_bf16 v[46:49], v[130:133], v[192:195], v[46:49]
	v_mfma_f32_16x16x32_bf16 v[42:45], v[138:141], v[192:195], v[42:45]
	v_mfma_f32_16x16x32_bf16 v[30:33], v[130:133], v[200:203], v[30:33]
	v_mfma_f32_16x16x32_bf16 v[26:29], v[138:141], v[200:203], v[26:29]
	v_mfma_f32_16x16x32_bf16 v[14:17], v[130:133], v[212:215], v[14:17]
	v_mfma_f32_16x16x32_bf16 v[10:13], v[138:141], v[212:215], v[10:13]
	v_mfma_f32_16x16x32_bf16 v[62:65], v[134:137], v[186:189], v[62:65]
	v_mfma_f32_16x16x32_bf16 v[58:61], v[142:145], v[186:189], v[58:61]
	v_mfma_f32_16x16x32_bf16 v[46:49], v[134:137], v[196:199], v[46:49]
	v_mfma_f32_16x16x32_bf16 v[42:45], v[142:145], v[196:199], v[42:45]
	v_mfma_f32_16x16x32_bf16 v[30:33], v[134:137], v[208:211], v[30:33]
	v_mfma_f32_16x16x32_bf16 v[26:29], v[142:145], v[208:211], v[26:29]
	v_mfma_f32_16x16x32_bf16 v[14:17], v[134:137], v[216:219], v[14:17]
	v_mfma_f32_16x16x32_bf16 v[10:13], v[142:145], v[216:219], v[10:13]
	s_setprio 0
	s_setprio 1
	v_mfma_f32_16x16x32_bf16 v[54:57], v[146:149], v[182:185], v[54:57]
	v_mfma_f32_16x16x32_bf16 v[50:53], v[154:157], v[182:185], v[50:53]
	v_mfma_f32_16x16x32_bf16 v[38:41], v[146:149], v[192:195], v[38:41]
	v_mfma_f32_16x16x32_bf16 v[34:37], v[154:157], v[192:195], v[34:37]
	v_mfma_f32_16x16x32_bf16 v[22:25], v[146:149], v[200:203], v[22:25]
	v_mfma_f32_16x16x32_bf16 v[18:21], v[154:157], v[200:203], v[18:21]
	v_mfma_f32_16x16x32_bf16 v[6:9], v[146:149], v[212:215], v[6:9]
	v_mfma_f32_16x16x32_bf16 v[2:5], v[154:157], v[212:215], v[2:5]
	v_mfma_f32_16x16x32_bf16 v[54:57], v[150:153], v[186:189], v[54:57]
	v_mfma_f32_16x16x32_bf16 v[50:53], v[158:161], v[186:189], v[50:53]
	v_mfma_f32_16x16x32_bf16 v[38:41], v[150:153], v[196:199], v[38:41]
	v_mfma_f32_16x16x32_bf16 v[34:37], v[158:161], v[196:199], v[34:37]
	v_mfma_f32_16x16x32_bf16 v[22:25], v[150:153], v[208:211], v[22:25]
	v_mfma_f32_16x16x32_bf16 v[18:21], v[158:161], v[208:211], v[18:21]
	v_mfma_f32_16x16x32_bf16 v[6:9], v[150:153], v[216:219], v[6:9]
	v_mfma_f32_16x16x32_bf16 v[2:5], v[158:161], v[216:219], v[2:5]
	s_setprio 0
	s_barrier
	s_add_i32 s74, s74, 2
	s_add_u32 s43, s43, 0x100
	s_addc_u32 s45, s45, 0
	s_mov_b64 s[6:7], s[8:9]

; #define PG8_BAR __builtin_amdgcn_s_barrier()
; template <class Epi, class Sched, bool ALIGN_EPI = false, bool SP2 = false>
; __device__ __forceinline__ void gemm_phase(PG8_LAS unsigned char* lds, const Gemm g, const Sched& S, const Epi& E, const int tid) {
;     ...
;         if (!has_next) break;
; #pragma unroll
;         for (int a = 0; a < 2; ++a)
; #pragma unroll
;             for (int b = 0; b < 2; ++b)
; #pragma unroll
;                 for (int m = 0; m < 4; ++m)
; #pragma unroll
;                     for (int n = 0; n < 2; ++n) acc[a][b][m][n] = (f32x4){0.f, 0.f, 0.f, 0.f};
;         cur = nxt; cA = nA; cB = nB; ++ui;
;         if constexpr (ALIGN_EPI) { if (wr == 1) PG8_BAR; }
;     }
.LBB0_5303:
	s_or_b64 exec, exec, s[6:7]
	s_and_b64 vcc, exec, s[4:5]
	s_mov_b64 s[4:5], -1
	s_cbranch_vccnz .LBB0_5212
	s_andn2_b64 vcc, exec, s[26:27]
	s_cbranch_vccnz .LBB0_5211
	s_mov_b32 s101, 1
	s_branch .LBB0_5211

;     __device__ __forceinline__ bool next(int i, pg8::Unit& u) const { if (!base.next(i >> 2, u)) return false; u.sub = i & 3; return true; }
;     __host__ __device__ bool next(int i, Unit& u) const {
;         const long L = (long)i * G + c; if (L >= nwg) return false;
;         int wgid = (int)L; { const int q = nwg / NXCD, r = nwg % NXCD, xcd = wgid % NXCD, off = wgid / NXCD; wgid = (xcd < r ? xcd * (q + 1) : r * (q + 1) + (xcd - r) * q) + off; }
;         const int nig = WGM * nN, gid = wgid / nig, fm = gid * WGM, gsz = (nM - fm) < WGM ? (nM - fm) : WGM;
;         u.pm = fm + ((wgid % nig) % gsz); u.pn = (wgid % nig) / gsz; u.sub = 0; return true;
; template <class Epi, class Sched, bool ALIGN_EPI = false, bool SP2 = false>
; __device__ __forceinline__ void gemm_phase(PG8_LAS unsigned char* lds, const Gemm g, const Sched& S, const Epi& E, const int tid) {
;     ...
;     Unit cur, nxt; int ui = 0;
;     if (!S.next(0, cur)) return;
.LBB0_5740:
	s_mov_b32 s101, 0
	s_add_i32 s0, 0, 0x204b0
	s_waitcnt vmcnt(0)
	v_mov_b32_e32 v2, v190
	s_mov_b32 s6, s14
	s_mov_b32 s62, s16
	v_mov_b32_e32 v1, s0
	ds_read_b64 v[4:5], v1
	s_ashr_i32 s7, s6, 31
	s_cmpk_lt_i32 s6, 0x308
	s_cselect_b64 s[2:3], -1, 0
	s_cmpk_gt_i32 s6, 0x307
	s_waitcnt lgkmcnt(0)
	v_readfirstlane_b32 s1, v5
	v_readfirstlane_b32 s0, v4
	v_readfirstlane_b32 s15, v2
	s_cbranch_scc1 .LBB0_5742
	s_ashr_i32 s4, s6, 31
	s_lshr_b32 s4, s4, 29
	s_add_i32 s4, s6, s4
	s_ashr_i32 s5, s4, 3
	s_and_b32 s4, s4, -8
	s_sub_i32 s4, s6, s4
	s_cmp_lt_i32 s4, 0
	s_movk_i32 s8, 0x62
	s_cselect_b32 s8, s8, 0x61
	s_mul_i32 s4, s8, s4
	s_add_i32 s4, s4, s5
	s_ashr_i32 s5, s4, 31
	s_lshr_b32 s5, s5, 27
	s_add_i32 s5, s4, s5
	s_ashr_i32 s8, s5, 5
	s_lshl_b32 s8, s8, 3
	s_sub_i32 s9, 0xc2, s8
	s_min_u32 s9, s9, 8
	s_andn2_b32 s5, s5, 31
	s_sub_i32 s10, s4, s5
	v_cvt_f32_ubyte0_e32 v3, s9
	v_cvt_f32_i32_e32 v1, s10
	v_rcp_iflag_f32_e32 v4, v3
	s_ashr_i32 s4, s10, 30
	s_or_b32 s11, s4, 1
	v_mul_f32_e32 v4, v1, v4
	v_trunc_f32_e32 v4, v4
	v_fma_f32 v1, -v4, v3, v1
	v_cvt_i32_f32_e32 v4, v4
	v_cmp_ge_f32_e64 s[4:5], |v1|, v3
	s_and_b64 s[4:5], s[4:5], exec
	s_cselect_b32 s4, s11, 0
	v_readfirstlane_b32 s5, v4
	s_add_i32 s5, s5, s4
	s_sext_i32_i8 s4, s5
	s_mul_i32 s5, s5, s9
	s_sub_i32 s5, s10, s5
	s_sext_i32_i8 s5, s5
	s_add_i32 s52, s8, s5

; #define PG8_STAGE(bufoff, gbase, voff) do { _Pragma("unroll") for (int _i = 0; _i < 2; ++_i) \
;         __builtin_amdgcn_global_load_lds((const unsigned*)((const char*)(gbase) + (voff)[_i]), (PG8_LAS unsigned*)(lds + (bufoff) + ldsw + _i * 8192), 16, 0, 0); } while (0)
; #define PG8_LDA(dst, b, h) do { _Pragma("unroll") for (int m = 0; m < 4; ++m) _Pragma("unroll") for (int k = 0; k < 2; ++k) dst[m][k] = *(const PG8_LAS bf16x8*)(lds + PG8_SA(b, h) + aoff + m * 2048 + k * 1024); } while (0)
; #define PG8_LDB(dst, b, h) do { _Pragma("unroll") for (int n = 0; n < 2; ++n) _Pragma("unroll") for (int k = 0; k < 2; ++k) dst[n][k] = *(const PG8_LAS bf16x8*)(lds + PG8_SB(b, h) + boff + n * 2048 + k * 1024); } while (0)
; #define PG8_WAIT_V(n) asm volatile("s_waitcnt vmcnt(" #n ")" ::: "memory")
; #define PG8_WAIT_L(n) asm volatile("s_waitcnt lgkmcnt(" #n ")" ::: "memory")
; #define PG8_BAR __builtin_amdgcn_s_barrier()
; #define PG8_SCHED __builtin_amdgcn_sched_barrier(0)
; template <class Epi, class Sched, bool ALIGN_EPI = false, bool SP2 = false>
; __device__ __forceinline__ void gemm_phase(PG8_LAS unsigned char* lds, const Gemm g, const Sched& S, const Epi& E, const int tid) {
;     ...
;         const bool has_next = S.next(ui + 1, nxt);
;         const char* nA = has_next ? S.aptr(nxt) : cA; const char* nB = has_next ? S.bptr(nxt) : cB;
;         for (int t = 0; t < nt; t += 2) {
;             const bool last = (t == nt - 2);
;             const char* a1 = cA + (size_t)(t + 1) * kstep;
;             const char* a2 = last ? nA : cA + (size_t)(t + 2) * kstep; const char* b2 = last ? nB : cB + (size_t)(t + 2) * kstep;
;             const char* a3 = a2 + kstep; const char* b3 = b2 + kstep;
;             if (last && has_next) S.a_ready(nxt);
;             if constexpr (SP2) {
;             PG8_LDB(B0, 0, 0); PG8_LDB(B1, 0, 1); PG8_SCHED; PG8_LDA(At, 0, 0); PG8_STAGE(PG8_SA(1, 1), a1 + hstep, voffA);
;             PG8_WAIT_V(8); PG8_WAIT_L(0); PG8_BAR; PG8_MMA(0, 0, At, B0); PG8_MMA(0, 1, At, B1); PG8_BAR; PG8_SCHED;
;             PG8_LDA(At, 0, 1); PG8_STAGE(PG8_SB(0, 0), b2, voffB); PG8_STAGE(PG8_SB(0, 1), b2 + hstep, voffB); PG8_STAGE(PG8_SA(0, 0), a2, voffA);
;             PG8_WAIT_V(8); PG8_WAIT_L(0); PG8_BAR; PG8_MMA(1, 0, At, B0); PG8_MMA(1, 1, At, B1); PG8_BAR; PG8_SCHED;
.LBB0_5776:
	s_add_u32 s5, s54, 0x100
	s_addc_u32 s47, s55, 0
	s_add_u32 s54, s56, 0x40080
	s_addc_u32 s55, s57, 0
	s_mov_b32 s49, -2
	s_cmp_eq_u32 s101, 0
	s_cbranch_scc1 .Lnobar24
	s_barrier
.Lnobar24:
	ds_read_b128 v[130:133], v171
	ds_read_b128 v[134:137], v171 offset:1024
	ds_read_b128 v[160:163], v171 offset:2048
	ds_read_b128 v[164:167], v171 offset:3072
	ds_read_b128 v[176:179], v172
	ds_read_b128 v[180:183], v172 offset:1024
	ds_read_b128 v[184:187], v172 offset:2048
	ds_read_b128 v[192:195], v172 offset:3072
	s_add_u32 s15, s54, 0xfffc0080
	s_addc_u32 s18, s55, -1
	s_cmp_eq_u32 s49, 12
	s_cselect_b32 s59, s1, s18
	s_cselect_b32 s58, s0, s15
	s_cselect_b32 s57, s51, s47
	s_cselect_b32 s56, s50, s5
	v_lshl_add_u64 v[168:169], s[54:55], 0, v[154:155]
	s_add_i32 m0, s64, 0xc000
	ds_read_b128 v[196:199], v173
	ds_read_b128 v[200:203], v173 offset:1024
	ds_read_b128 v[204:207], v173 offset:2048
	ds_read_b128 v[208:211], v173 offset:3072
	ds_read_b128 v[212:215], v173 offset:4096
	ds_read_b128 v[216:219], v173 offset:5120
	ds_read_b128 v[220:223], v173 offset:6144
	ds_read_b128 v[224:227], v173 offset:7168
	global_load_lds_dwordx4 v[168:169], off
	v_lshl_add_u64 v[168:169], s[54:55], 0, v[152:153]
	s_add_i32 m0, s64, 0xe000
	s_nop 0
	global_load_lds_dwordx4 v[168:169], off
	s_waitcnt vmcnt(8)
	s_waitcnt lgkmcnt(0)
	s_barrier
	s_setprio 1
	s_waitcnt lgkmcnt(0)
	v_mfma_f32_16x16x32_bf16 v[126:129], v[130:133], v[196:199], 0
	v_mfma_f32_16x16x32_bf16 v[122:125], v[160:163], v[196:199], 0
	v_mfma_f32_16x16x32_bf16 v[110:113], v[130:133], v[204:207], 0
	v_mfma_f32_16x16x32_bf16 v[106:109], v[160:163], v[204:207], 0
	v_mfma_f32_16x16x32_bf16 v[94:97], v[130:133], v[212:215], 0
	v_mfma_f32_16x16x32_bf16 v[90:93], v[160:163], v[212:215], 0
	v_mfma_f32_16x16x32_bf16 v[78:81], v[130:133], v[220:223], 0
	v_mfma_f32_16x16x32_bf16 v[74:77], v[160:163], v[220:223], 0
	v_mfma_f32_16x16x32_bf16 v[126:129], v[134:137], v[200:203], v[126:129]
	v_mfma_f32_16x16x32_bf16 v[122:125], v[164:167], v[200:203], v[122:125]
	v_mfma_f32_16x16x32_bf16 v[110:113], v[134:137], v[208:211], v[110:113]
	v_mfma_f32_16x16x32_bf16 v[106:109], v[164:167], v[208:211], v[106:109]
	v_mfma_f32_16x16x32_bf16 v[94:97], v[134:137], v[216:219], v[94:97]
	v_mfma_f32_16x16x32_bf16 v[90:93], v[164:167], v[216:219], v[90:93]
	v_mfma_f32_16x16x32_bf16 v[78:81], v[134:137], v[224:227], v[78:81]
	v_mfma_f32_16x16x32_bf16 v[74:77], v[164:167], v[224:227], v[74:77]
	s_setprio 0
	s_setprio 1
	v_mfma_f32_16x16x32_bf16 v[118:121], v[176:179], v[196:199], 0
	v_mfma_f32_16x16x32_bf16 v[114:117], v[184:187], v[196:199], 0
	v_mfma_f32_16x16x32_bf16 v[102:105], v[176:179], v[204:207], 0
	v_mfma_f32_16x16x32_bf16 v[98:101], v[184:187], v[204:207], 0
	v_mfma_f32_16x16x32_bf16 v[86:89], v[176:179], v[212:215], 0
	v_mfma_f32_16x16x32_bf16 v[82:85], v[184:187], v[212:215], 0
	v_mfma_f32_16x16x32_bf16 v[70:73], v[176:179], v[220:223], 0
	v_mfma_f32_16x16x32_bf16 v[66:69], v[184:187], v[220:223], 0
	v_mfma_f32_16x16x32_bf16 v[118:121], v[180:183], v[200:203], v[118:121]
	v_mfma_f32_16x16x32_bf16 v[114:117], v[192:195], v[200:203], v[114:117]
	v_mfma_f32_16x16x32_bf16 v[102:105], v[180:183], v[208:211], v[102:105]
	v_mfma_f32_16x16x32_bf16 v[98:101], v[192:195], v[208:211], v[98:101]
	v_mfma_f32_16x16x32_bf16 v[86:89], v[180:183], v[216:219], v[86:89]
	v_mfma_f32_16x16x32_bf16 v[82:85], v[192:195], v[216:219], v[82:85]
	v_mfma_f32_16x16x32_bf16 v[70:73], v[180:183], v[224:227], v[70:73]
	v_mfma_f32_16x16x32_bf16 v[66:69], v[192:195], v[224:227], v[66:69]
	s_setprio 0
	s_barrier
	s_add_i32 s15, s83, s63
	v_lshl_add_u64 v[168:169], s[56:57], 0, v[140:141]
	s_mov_b32 m0, s15
	ds_read_b128 v[196:199], v173 offset:16384
	ds_read_b128 v[200:203], v173 offset:17408
	ds_read_b128 v[204:207], v173 offset:18432
	ds_read_b128 v[208:211], v173 offset:19456
	ds_read_b128 v[212:215], v173 offset:20480
	ds_read_b128 v[216:219], v173 offset:21504
	ds_read_b128 v[220:223], v173 offset:22528
	ds_read_b128 v[224:227], v173 offset:23552
	global_load_lds_dwordx4 v[168:169], off
	s_add_i32 m0, s15, 0x2000
	s_add_u32 s18, s56, 0x40000
	v_lshl_add_u64 v[188:189], s[56:57], 0, v[144:145]
	s_addc_u32 s19, s57, 0
	s_add_i32 s15, s84, s63
	global_load_lds_dwordx4 v[188:189], off
	v_lshl_add_u64 v[228:229], s[18:19], 0, v[140:141]
	s_mov_b32 m0, s15
	v_lshl_add_u64 v[230:231], s[58:59], 0, v[142:143]
	global_load_lds_dwordx4 v[228:229], off
	v_lshl_add_u64 v[228:229], s[18:19], 0, v[144:145]
	s_add_i32 m0, s15, 0x2000
	s_nop 0
	global_load_lds_dwordx4 v[228:229], off
	v_lshl_add_u64 v[228:229], s[58:59], 0, v[138:139]
	s_mov_b32 m0, s64
	s_nop 0
	global_load_lds_dwordx4 v[228:229], off
	s_mov_b32 m0, s65
	s_nop 0
	global_load_lds_dwordx4 v[230:231], off
	s_waitcnt vmcnt(8)
	s_waitcnt lgkmcnt(0)
	s_barrier
; #define PG8_STAGE(bufoff, gbase, voff) do { _Pragma("unroll") for (int _i = 0; _i < 2; ++_i) \
;         __builtin_amdgcn_global_load_lds((const unsigned*)((const char*)(gbase) + (voff)[_i]), (PG8_LAS unsigned*)(lds + (bufoff) + ldsw + _i * 8192), 16, 0, 0); } while (0)
; #define PG8_LDA(dst, b, h) do { _Pragma("unroll") for (int m = 0; m < 4; ++m) _Pragma("unroll") for (int k = 0; k < 2; ++k) dst[m][k] = *(const PG8_LAS bf16x8*)(lds + PG8_SA(b, h) + aoff + m * 2048 + k * 1024); } while (0)
; #define PG8_LDB(dst, b, h) do { _Pragma("unroll") for (int n = 0; n < 2; ++n) _Pragma("unroll") for (int k = 0; k < 2; ++k) dst[n][k] = *(const PG8_LAS bf16x8*)(lds + PG8_SB(b, h) + boff + n * 2048 + k * 1024); } while (0)
; #define PG8_MMA(ai, bj, At, Bt) do { __builtin_amdgcn_s_setprio(1); _Pragma("unroll") for (int m = 0; m < 4; ++m) _Pragma("unroll") for (int n = 0; n < 2; ++n) _Pragma("unroll") for (int k = 0; k < 2; ++k) \
;         acc[ai][bj][m][n] = __builtin_amdgcn_mfma_f32_16x16x32_bf16(Bt[n][k], At[m][k], acc[ai][bj][m][n], 0, 0, 0); __builtin_amdgcn_s_setprio(0); } while (0)
; #define PG8_WAIT_V(n) asm volatile("s_waitcnt vmcnt(" #n ")" ::: "memory")
; #define PG8_WAIT_L(n) asm volatile("s_waitcnt lgkmcnt(" #n ")" ::: "memory")
; #define PG8_BAR __builtin_amdgcn_s_barrier()
; #define PG8_SCHED __builtin_amdgcn_sched_barrier(0)
; template <class Epi, class Sched, bool ALIGN_EPI = false, bool SP2 = false>
; __device__ __forceinline__ void gemm_phase(PG8_LAS unsigned char* lds, const Gemm g, const Sched& S, const Epi& E, const int tid) {
;     ...
;             PG8_WAIT_V(8); PG8_WAIT_L(0); PG8_BAR; PG8_MMA(1, 0, At, B0); PG8_MMA(1, 1, At, B1); PG8_BAR; PG8_SCHED;
;             PG8_LDB(B0, 1, 0); PG8_LDB(B1, 1, 1); PG8_SCHED; PG8_LDA(At, 1, 0); PG8_STAGE(PG8_SA(0, 1), a2 + hstep, voffA);
;             PG8_WAIT_V(8); PG8_WAIT_L(0); PG8_BAR; PG8_MMA(0, 0, At, B0); PG8_MMA(0, 1, At, B1); PG8_BAR; PG8_SCHED;
	s_setprio 1
	s_waitcnt lgkmcnt(0)
	v_mfma_f32_16x16x32_bf16 v[62:65], v[130:133], v[196:199], 0
	v_mfma_f32_16x16x32_bf16 v[58:61], v[160:163], v[196:199], 0
	v_mfma_f32_16x16x32_bf16 v[46:49], v[130:133], v[204:207], 0
	v_mfma_f32_16x16x32_bf16 v[42:45], v[160:163], v[204:207], 0
	v_mfma_f32_16x16x32_bf16 v[30:33], v[130:133], v[212:215], 0
	v_mfma_f32_16x16x32_bf16 v[26:29], v[160:163], v[212:215], 0
	v_mfma_f32_16x16x32_bf16 v[14:17], v[130:133], v[220:223], 0
	v_mfma_f32_16x16x32_bf16 v[10:13], v[160:163], v[220:223], 0
	v_mfma_f32_16x16x32_bf16 v[62:65], v[134:137], v[200:203], v[62:65]
	v_mfma_f32_16x16x32_bf16 v[58:61], v[164:167], v[200:203], v[58:61]
	v_mfma_f32_16x16x32_bf16 v[46:49], v[134:137], v[208:211], v[46:49]
	v_mfma_f32_16x16x32_bf16 v[42:45], v[164:167], v[208:211], v[42:45]
	v_mfma_f32_16x16x32_bf16 v[30:33], v[134:137], v[216:219], v[30:33]
	v_mfma_f32_16x16x32_bf16 v[26:29], v[164:167], v[216:219], v[26:29]
	v_mfma_f32_16x16x32_bf16 v[14:17], v[134:137], v[224:227], v[14:17]
	v_mfma_f32_16x16x32_bf16 v[10:13], v[164:167], v[224:227], v[10:13]
	s_setprio 0
	s_setprio 1
	v_mfma_f32_16x16x32_bf16 v[54:57], v[176:179], v[196:199], 0
	v_mfma_f32_16x16x32_bf16 v[50:53], v[184:187], v[196:199], 0
	v_mfma_f32_16x16x32_bf16 v[38:41], v[176:179], v[204:207], 0
	v_mfma_f32_16x16x32_bf16 v[34:37], v[184:187], v[204:207], 0
	v_mfma_f32_16x16x32_bf16 v[22:25], v[176:179], v[212:215], 0
	v_mfma_f32_16x16x32_bf16 v[18:21], v[184:187], v[212:215], 0
	v_mfma_f32_16x16x32_bf16 v[6:9], v[176:179], v[220:223], 0
	v_mfma_f32_16x16x32_bf16 v[2:5], v[184:187], v[220:223], 0
	v_mfma_f32_16x16x32_bf16 v[54:57], v[180:183], v[200:203], v[54:57]
	v_mfma_f32_16x16x32_bf16 v[50:53], v[192:195], v[200:203], v[50:53]
	v_mfma_f32_16x16x32_bf16 v[38:41], v[180:183], v[208:211], v[38:41]
	v_mfma_f32_16x16x32_bf16 v[34:37], v[192:195], v[208:211], v[34:37]
	v_mfma_f32_16x16x32_bf16 v[22:25], v[180:183], v[216:219], v[22:25]
	v_mfma_f32_16x16x32_bf16 v[18:21], v[192:195], v[216:219], v[18:21]
	v_mfma_f32_16x16x32_bf16 v[6:9], v[180:183], v[224:227], v[6:9]
	v_mfma_f32_16x16x32_bf16 v[2:5], v[192:195], v[224:227], v[2:5]
	s_setprio 0
	s_barrier
	s_add_i32 s15, 0, 0x18000
	s_add_i32 s60, 0, 0x1c000
	v_add_u32_e32 v164, s15, v170
	v_add_u32_e32 v175, s60, v170
	ds_read_b128 v[130:133], v164
	ds_read_b128 v[134:137], v164 offset:1024
	ds_read_b128 v[160:163], v164 offset:2048
	ds_read_b128 v[164:167], v164 offset:3072
	ds_read_b128 v[176:179], v175
	ds_read_b128 v[180:183], v175 offset:1024
	ds_read_b128 v[184:187], v175 offset:2048
	ds_read_b128 v[192:195], v175 offset:3072
	s_add_u32 s18, s58, 0x40000
	s_addc_u32 s19, s59, 0
	s_mov_b32 m0, s66
	v_lshl_add_u64 v[232:233], s[18:19], 0, v[138:139]
	ds_read_b128 v[196:199], v173 offset:32768
	ds_read_b128 v[200:203], v173 offset:33792
	ds_read_b128 v[204:207], v173 offset:34816
	ds_read_b128 v[208:211], v173 offset:35840
	ds_read_b128 v[212:215], v173 offset:36864
	ds_read_b128 v[216:219], v173 offset:37888
	ds_read_b128 v[220:223], v173 offset:38912
	ds_read_b128 v[224:227], v173 offset:39936
	global_load_lds_dwordx4 v[232:233], off
	v_lshl_add_u64 v[232:233], s[18:19], 0, v[142:143]
	s_mov_b32 m0, s67
	s_nop 0
	global_load_lds_dwordx4 v[232:233], off
	s_waitcnt vmcnt(8)
	s_waitcnt lgkmcnt(0)
	s_barrier
	s_setprio 1
	s_waitcnt lgkmcnt(0)
	v_mfma_f32_16x16x32_bf16 v[126:129], v[130:133], v[196:199], v[126:129]
	v_mfma_f32_16x16x32_bf16 v[122:125], v[160:163], v[196:199], v[122:125]
	v_mfma_f32_16x16x32_bf16 v[110:113], v[130:133], v[204:207], v[110:113]
	v_mfma_f32_16x16x32_bf16 v[106:109], v[160:163], v[204:207], v[106:109]
	v_mfma_f32_16x16x32_bf16 v[94:97], v[130:133], v[212:215], v[94:97]
	v_mfma_f32_16x16x32_bf16 v[90:93], v[160:163], v[212:215], v[90:93]
	v_mfma_f32_16x16x32_bf16 v[78:81], v[130:133], v[220:223], v[78:81]
	v_mfma_f32_16x16x32_bf16 v[74:77], v[160:163], v[220:223], v[74:77]
	v_mfma_f32_16x16x32_bf16 v[126:129], v[134:137], v[200:203], v[126:129]
	v_mfma_f32_16x16x32_bf16 v[122:125], v[164:167], v[200:203], v[122:125]
	v_mfma_f32_16x16x32_bf16 v[110:113], v[134:137], v[208:211], v[110:113]
	v_mfma_f32_16x16x32_bf16 v[106:109], v[164:167], v[208:211], v[106:109]
	v_mfma_f32_16x16x32_bf16 v[94:97], v[134:137], v[216:219], v[94:97]
	v_mfma_f32_16x16x32_bf16 v[90:93], v[164:167], v[216:219], v[90:93]
	v_mfma_f32_16x16x32_bf16 v[78:81], v[134:137], v[224:227], v[78:81]
	v_mfma_f32_16x16x32_bf16 v[74:77], v[164:167], v[224:227], v[74:77]
	s_setprio 0
	s_setprio 1
	v_mfma_f32_16x16x32_bf16 v[118:121], v[176:179], v[196:199], v[118:121]
	v_mfma_f32_16x16x32_bf16 v[114:117], v[184:187], v[196:199], v[114:117]
	v_mfma_f32_16x16x32_bf16 v[102:105], v[176:179], v[204:207], v[102:105]
	v_mfma_f32_16x16x32_bf16 v[98:101], v[184:187], v[204:207], v[98:101]
	v_mfma_f32_16x16x32_bf16 v[86:89], v[176:179], v[212:215], v[86:89]
	v_mfma_f32_16x16x32_bf16 v[82:85], v[184:187], v[212:215], v[82:85]
	v_mfma_f32_16x16x32_bf16 v[70:73], v[176:179], v[220:223], v[70:73]
	v_mfma_f32_16x16x32_bf16 v[66:69], v[184:187], v[220:223], v[66:69]
	v_mfma_f32_16x16x32_bf16 v[118:121], v[180:183], v[200:203], v[118:121]
	v_mfma_f32_16x16x32_bf16 v[114:117], v[192:195], v[200:203], v[114:117]
	v_mfma_f32_16x16x32_bf16 v[102:105], v[180:183], v[208:211], v[102:105]
	v_mfma_f32_16x16x32_bf16 v[98:101], v[192:195], v[208:211], v[98:101]
	v_mfma_f32_16x16x32_bf16 v[86:89], v[180:183], v[216:219], v[86:89]
	v_mfma_f32_16x16x32_bf16 v[82:85], v[192:195], v[216:219], v[82:85]
	v_mfma_f32_16x16x32_bf16 v[70:73], v[180:183], v[224:227], v[70:73]
	v_mfma_f32_16x16x32_bf16 v[66:69], v[192:195], v[224:227], v[66:69]
	s_setprio 0
	s_barrier
; #define PG8_STAGE(bufoff, gbase, voff) do { _Pragma("unroll") for (int _i = 0; _i < 2; ++_i) \
;         __builtin_amdgcn_global_load_lds((const unsigned*)((const char*)(gbase) + (voff)[_i]), (PG8_LAS unsigned*)(lds + (bufoff) + ldsw + _i * 8192), 16, 0, 0); } while (0)
; #define PG8_LDA(dst, b, h) do { _Pragma("unroll") for (int m = 0; m < 4; ++m) _Pragma("unroll") for (int k = 0; k < 2; ++k) dst[m][k] = *(const PG8_LAS bf16x8*)(lds + PG8_SA(b, h) + aoff + m * 2048 + k * 1024); } while (0)
; #define PG8_MMA(ai, bj, At, Bt) do { __builtin_amdgcn_s_setprio(1); _Pragma("unroll") for (int m = 0; m < 4; ++m) _Pragma("unroll") for (int n = 0; n < 2; ++n) _Pragma("unroll") for (int k = 0; k < 2; ++k) \
;         acc[ai][bj][m][n] = __builtin_amdgcn_mfma_f32_16x16x32_bf16(Bt[n][k], At[m][k], acc[ai][bj][m][n], 0, 0, 0); __builtin_amdgcn_s_setprio(0); } while (0)
; #define PG8_WAIT_V(n) asm volatile("s_waitcnt vmcnt(" #n ")" ::: "memory")
; #define PG8_WAIT_L(n) asm volatile("s_waitcnt lgkmcnt(" #n ")" ::: "memory")
; #define PG8_BAR __builtin_amdgcn_s_barrier()
; #define PG8_SCHED __builtin_amdgcn_sched_barrier(0)
; template <class Epi, class Sched, bool ALIGN_EPI = false, bool SP2 = false>
; __device__ __forceinline__ void gemm_phase(PG8_LAS unsigned char* lds, const Gemm g, const Sched& S, const Epi& E, const int tid) {
;     ...
;         for (int t = 0; t < nt; t += 2) {
;     ...
;             PG8_LDA(At, 1, 1); PG8_STAGE(PG8_SB(1, 0), b3, voffB); PG8_STAGE(PG8_SB(1, 1), b3 + hstep, voffB); PG8_STAGE(PG8_SA(1, 0), a3, voffA);
;             PG8_WAIT_V(8); PG8_WAIT_L(0); PG8_BAR; PG8_MMA(1, 0, At, B0); PG8_MMA(1, 1, At, B1); PG8_BAR; PG8_SCHED;
	s_add_i32 s15, s15, s63
	v_lshl_add_u64 v[168:169], v[168:169], 0, s[42:43]
	s_mov_b32 m0, s15
	ds_read_b128 v[196:199], v173 offset:49152
	ds_read_b128 v[200:203], v173 offset:50176
	ds_read_b128 v[204:207], v173 offset:51200
	ds_read_b128 v[208:211], v173 offset:52224
	ds_read_b128 v[212:215], v173 offset:53248
	ds_read_b128 v[216:219], v173 offset:54272
	ds_read_b128 v[220:223], v173 offset:55296
	ds_read_b128 v[224:227], v173 offset:56320
	global_load_lds_dwordx4 v[168:169], off
	s_add_i32 m0, s15, 0x2000
	s_add_u32 s18, s56, 0x40080
	v_lshl_add_u64 v[168:169], v[188:189], 0, s[42:43]
	s_addc_u32 s19, s57, 0
	s_add_i32 s15, s60, s63
	global_load_lds_dwordx4 v[168:169], off
	v_lshl_add_u64 v[168:169], s[18:19], 0, v[140:141]
	s_mov_b32 m0, s15
	s_nop 0
	global_load_lds_dwordx4 v[168:169], off
	v_lshl_add_u64 v[168:169], s[18:19], 0, v[144:145]
	s_add_i32 m0, s15, 0x2000
	s_nop 0
	global_load_lds_dwordx4 v[168:169], off
	v_lshl_add_u64 v[168:169], v[228:229], 0, s[42:43]
	s_mov_b32 m0, s74
	s_nop 0
	global_load_lds_dwordx4 v[168:169], off
	v_lshl_add_u64 v[168:169], v[230:231], 0, s[42:43]
	s_mov_b32 m0, s75
	s_nop 0
	global_load_lds_dwordx4 v[168:169], off
	s_waitcnt vmcnt(8)
	s_waitcnt lgkmcnt(0)
	s_barrier
	s_setprio 1
	s_waitcnt lgkmcnt(0)
	v_mfma_f32_16x16x32_bf16 v[62:65], v[130:133], v[196:199], v[62:65]
	v_mfma_f32_16x16x32_bf16 v[58:61], v[160:163], v[196:199], v[58:61]
	v_mfma_f32_16x16x32_bf16 v[46:49], v[130:133], v[204:207], v[46:49]
	v_mfma_f32_16x16x32_bf16 v[42:45], v[160:163], v[204:207], v[42:45]
	v_mfma_f32_16x16x32_bf16 v[30:33], v[130:133], v[212:215], v[30:33]
	v_mfma_f32_16x16x32_bf16 v[26:29], v[160:163], v[212:215], v[26:29]
	v_mfma_f32_16x16x32_bf16 v[14:17], v[130:133], v[220:223], v[14:17]
	v_mfma_f32_16x16x32_bf16 v[10:13], v[160:163], v[220:223], v[10:13]
	v_mfma_f32_16x16x32_bf16 v[62:65], v[134:137], v[200:203], v[62:65]
	v_mfma_f32_16x16x32_bf16 v[58:61], v[164:167], v[200:203], v[58:61]
	v_mfma_f32_16x16x32_bf16 v[46:49], v[134:137], v[208:211], v[46:49]
	v_mfma_f32_16x16x32_bf16 v[42:45], v[164:167], v[208:211], v[42:45]
	v_mfma_f32_16x16x32_bf16 v[30:33], v[134:137], v[216:219], v[30:33]
	v_mfma_f32_16x16x32_bf16 v[26:29], v[164:167], v[216:219], v[26:29]
	v_mfma_f32_16x16x32_bf16 v[14:17], v[134:137], v[224:227], v[14:17]
	v_mfma_f32_16x16x32_bf16 v[10:13], v[164:167], v[224:227], v[10:13]
	s_setprio 0
	s_setprio 1
	v_mfma_f32_16x16x32_bf16 v[54:57], v[176:179], v[196:199], v[54:57]
	v_mfma_f32_16x16x32_bf16 v[50:53], v[184:187], v[196:199], v[50:53]
	v_mfma_f32_16x16x32_bf16 v[38:41], v[176:179], v[204:207], v[38:41]
	v_mfma_f32_16x16x32_bf16 v[34:37], v[184:187], v[204:207], v[34:37]
	v_mfma_f32_16x16x32_bf16 v[22:25], v[176:179], v[212:215], v[22:25]
	v_mfma_f32_16x16x32_bf16 v[18:21], v[184:187], v[212:215], v[18:21]
	v_mfma_f32_16x16x32_bf16 v[6:9], v[176:179], v[220:223], v[6:9]
	v_mfma_f32_16x16x32_bf16 v[2:5], v[184:187], v[220:223], v[2:5]
	v_mfma_f32_16x16x32_bf16 v[54:57], v[180:183], v[200:203], v[54:57]
	v_mfma_f32_16x16x32_bf16 v[50:53], v[192:195], v[200:203], v[50:53]
	v_mfma_f32_16x16x32_bf16 v[38:41], v[180:183], v[208:211], v[38:41]
	v_mfma_f32_16x16x32_bf16 v[34:37], v[192:195], v[208:211], v[34:37]
	v_mfma_f32_16x16x32_bf16 v[22:25], v[180:183], v[216:219], v[22:25]
	v_mfma_f32_16x16x32_bf16 v[18:21], v[192:195], v[216:219], v[18:21]
	v_mfma_f32_16x16x32_bf16 v[6:9], v[180:183], v[224:227], v[6:9]
	v_mfma_f32_16x16x32_bf16 v[2:5], v[192:195], v[224:227], v[2:5]
	s_setprio 0
	s_barrier
	s_add_i32 s49, s49, 2
	s_add_u32 s5, s5, 0x100
	s_addc_u32 s47, s47, 0
	s_add_u32 s54, s54, 0x100
	s_addc_u32 s55, s55, 0

; #define PG8_BAR __builtin_amdgcn_s_barrier()
; template <class Epi, class Sched, bool ALIGN_EPI = false, bool SP2 = false>
; __device__ __forceinline__ void gemm_phase(PG8_LAS unsigned char* lds, const Gemm g, const Sched& S, const Epi& E, const int tid) {
;     ...
;         if (!has_next) break;
; #pragma unroll
;         for (int a = 0; a < 2; ++a)
; #pragma unroll
;             for (int b = 0; b < 2; ++b)
; #pragma unroll
;                 for (int m = 0; m < 4; ++m)
; #pragma unroll
;                     for (int n = 0; n < 2; ++n) acc[a][b][m][n] = (f32x4){0.f, 0.f, 0.f, 0.f};
;         cur = nxt; cA = nA; cB = nB; ++ui;
;         if constexpr (ALIGN_EPI) { if (wr == 1) PG8_BAR; }
;     }
.LBB0_5835:
	s_and_b64 vcc, exec, s[2:3]
	s_mov_b64 s[2:3], -1
	s_cbranch_vccnz .LBB0_5747
	s_andn2_b64 vcc, exec, s[26:27]
	s_cbranch_vccnz .LBB0_5746
	s_mov_b32 s101, 1
	s_branch .LBB0_5746

;     __device__ __forceinline__ const float* in(int i) const { return (const float*)(const GAS float*)get(i); }
;     __device__ __forceinline__ float* out() const { return (float*)(GAS float*)get(21); }
;     __device__ __forceinline__ unsigned char* ws() const { return (unsigned char*)(GAS unsigned char*)get(22); }
; __device__ __forceinline__ void final_phase(const PT a, unsigned char* ws, int wave, int lane, int bid, int G) {
;     const int gw = bid * NWAVES + wave, NGW = G * NWAVES;
;     const float* ssq = (const float*)(ws + WS_SSQ); const bf16* hb = (const bf16*)(ws + WS_HB); float* out = a.out();
;     f32x4 g[4];
; #pragma unroll
;     for (int j = 0; j < 4; ++j) g[j] = ((const f32x4*)a.in(20))[lane + 64 * j];
;     for (int r = gw; r < T_ROWS; r += NGW) {
;         int pos, L; rowinfo(r, pos, L); if (pos < 16) continue;
;         float* p = r < ROWS_P ? out + ((size_t)(r / LP) * 4096 + pos - 16) * DM : out + (size_t)NSEQ_P * 4096 * DM + ((size_t)((r - ROWS_P) / LS) * 2048 + pos - 16) * DM;
;         const float rs = rstd_of(ssq, r);
.LBB0_6327:
	s_mov_b32 s101, 0
	s_add_i32 s0, 0, 0x204b0
	v_mov_b32_e32 v0, s0
	ds_read_b64 v[0:1], v0
	v_readfirstlane_b32 s2, v190
	s_ashr_i32 s11, s2, 6
	s_add_i32 s2, 0, 0x204a8
	s_lshl_b32 s12, s14, 3
	s_waitcnt lgkmcnt(0)
	v_readfirstlane_b32 s10, v0
	v_mov_b32_e32 v0, s2
	s_add_i32 s2, 0, 0x204a0
	s_waitcnt vmcnt(0)
	v_mov_b32_e32 v6, s2
	v_readfirstlane_b32 s0, v1
	ds_read_b64 v[0:1], v0
	ds_read_b64 v[2:3], v6
	s_add_i32 s14, s11, s12
	s_mov_b32 s1, 0
	s_cmp_gt_i32 s14, 0xc13f
	s_waitcnt lgkmcnt(1)
	v_readfirstlane_b32 s15, v1
	v_readfirstlane_b32 s17, v0
	ds_read_b64 v[0:1], v6
	s_waitcnt lgkmcnt(1)
	v_readfirstlane_b32 s3, v3
	ds_read_b64 v[4:5], v6
	v_readfirstlane_b32 s2, v2
	ds_read_b64 v[2:3], v6
	s_waitcnt lgkmcnt(2)
	v_readfirstlane_b32 s5, v1
	v_readfirstlane_b32 s4, v0
	s_waitcnt lgkmcnt(1)
	v_readfirstlane_b32 s7, v5
	v_readfirstlane_b32 s6, v4
	s_waitcnt lgkmcnt(0)
	v_readfirstlane_b32 s9, v3
	v_readfirstlane_b32 s8, v2
	s_cbranch_scc1 .LBB0_6340
	v_and_b32_e32 v20, 63, v190
	v_lshlrev_b32_e32 v16, 4, v20
	global_load_dwordx4 v[0:3], v16, s[2:3]
	global_load_dwordx4 v[4:7], v16, s[4:5] offset:1024
	global_load_dwordx4 v[8:11], v16, s[6:7] offset:2048
	global_load_dwordx4 v[12:15], v16, s[8:9] offset:3072
	s_lshl_b32 s2, s16, 3
	s_add_u32 s16, s17, 0x3ff0000
	s_addc_u32 s18, s15, 0
	s_ashr_i32 s3, s11, 31
	s_ashr_i32 s4, s12, 31
	s_add_u32 s8, s11, s12
	s_addc_u32 s9, s3, s4
	s_lshl_b64 s[4:5], s[8:9], 6
	s_add_u32 s3, s10, s4
	s_addc_u32 s5, s0, s5
	s_add_u32 s4, s3, 0x300000
	s_addc_u32 s5, s5, 0
	s_ashr_i32 s3, s2, 31
	s_lshl_b64 s[6:7], s[2:3], 6
	s_lshl_b64 s[8:9], s[8:9], 11
	s_add_u32 s8, s10, s8
	v_mov_b32_e32 v17, 0
	v_lshlrev_b32_e32 v16, 3, v20
	s_addc_u32 s9, s0, s9
	v_lshl_add_u64 v[18:19], s[8:9], 0, v[16:17]
	s_mov_b64 s[8:9], 0x7800400
	v_lshl_add_u64 v[18:19], v[18:19], 0, s[8:9]
	s_lshl_b64 s[8:9], s[2:3], 11
	v_mov_b32_e32 v16, 0x358637bd
	v_lshlrev_b32_e32 v20, 4, v20
	s_branch .LBB0_6331

; __global__ void __launch_bounds__(NWAVES * 64, 2) mega_fwd(Args args) {
;     extern __shared__ __attribute__((aligned(16))) unsigned char lds[];
	.amdhsa_kernel _Z8mega_fwd4Args
		.amdhsa_group_segment_fixed_size 0
		.amdhsa_private_segment_fixed_size 0
		.amdhsa_kernarg_size 448
		.amdhsa_user_sgpr_count 2
		.amdhsa_user_sgpr_dispatch_ptr 0
		.amdhsa_user_sgpr_queue_ptr 0
		.amdhsa_user_sgpr_kernarg_segment_ptr 1
		.amdhsa_user_sgpr_dispatch_id 0
		.amdhsa_user_sgpr_kernarg_preload_length 0
		.amdhsa_user_sgpr_kernarg_preload_offset 0
		.amdhsa_user_sgpr_private_segment_size 0
		.amdhsa_uses_dynamic_stack 0
		.amdhsa_enable_private_segment 0
		.amdhsa_system_sgpr_workgroup_id_x 1
		.amdhsa_system_sgpr_workgroup_id_y 0
		.amdhsa_system_sgpr_workgroup_id_z 0
		.amdhsa_system_sgpr_workgroup_info 0
		.amdhsa_system_vgpr_workitem_id 2
		.amdhsa_next_free_vgpr 256
		.amdhsa_next_free_sgpr 102
		.amdhsa_accum_offset 256
		.amdhsa_reserve_vcc 1
		.amdhsa_float_round_mode_32 0
		.amdhsa_float_round_mode_16_64 0
		.amdhsa_float_denorm_mode_32 3
		.amdhsa_float_denorm_mode_16_64 3
		.amdhsa_dx10_clamp 1
		.amdhsa_ieee_mode 1
		.amdhsa_fp16_overflow 0
		.amdhsa_tg_split 0
		.amdhsa_exception_fp_ieee_invalid_op 0
		.amdhsa_exception_fp_denorm_src 0
		.amdhsa_exception_fp_ieee_div_zero 0
		.amdhsa_exception_fp_ieee_overflow 0
		.amdhsa_exception_fp_ieee_underflow 0
		.amdhsa_exception_fp_ieee_inexact 0
		.amdhsa_exception_int_div_zero 0
	.end_amdhsa_kernel

; __global__ void __launch_bounds__(NWAVES * 64, 2) mega_fwd(Args args) {
;     extern __shared__ __attribute__((aligned(16))) unsigned char lds[];
amdhsa.kernels:
  - .agpr_count:     0
    .args:
      - .offset:         0
        .size:           192
        .value_kind:     by_value
      - .offset:         192
        .size:           4
        .value_kind:     hidden_block_count_x
      - .offset:         196
        .size:           4
        .value_kind:     hidden_block_count_y
      - .offset:         200
        .size:           4
        .value_kind:     hidden_block_count_z
      - .offset:         204
        .size:           2
        .value_kind:     hidden_group_size_x
      - .offset:         206
        .size:           2
        .value_kind:     hidden_group_size_y
      - .offset:         208
        .size:           2
        .value_kind:     hidden_group_size_z
      - .offset:         210
        .size:           2
        .value_kind:     hidden_remainder_x
      - .offset:         212
        .size:           2
        .value_kind:     hidden_remainder_y
      - .offset:         214
        .size:           2
        .value_kind:     hidden_remainder_z
      - .offset:         232
        .size:           8
        .value_kind:     hidden_global_offset_x
      - .offset:         240
        .size:           8
        .value_kind:     hidden_global_offset_y
      - .offset:         248
        .size:           8
        .value_kind:     hidden_global_offset_z
      - .offset:         256
        .size:           2
        .value_kind:     hidden_grid_dims
      - .offset:         280
        .size:           8
        .value_kind:     hidden_multigrid_sync_arg
      - .offset:         312
        .size:           4
        .value_kind:     hidden_dynamic_lds_size
    .group_segment_fixed_size: 0
    .kernarg_segment_align: 8
    .kernarg_segment_size: 448
    .language:       OpenCL C
    .language_version:
      - 2
      - 0
    .max_flat_workgroup_size: 512
    .name:           _Z8mega_fwd4Args
    .private_segment_fixed_size: 0
    .sgpr_count:     108
    .sgpr_spill_count: 3
    .symbol:         _Z8mega_fwd4Args.kd
    .uniform_work_group_size: 1
    .uses_dynamic_stack: false
    .vgpr_count:     256
    .vgpr_spill_count: 0
    .wavefront_size: 64
